# baseline (speedup 1.0000x reference)
; __device__ __forceinline__ int crow(int r, int hi) { return (r & 3) + 8 * (r >> 2) + 4 * hi; }
; __device__ void gmlp_item(const Params& p, int ch, int gg, char* smem) {
;     ...
;     for (int r = 0; r < 16; ++r) { const int row = crow(r, hi); const float bsp = p.b_sp[gg * 128 + 32 * rb + row];
; #pragma unroll
;       for (int d0 = 0; d0 < 4; ++d0) wl[row * 128 + 32 * d0 + r32] = o[d0][r] + bsp; }
;     asm volatile("s_waitcnt lgkmcnt(0)" ::: "memory");
; #pragma unroll
;     for (int i = 0; i < 8; ++i) {
;       const int c = i * 64 + lane, row = c >> 4, col8 = (c & 15) * 8;
;       const long t = t0 + 32 * rb + row; const int d = gg * 256 + chh * 128 + col8;
;       const f32x4 a0 = *reinterpret_cast<const f32x4*>(wl + row * 128 + col8), a1 = *reinterpret_cast<const f32x4*>(wl + row * 128 + col8 + 4);
;       const bf16x8 uv = ld8(p.P + t * LDP + C_U + d), zv = ld8(p.P + t * LDP + C_ZG + d);
.LBB0_216:
	s_or_b64 exec, exec, s[12:13]
	v_add_lshl_u32 v78, v68, v108, 2
	v_or_b32_e32 v66, v68, v108
	s_barrier
	global_load_dwordx4 v[70:73], v78, s[24:25] offset:64
	v_lshlrev_b32_e32 v74, 2, v66
	global_load_dwordx4 v[66:69], v78, s[24:25] offset:96
	s_nop 0
	global_load_dwordx4 v[74:77], v74, s[24:25]
	s_nop 0
	global_load_dwordx4 v[78:81], v78, s[24:25] offset:32
	v_add_u32_e32 v82, v109, v110
	s_waitcnt vmcnt(2)
	v_add_f32_e32 v14, v14, v66
	v_add_f32_e32 v10, v10, v70
	v_add_f32_e32 v26, v26, v70
	s_waitcnt vmcnt(1)
	v_add_f32_e32 v2, v2, v74
	v_add_f32_e32 v42, v42, v70
	v_add_f32_e32 v58, v58, v70
	v_add_f32_e32 v11, v11, v71
	v_add_f32_e32 v27, v27, v71
	v_add_f32_e32 v43, v43, v71
	v_add_f32_e32 v59, v59, v71
	v_add_f32_e32 v12, v12, v72
	v_add_f32_e32 v28, v28, v72
	v_add_f32_e32 v44, v44, v72
	v_add_f32_e32 v60, v60, v72
	v_add_f32_e32 v13, v13, v73
	v_add_f32_e32 v29, v29, v73
	v_add_f32_e32 v45, v45, v73
	v_add_f32_e32 v61, v61, v73
	v_add_f32_e32 v18, v18, v74
	v_add_f32_e32 v34, v34, v74
	v_add_f32_e32 v50, v50, v74
	v_add_f32_e32 v3, v3, v75
	v_add_f32_e32 v19, v19, v75
	v_add_f32_e32 v35, v35, v75
	v_add_f32_e32 v51, v51, v75
	v_add_f32_e32 v4, v4, v76
	v_add_f32_e32 v20, v20, v76
	v_add_f32_e32 v36, v36, v76
	v_add_f32_e32 v52, v52, v76
	v_add_f32_e32 v5, v5, v77
	v_add_f32_e32 v21, v21, v77
	v_add_f32_e32 v37, v37, v77
	v_add_f32_e32 v53, v53, v77
	s_waitcnt vmcnt(0)
	v_add_f32_e32 v6, v6, v78
	v_add_f32_e32 v22, v22, v78
	v_add_f32_e32 v38, v38, v78
	v_add_f32_e32 v54, v54, v78
	v_add_f32_e32 v7, v7, v79
	v_add_f32_e32 v23, v23, v79
	v_add_f32_e32 v39, v39, v79
	v_add_f32_e32 v55, v55, v79
	v_add_f32_e32 v8, v8, v80
	v_add_f32_e32 v24, v24, v80
	v_add_f32_e32 v40, v40, v80
	v_add_f32_e32 v56, v56, v80
	v_add_f32_e32 v9, v9, v81
	v_add_f32_e32 v25, v25, v81
	v_add_f32_e32 v41, v41, v81
	v_add_f32_e32 v57, v57, v81
	ds_write2_b32 v129, v10, v26 offset1:32
	ds_write2_b32 v129, v42, v58 offset0:64 offset1:96
	ds_write2_b32 v130, v11, v27 offset1:32
	ds_write2_b32 v130, v43, v59 offset0:64 offset1:96
	ds_write2_b32 v131, v12, v28 offset1:32
	ds_write2_b32 v131, v44, v60 offset0:64 offset1:96
	ds_write2_b32 v132, v13, v29 offset1:32
	ds_write2_b32 v132, v45, v61 offset0:64 offset1:96
	ds_write2_b32 v82, v2, v18 offset1:32
	ds_write2_b32 v82, v34, v50 offset0:64 offset1:96
	ds_write2_b32 v122, v3, v19 offset1:32
	ds_write2_b32 v122, v35, v51 offset0:64 offset1:96
	ds_write2_b32 v123, v4, v20 offset1:32
	ds_write2_b32 v123, v36, v52 offset0:64 offset1:96
	ds_write2_b32 v124, v5, v21 offset1:32
	ds_write2_b32 v124, v37, v53 offset0:64 offset1:96
	ds_write2_b32 v125, v6, v22 offset1:32
	ds_write2_b32 v125, v38, v54 offset0:64 offset1:96
	ds_write2_b32 v126, v7, v23 offset1:32
	ds_write2_b32 v126, v39, v55 offset0:64 offset1:96
	ds_write2_b32 v127, v8, v24 offset1:32
	ds_write2_b32 v127, v40, v56 offset0:64 offset1:96
	ds_write2_b32 v128, v9, v25 offset1:32
	ds_write2_b32 v128, v41, v57 offset0:64 offset1:96
	v_add_f32_e32 v2, v30, v66
	ds_write2_b32 v133, v14, v2 offset1:32
	v_add_f32_e32 v2, v46, v66
	v_add_f32_e32 v3, v62, v66
	ds_write2_b32 v133, v2, v3 offset0:64 offset1:96
	v_add_f32_e32 v2, v15, v67
	v_add_f32_e32 v3, v31, v67
	ds_write2_b32 v134, v2, v3 offset1:32
	v_add_f32_e32 v2, v47, v67
	v_add_f32_e32 v3, v63, v67
	ds_write2_b32 v134, v2, v3 offset0:64 offset1:96
	v_add_f32_e32 v2, v16, v68
	v_add_f32_e32 v3, v32, v68
	ds_write2_b32 v135, v2, v3 offset1:32
	v_add_f32_e32 v2, v48, v68
	v_add_f32_e32 v3, v64, v68
	ds_write2_b32 v135, v2, v3 offset0:64 offset1:96
	v_add_f32_e32 v2, v17, v69
	v_add_f32_e32 v3, v33, v69
	v_or_b32_e32 v6, s1, v105
	ds_write2_b32 v136, v2, v3 offset1:32
	v_add_f32_e32 v2, v49, v69
	v_add_f32_e32 v3, v65, v69
	v_or_b32_e32 v92, v6, v112
	v_mov_b64_e32 v[4:5], s[46:47]
	ds_write2_b32 v136, v2, v3 offset0:64 offset1:96
	v_mad_u64_u32 v[8:9], s[12:13], v92, s52, v[4:5]
	v_add_lshl_u32 v2, v111, s2, 1
	v_mov_b32_e32 v3, v93
	v_lshl_add_u64 v[12:13], v[8:9], 0, v[2:3]
	s_lshl_b32 s12, s52, 2
	v_add_co_u32_e32 v16, vcc, s12, v12
	s_nop 1
	v_addc_co_u32_e32 v17, vcc, 0, v13, vcc
	v_add_co_u32_e32 v20, vcc, s50, v16
	s_nop 1
	v_addc_co_u32_e32 v21, vcc, 0, v17, vcc
	global_load_dword v28, v[20:21], off offset:2048
	v_add_co_u32_e32 v20, vcc, s23, v16
	s_nop 1
	v_addc_co_u32_e32 v21, vcc, 0, v17, vcc
	global_load_dword v28, v[20:21], off offset:2048
	v_add_co_u32_e32 v16, vcc, s12, v16
	s_nop 1
	v_addc_co_u32_e32 v17, vcc, 0, v17, vcc
	v_add_co_u32_e32 v20, vcc, s50, v16
	s_nop 1
	v_addc_co_u32_e32 v21, vcc, 0, v17, vcc
	global_load_dword v28, v[20:21], off offset:2048
	v_add_co_u32_e32 v20, vcc, s23, v16
	s_nop 1
	v_addc_co_u32_e32 v21, vcc, 0, v17, vcc
	global_load_dword v28, v[20:21], off offset:2048
	v_add_co_u32_e32 v16, vcc, s12, v16
	s_nop 1
	v_addc_co_u32_e32 v17, vcc, 0, v17, vcc
	v_add_co_u32_e32 v20, vcc, s50, v16
	s_nop 1
	v_addc_co_u32_e32 v21, vcc, 0, v17, vcc
	global_load_dword v28, v[20:21], off offset:2048
	v_add_co_u32_e32 v20, vcc, s23, v16
	s_nop 1
	v_addc_co_u32_e32 v21, vcc, 0, v17, vcc
	global_load_dword v28, v[20:21], off offset:2048
	v_add_co_u32_e32 v16, vcc, s12, v16
	s_nop 1
	v_addc_co_u32_e32 v17, vcc, 0, v17, vcc
	v_add_co_u32_e32 v20, vcc, s50, v16
	s_nop 1
	v_addc_co_u32_e32 v21, vcc, 0, v17, vcc
	global_load_dword v28, v[20:21], off offset:2048
	v_add_co_u32_e32 v20, vcc, s23, v16
	s_nop 1
	v_addc_co_u32_e32 v21, vcc, 0, v17, vcc
	global_load_dword v28, v[20:21], off offset:2048
	v_add_co_u32_e32 v16, vcc, s12, v16
	s_nop 1
	v_addc_co_u32_e32 v17, vcc, 0, v17, vcc
	v_add_co_u32_e32 v20, vcc, s50, v16
	s_nop 1
	v_addc_co_u32_e32 v21, vcc, 0, v17, vcc
	global_load_dword v28, v[20:21], off offset:2048
	v_add_co_u32_e32 v20, vcc, s23, v16
	s_nop 1
	v_addc_co_u32_e32 v21, vcc, 0, v17, vcc
	global_load_dword v28, v[20:21], off offset:2048
	v_add_co_u32_e32 v16, vcc, s12, v16
	s_nop 1
	v_addc_co_u32_e32 v17, vcc, 0, v17, vcc
	v_add_co_u32_e32 v20, vcc, s50, v16
	s_nop 1
	v_addc_co_u32_e32 v21, vcc, 0, v17, vcc
	global_load_dword v28, v[20:21], off offset:2048
	v_add_co_u32_e32 v20, vcc, s23, v16
	s_nop 1
	v_addc_co_u32_e32 v21, vcc, 0, v17, vcc
	global_load_dword v28, v[20:21], off offset:2048
	v_add_co_u32_e32 v16, vcc, s12, v16
	s_nop 1
	v_addc_co_u32_e32 v17, vcc, 0, v17, vcc
	v_add_co_u32_e32 v20, vcc, s50, v16
	s_nop 1
	v_addc_co_u32_e32 v21, vcc, 0, v17, vcc
	global_load_dword v28, v[20:21], off offset:2048
	v_add_co_u32_e32 v20, vcc, s23, v16
	s_nop 1
	v_addc_co_u32_e32 v21, vcc, 0, v17, vcc
	global_load_dword v28, v[20:21], off offset:2048
	v_add_co_u32_e32 v8, vcc, s50, v12
	s_waitcnt lgkmcnt(0)
; __device__ __forceinline__ float bf2f(unsigned short u) { return __uint_as_float(((unsigned)u) << 16); }
; __device__ __forceinline__ float silu_f(float z) { return z / (1.f + __expf(-z)); }
; __device__ void gmlp_item(const Params& p, int ch, int gg, char* smem) {
;     ...
;     for (int i = 0; i < 8; ++i) {
;       const int c = i * 64 + lane, row = c >> 4, col8 = (c & 15) * 8;
;       const long t = t0 + 32 * rb + row; const int d = gg * 256 + chh * 128 + col8;
;       const f32x4 a0 = *reinterpret_cast<const f32x4*>(wl + row * 128 + col8), a1 = *reinterpret_cast<const f32x4*>(wl + row * 128 + col8 + 4);
;       const bf16x8 uv = ld8(p.P + t * LDP + C_U + d), zv = ld8(p.P + t * LDP + C_ZG + d);
;       float f[8];
; #pragma unroll
;       for (int j = 0; j < 4; ++j) { f[j] = bf2f((unsigned short)uv[j]) * a0[j] * silu_f(bf2f((unsigned short)zv[j]));
;                                     f[4 + j] = bf2f((unsigned short)uv[4 + j]) * a1[j] * silu_f(bf2f((unsigned short)zv[4 + j])); }
;       u32x4 w = {cvtpk(f[0], f[1]), cvtpk(f[2], f[3]), cvtpk(f[4], f[5]), cvtpk(f[6], f[7])};
;       *reinterpret_cast<u32x4*>(p.y + t * DM + 2048 + d) = w;
	s_nop 1
	v_addc_co_u32_e32 v9, vcc, 0, v13, vcc
	v_add_co_u32_e32 v12, vcc, s23, v12
	global_load_dwordx4 v[8:11], v[8:9], off offset:2048
	s_nop 0
	v_addc_co_u32_e32 v13, vcc, 0, v13, vcc
	global_load_dwordx4 v[12:15], v[12:13], off offset:2048
	ds_read_b128 v[16:19], v137
	ds_read_b128 v[20:23], v137 offset:16
	s_waitcnt vmcnt(1)
	v_and_b32_e32 v7, 0xffff0000, v8
	v_lshlrev_b32_e32 v8, 16, v8
	v_mul_f32_e32 v29, 0xbfb8aa3b, v7
	s_waitcnt vmcnt(0)
	v_and_b32_e32 v27, 0xffff0000, v14
	v_lshlrev_b32_e32 v26, 16, v14
	v_mul_f32_e32 v14, 0xbfb8aa3b, v8
	v_exp_f32_e32 v28, v14
	v_exp_f32_e32 v29, v29
	v_and_b32_e32 v25, 0xffff0000, v12
	v_lshlrev_b32_e32 v24, 16, v12
	v_and_b32_e32 v12, 0xffff0000, v10
	v_lshlrev_b32_e32 v10, 16, v10
	s_waitcnt lgkmcnt(1)
	v_pk_mul_f32 v[16:17], v[16:17], v[24:25]
	v_pk_add_f32 v[24:25], v[28:29], 1.0 op_sel_hi:[1,0]
	v_mul_f32_e32 v30, 0xbfb8aa3b, v10
	v_mul_f32_e32 v31, 0xbfb8aa3b, v12
	v_div_scale_f32 v14, s[2:3], v25, v25, v7
	v_exp_f32_e32 v30, v30
	v_exp_f32_e32 v31, v31
	v_div_scale_f32 v29, s[2:3], v24, v24, v8
	v_rcp_f32_e32 v32, v14
	v_rcp_f32_e32 v33, v29
	s_waitcnt lgkmcnt(0)
	v_pk_mul_f32 v[20:21], v[20:21], v[26:27]
	v_pk_add_f32 v[26:27], v[30:31], 1.0 op_sel_hi:[1,0]
	v_fma_f32 v36, -v14, v32, 1.0
	v_div_scale_f32 v28, vcc, v7, v25, v7
	v_div_scale_f32 v31, s[2:3], v27, v27, v12
	v_fma_f32 v37, -v29, v33, 1.0
	v_fmac_f32_e32 v32, v36, v32
	v_div_scale_f32 v30, s[12:13], v8, v24, v8
	v_rcp_f32_e32 v34, v31
	v_fmac_f32_e32 v33, v37, v33
	v_mul_f32_e32 v36, v28, v32
	v_mul_f32_e32 v37, v30, v33
	v_fma_f32 v39, -v14, v36, v28
	v_fma_f32 v40, -v29, v37, v30
	v_fmac_f32_e32 v36, v39, v32
	v_fmac_f32_e32 v37, v40, v33
	v_fma_f32 v14, -v14, v36, v28
	v_fma_f32 v38, -v31, v34, 1.0
	v_fma_f32 v28, -v29, v37, v30
	v_div_fmas_f32 v14, v14, v32, v36
	s_mov_b64 vcc, s[12:13]
	v_div_scale_f32 v35, s[14:15], v12, v27, v12
	v_fmac_f32_e32 v34, v38, v34
	v_div_fixup_f32 v25, v14, v25, v7
	v_div_fmas_f32 v7, v28, v33, v37
	v_mul_f32_e32 v38, v35, v34
	v_div_fixup_f32 v24, v7, v24, v8
	v_div_scale_f32 v8, s[2:3], v26, v26, v10
	v_fma_f32 v41, -v31, v38, v35
	v_rcp_f32_e32 v14, v8
	v_fmac_f32_e32 v38, v41, v34
	v_fma_f32 v7, -v31, v38, v35
	s_mov_b64 vcc, s[14:15]
	v_div_fmas_f32 v7, v7, v34, v38
	v_pk_mul_f32 v[16:17], v[16:17], v[24:25]
	v_div_fixup_f32 v25, v7, v27, v12
	v_fma_f32 v7, -v8, v14, 1.0
	v_fmac_f32_e32 v14, v7, v14
	v_div_scale_f32 v7, vcc, v10, v26, v10
	v_mul_f32_e32 v12, v7, v14
	v_fma_f32 v24, -v8, v12, v7
	v_fmac_f32_e32 v12, v24, v14
	v_and_b32_e32 v27, 0xffff0000, v9
	v_lshlrev_b32_e32 v28, 16, v9
	v_fma_f32 v7, -v8, v12, v7
	v_mul_f32_e32 v8, 0xbfb8aa3b, v28
	v_mul_f32_e32 v9, 0xbfb8aa3b, v27
	v_exp_f32_e32 v8, v8
	v_exp_f32_e32 v9, v9
	v_div_fmas_f32 v7, v7, v14, v12
	v_div_fixup_f32 v24, v7, v26, v10
	v_pk_mul_f32 v[20:21], v[20:21], v[24:25]
	v_pk_add_f32 v[8:9], v[8:9], 1.0 op_sel_hi:[1,0]
	v_and_b32_e32 v25, 0xffff0000, v13
	v_div_scale_f32 v7, s[2:3], v9, v9, v27
	v_rcp_f32_e32 v10, v7
	v_lshlrev_b32_e32 v24, 16, v13
	v_pk_mul_f32 v[12:13], v[18:19], v[24:25]
	v_lshlrev_b32_e32 v24, 16, v11
	v_fma_f32 v14, -v7, v10, 1.0
	v_fmac_f32_e32 v10, v14, v10
	v_div_scale_f32 v14, vcc, v27, v9, v27
	v_mul_f32_e32 v18, v14, v10
	v_fma_f32 v19, -v7, v18, v14
	v_fmac_f32_e32 v18, v19, v10
	v_fma_f32 v7, -v7, v18, v14
	v_div_scale_f32 v14, s[2:3], v8, v8, v28
	v_rcp_f32_e32 v19, v14
	v_div_fmas_f32 v7, v7, v10, v18
	v_div_fixup_f32 v9, v7, v9, v27
	v_fma_f32 v7, -v14, v19, 1.0
	v_fmac_f32_e32 v19, v7, v19
	v_div_scale_f32 v7, vcc, v28, v8, v28
	v_mul_f32_e32 v18, v7, v19
	v_fma_f32 v10, -v14, v18, v7
	v_fmac_f32_e32 v18, v10, v19
	v_fma_f32 v7, -v14, v18, v7
	v_and_b32_e32 v14, 0xffff0000, v11
	v_mul_f32_e32 v10, 0xbfb8aa3b, v24
	v_mul_f32_e32 v11, 0xbfb8aa3b, v14
	v_exp_f32_e32 v10, v10
	v_exp_f32_e32 v11, v11
	v_div_fmas_f32 v7, v7, v19, v18
	v_div_fixup_f32 v8, v7, v8, v28
	v_pk_mul_f32 v[12:13], v[12:13], v[8:9]
	v_pk_add_f32 v[8:9], v[10:11], 1.0 op_sel_hi:[1,0]
	v_and_b32_e32 v11, 0xffff0000, v15
	v_div_scale_f32 v7, s[2:3], v9, v9, v14
	v_rcp_f32_e32 v18, v7
	v_lshlrev_b32_e32 v10, 16, v15
	v_pk_mul_f32 v[10:11], v[22:23], v[10:11]
	v_fma_f32 v15, -v7, v18, 1.0
	v_fmac_f32_e32 v18, v15, v18
	v_div_scale_f32 v15, vcc, v14, v9, v14
	v_mul_f32_e32 v19, v15, v18
	v_fma_f32 v22, -v7, v19, v15
	v_fmac_f32_e32 v19, v22, v18
	v_fma_f32 v7, -v7, v19, v15
	v_div_scale_f32 v15, s[2:3], v8, v8, v24
	v_rcp_f32_e32 v22, v15
	v_div_fmas_f32 v7, v7, v18, v19
	v_div_fixup_f32 v9, v7, v9, v14
	v_fma_f32 v7, -v15, v22, 1.0
	v_fmac_f32_e32 v22, v7, v22
	v_div_scale_f32 v7, vcc, v24, v8, v24
	v_mul_f32_e32 v14, v7, v22
	v_fma_f32 v18, -v15, v14, v7
	v_fmac_f32_e32 v14, v18, v22
	v_fma_f32 v7, -v15, v14, v7
	v_div_fmas_f32 v7, v7, v22, v14
	v_div_fixup_f32 v8, v7, v8, v24
	v_pk_mul_f32 v[14:15], v[10:11], v[8:9]
	v_cvt_pk_bf16_f32 v9, v12, v13
	v_lshlrev_b64 v[12:13], 13, v[92:93]
	v_lshl_add_u64 v[12:13], s[48:49], 0, v[12:13]
	v_lshl_add_u64 v[12:13], v[12:13], 0, v[2:3]
	v_add_co_u32_e32 v12, vcc, s5, v12
	v_cvt_pk_bf16_f32 v8, v16, v17
	v_cvt_pk_bf16_f32 v10, v20, v21
	v_cvt_pk_bf16_f32 v11, v14, v15
	v_addc_co_u32_e32 v13, vcc, 0, v13, vcc
	v_or_b32_e32 v92, v6, v113
	global_store_dwordx4 v[12:13], v[8:11], off
	s_nop 1
	v_mad_u64_u32 v[8:9], s[2:3], v92, s52, v[4:5]
	v_lshl_add_u64 v[12:13], v[8:9], 0, v[2:3]
	v_add_co_u32_e32 v8, vcc, s50, v12
	s_nop 1
	v_addc_co_u32_e32 v9, vcc, 0, v13, vcc
	global_load_dwordx4 v[8:11], v[8:9], off offset:2048
	v_add_co_u32_e32 v12, vcc, s23, v12
	s_nop 1
	v_addc_co_u32_e32 v13, vcc, 0, v13, vcc
	global_load_dwordx4 v[12:15], v[12:13], off offset:2048
	s_waitcnt vmcnt(1)
; __device__ __forceinline__ float bf2f(unsigned short u) { return __uint_as_float(((unsigned)u) << 16); }
; __device__ __forceinline__ float silu_f(float z) { return z / (1.f + __expf(-z)); }
; __device__ void gmlp_item(const Params& p, int ch, int gg, char* smem) {
;     ...
;     for (int i = 0; i < 8; ++i) {
;       const int c = i * 64 + lane, row = c >> 4, col8 = (c & 15) * 8;
;       const long t = t0 + 32 * rb + row; const int d = gg * 256 + chh * 128 + col8;
;       const f32x4 a0 = *reinterpret_cast<const f32x4*>(wl + row * 128 + col8), a1 = *reinterpret_cast<const f32x4*>(wl + row * 128 + col8 + 4);
;       const bf16x8 uv = ld8(p.P + t * LDP + C_U + d), zv = ld8(p.P + t * LDP + C_ZG + d);
;       float f[8];
; #pragma unroll
;       for (int j = 0; j < 4; ++j) { f[j] = bf2f((unsigned short)uv[j]) * a0[j] * silu_f(bf2f((unsigned short)zv[j]));
;                                     f[4 + j] = bf2f((unsigned short)uv[4 + j]) * a1[j] * silu_f(bf2f((unsigned short)zv[4 + j])); }
;       u32x4 w = {cvtpk(f[0], f[1]), cvtpk(f[2], f[3]), cvtpk(f[4], f[5]), cvtpk(f[6], f[7])};
;       *reinterpret_cast<u32x4*>(p.y + t * DM + 2048 + d) = w;
	v_and_b32_e32 v7, 0xffff0000, v8
	v_lshlrev_b32_e32 v8, 16, v8
	v_mul_f32_e32 v16, 0xbfb8aa3b, v8
	v_exp_f32_e32 v24, v16
	v_mul_f32_e32 v16, 0xbfb8aa3b, v7
	v_exp_f32_e32 v25, v16
	ds_read_b128 v[16:19], v138
	ds_read_b128 v[20:23], v138 offset:16
	s_waitcnt vmcnt(0)
	v_and_b32_e32 v27, 0xffff0000, v12
	v_lshlrev_b32_e32 v26, 16, v12
	v_pk_add_f32 v[24:25], v[24:25], 1.0 op_sel_hi:[1,0]
	s_waitcnt lgkmcnt(1)
	v_pk_mul_f32 v[16:17], v[16:17], v[26:27]
	v_div_scale_f32 v28, s[2:3], v25, v25, v7
	v_rcp_f32_e32 v29, v28
	s_nop 0
	v_fma_f32 v12, -v28, v29, 1.0
	v_fmac_f32_e32 v29, v12, v29
	v_div_scale_f32 v12, vcc, v7, v25, v7
	v_mul_f32_e32 v26, v12, v29
	v_fma_f32 v27, -v28, v26, v12
	v_fmac_f32_e32 v26, v27, v29
	v_div_scale_f32 v27, s[2:3], v24, v24, v8
	v_fma_f32 v12, -v28, v26, v12
	v_rcp_f32_e32 v28, v27
	v_div_fmas_f32 v12, v12, v29, v26
	v_div_fixup_f32 v25, v12, v25, v7
	v_and_b32_e32 v29, 0xffff0000, v10
	v_fma_f32 v7, -v27, v28, 1.0
	v_fmac_f32_e32 v28, v7, v28
	v_div_scale_f32 v7, vcc, v8, v24, v8
	v_mul_f32_e32 v12, v7, v28
	v_fma_f32 v26, -v27, v12, v7
	v_fmac_f32_e32 v12, v26, v28
	v_lshlrev_b32_e32 v10, 16, v10
	v_fma_f32 v7, -v27, v12, v7
	v_mul_f32_e32 v26, 0xbfb8aa3b, v10
	v_mul_f32_e32 v27, 0xbfb8aa3b, v29
	v_exp_f32_e32 v26, v26
	v_exp_f32_e32 v27, v27
	v_div_fmas_f32 v7, v7, v28, v12
	v_div_fixup_f32 v24, v7, v24, v8
	v_pk_mul_f32 v[16:17], v[16:17], v[24:25]
	v_pk_add_f32 v[24:25], v[26:27], 1.0 op_sel_hi:[1,0]
	v_and_b32_e32 v27, 0xffff0000, v14
	v_div_scale_f32 v7, s[2:3], v25, v25, v29
	v_rcp_f32_e32 v8, v7
	v_lshlrev_b32_e32 v26, 16, v14
	s_waitcnt lgkmcnt(0)
	v_pk_mul_f32 v[20:21], v[20:21], v[26:27]
	v_and_b32_e32 v27, 0xffff0000, v9
	v_fma_f32 v12, -v7, v8, 1.0
	v_fmac_f32_e32 v8, v12, v8
	v_div_scale_f32 v12, vcc, v29, v25, v29
	v_mul_f32_e32 v14, v12, v8
	v_fma_f32 v26, -v7, v14, v12
	v_fmac_f32_e32 v14, v26, v8
	v_fma_f32 v7, -v7, v14, v12
	v_div_scale_f32 v12, s[2:3], v24, v24, v10
	v_rcp_f32_e32 v26, v12
	v_div_fmas_f32 v7, v7, v8, v14
	v_div_fixup_f32 v25, v7, v25, v29
	v_lshlrev_b32_e32 v28, 16, v9
	v_fma_f32 v7, -v12, v26, 1.0
	v_fmac_f32_e32 v26, v7, v26
	v_div_scale_f32 v7, vcc, v10, v24, v10
	v_mul_f32_e32 v14, v7, v26
	v_fma_f32 v8, -v12, v14, v7
	v_fmac_f32_e32 v14, v8, v26
	v_mul_f32_e32 v8, 0xbfb8aa3b, v28
	v_mul_f32_e32 v9, 0xbfb8aa3b, v27
	v_exp_f32_e32 v8, v8
	v_exp_f32_e32 v9, v9
	v_fma_f32 v7, -v12, v14, v7
	v_div_fmas_f32 v7, v7, v26, v14
	v_div_fixup_f32 v24, v7, v24, v10
	v_pk_add_f32 v[8:9], v[8:9], 1.0 op_sel_hi:[1,0]
	v_pk_mul_f32 v[20:21], v[20:21], v[24:25]
	v_div_scale_f32 v7, s[2:3], v9, v9, v27
	v_rcp_f32_e32 v10, v7
	v_and_b32_e32 v25, 0xffff0000, v13
	v_lshlrev_b32_e32 v24, 16, v13
	v_pk_mul_f32 v[12:13], v[18:19], v[24:25]
	v_fma_f32 v14, -v7, v10, 1.0
	v_fmac_f32_e32 v10, v14, v10
	v_div_scale_f32 v14, vcc, v27, v9, v27
	v_mul_f32_e32 v18, v14, v10
	v_fma_f32 v19, -v7, v18, v14
	v_fmac_f32_e32 v18, v19, v10
	v_fma_f32 v7, -v7, v18, v14
	v_div_scale_f32 v14, s[2:3], v8, v8, v28
	v_rcp_f32_e32 v19, v14
	v_div_fmas_f32 v7, v7, v10, v18
	v_div_fixup_f32 v9, v7, v9, v27
	v_lshlrev_b32_e32 v24, 16, v11
	v_fma_f32 v7, -v14, v19, 1.0
	v_fmac_f32_e32 v19, v7, v19
	v_div_scale_f32 v7, vcc, v28, v8, v28
	v_mul_f32_e32 v18, v7, v19
	v_fma_f32 v10, -v14, v18, v7
	v_fmac_f32_e32 v18, v10, v19
	v_fma_f32 v7, -v14, v18, v7
	v_and_b32_e32 v14, 0xffff0000, v11
	v_mul_f32_e32 v10, 0xbfb8aa3b, v24
	v_mul_f32_e32 v11, 0xbfb8aa3b, v14
	v_exp_f32_e32 v10, v10
	v_exp_f32_e32 v11, v11
	v_div_fmas_f32 v7, v7, v19, v18
	v_div_fixup_f32 v8, v7, v8, v28
	v_pk_mul_f32 v[12:13], v[12:13], v[8:9]
	v_pk_add_f32 v[8:9], v[10:11], 1.0 op_sel_hi:[1,0]
	v_and_b32_e32 v11, 0xffff0000, v15
	v_div_scale_f32 v7, s[2:3], v9, v9, v14
	v_rcp_f32_e32 v18, v7
	v_lshlrev_b32_e32 v10, 16, v15
	v_pk_mul_f32 v[10:11], v[22:23], v[10:11]
	v_fma_f32 v15, -v7, v18, 1.0
	v_fmac_f32_e32 v18, v15, v18
	v_div_scale_f32 v15, vcc, v14, v9, v14
	v_mul_f32_e32 v19, v15, v18
	v_fma_f32 v22, -v7, v19, v15
	v_fmac_f32_e32 v19, v22, v18
	v_fma_f32 v7, -v7, v19, v15
	v_div_scale_f32 v15, s[2:3], v8, v8, v24
	v_rcp_f32_e32 v22, v15
	v_div_fmas_f32 v7, v7, v18, v19
	v_div_fixup_f32 v9, v7, v9, v14
	v_fma_f32 v7, -v15, v22, 1.0
	v_fmac_f32_e32 v22, v7, v22
	v_div_scale_f32 v7, vcc, v24, v8, v24
	v_mul_f32_e32 v14, v7, v22
	v_fma_f32 v18, -v15, v14, v7
	v_fmac_f32_e32 v14, v18, v22
	v_fma_f32 v7, -v15, v14, v7
	v_div_fmas_f32 v7, v7, v22, v14
	v_div_fixup_f32 v8, v7, v8, v24
	v_pk_mul_f32 v[14:15], v[10:11], v[8:9]
	v_cvt_pk_bf16_f32 v9, v12, v13
	v_lshlrev_b64 v[12:13], 13, v[92:93]
	v_lshl_add_u64 v[12:13], s[48:49], 0, v[12:13]
	v_lshl_add_u64 v[12:13], v[12:13], 0, v[2:3]
	v_add_co_u32_e32 v12, vcc, s5, v12
	v_cvt_pk_bf16_f32 v8, v16, v17
	v_cvt_pk_bf16_f32 v10, v20, v21
	v_cvt_pk_bf16_f32 v11, v14, v15
	v_addc_co_u32_e32 v13, vcc, 0, v13, vcc
	v_or_b32_e32 v92, v6, v114
	global_store_dwordx4 v[12:13], v[8:11], off
	s_nop 1
	v_mad_u64_u32 v[8:9], s[2:3], v92, s52, v[4:5]
	v_lshl_add_u64 v[12:13], v[8:9], 0, v[2:3]
	v_add_co_u32_e32 v8, vcc, s50, v12
	s_nop 1
	v_addc_co_u32_e32 v9, vcc, 0, v13, vcc
	global_load_dwordx4 v[8:11], v[8:9], off offset:2048
	v_add_co_u32_e32 v12, vcc, s23, v12
	s_nop 1
	v_addc_co_u32_e32 v13, vcc, 0, v13, vcc
	global_load_dwordx4 v[12:15], v[12:13], off offset:2048
	s_waitcnt vmcnt(1)
	v_and_b32_e32 v7, 0xffff0000, v8
	v_lshlrev_b32_e32 v8, 16, v8
	v_mul_f32_e32 v16, 0xbfb8aa3b, v8
	v_exp_f32_e32 v24, v16
	v_mul_f32_e32 v16, 0xbfb8aa3b, v7
	v_exp_f32_e32 v25, v16
	ds_read_b128 v[16:19], v139
	ds_read_b128 v[20:23], v139 offset:16
	s_waitcnt vmcnt(0)
; __device__ __forceinline__ float bf2f(unsigned short u) { return __uint_as_float(((unsigned)u) << 16); }
; __device__ __forceinline__ float silu_f(float z) { return z / (1.f + __expf(-z)); }
; __device__ void gmlp_item(const Params& p, int ch, int gg, char* smem) {
;     ...
;     for (int i = 0; i < 8; ++i) {
;       const int c = i * 64 + lane, row = c >> 4, col8 = (c & 15) * 8;
;       const long t = t0 + 32 * rb + row; const int d = gg * 256 + chh * 128 + col8;
;       const f32x4 a0 = *reinterpret_cast<const f32x4*>(wl + row * 128 + col8), a1 = *reinterpret_cast<const f32x4*>(wl + row * 128 + col8 + 4);
;       const bf16x8 uv = ld8(p.P + t * LDP + C_U + d), zv = ld8(p.P + t * LDP + C_ZG + d);
;       float f[8];
; #pragma unroll
;       for (int j = 0; j < 4; ++j) { f[j] = bf2f((unsigned short)uv[j]) * a0[j] * silu_f(bf2f((unsigned short)zv[j]));
;                                     f[4 + j] = bf2f((unsigned short)uv[4 + j]) * a1[j] * silu_f(bf2f((unsigned short)zv[4 + j])); }
;       u32x4 w = {cvtpk(f[0], f[1]), cvtpk(f[2], f[3]), cvtpk(f[4], f[5]), cvtpk(f[6], f[7])};
;       *reinterpret_cast<u32x4*>(p.y + t * DM + 2048 + d) = w;
	v_and_b32_e32 v27, 0xffff0000, v12
	v_lshlrev_b32_e32 v26, 16, v12
	v_pk_add_f32 v[24:25], v[24:25], 1.0 op_sel_hi:[1,0]
	s_waitcnt lgkmcnt(1)
	v_pk_mul_f32 v[16:17], v[16:17], v[26:27]
	v_div_scale_f32 v28, s[2:3], v25, v25, v7
	v_rcp_f32_e32 v29, v28
	s_nop 0
	v_fma_f32 v12, -v28, v29, 1.0
	v_fmac_f32_e32 v29, v12, v29
	v_div_scale_f32 v12, vcc, v7, v25, v7
	v_mul_f32_e32 v26, v12, v29
	v_fma_f32 v27, -v28, v26, v12
	v_fmac_f32_e32 v26, v27, v29
	v_div_scale_f32 v27, s[2:3], v24, v24, v8
	v_fma_f32 v12, -v28, v26, v12
	v_rcp_f32_e32 v28, v27
	v_div_fmas_f32 v12, v12, v29, v26
	v_div_fixup_f32 v25, v12, v25, v7
	v_and_b32_e32 v29, 0xffff0000, v10
	v_fma_f32 v7, -v27, v28, 1.0
	v_fmac_f32_e32 v28, v7, v28
	v_div_scale_f32 v7, vcc, v8, v24, v8
	v_mul_f32_e32 v12, v7, v28
	v_fma_f32 v26, -v27, v12, v7
	v_fmac_f32_e32 v12, v26, v28
	v_lshlrev_b32_e32 v10, 16, v10
	v_fma_f32 v7, -v27, v12, v7
	v_mul_f32_e32 v26, 0xbfb8aa3b, v10
	v_mul_f32_e32 v27, 0xbfb8aa3b, v29
	v_exp_f32_e32 v26, v26
	v_exp_f32_e32 v27, v27
	v_div_fmas_f32 v7, v7, v28, v12
	v_div_fixup_f32 v24, v7, v24, v8
	v_pk_mul_f32 v[16:17], v[16:17], v[24:25]
	v_pk_add_f32 v[24:25], v[26:27], 1.0 op_sel_hi:[1,0]
	v_and_b32_e32 v27, 0xffff0000, v14
	v_div_scale_f32 v7, s[2:3], v25, v25, v29
	v_rcp_f32_e32 v8, v7
	v_lshlrev_b32_e32 v26, 16, v14
	s_waitcnt lgkmcnt(0)
	v_pk_mul_f32 v[20:21], v[20:21], v[26:27]
	v_and_b32_e32 v27, 0xffff0000, v9
	v_fma_f32 v12, -v7, v8, 1.0
	v_fmac_f32_e32 v8, v12, v8
	v_div_scale_f32 v12, vcc, v29, v25, v29
	v_mul_f32_e32 v14, v12, v8
	v_fma_f32 v26, -v7, v14, v12
	v_fmac_f32_e32 v14, v26, v8
	v_fma_f32 v7, -v7, v14, v12
	v_div_scale_f32 v12, s[2:3], v24, v24, v10
	v_rcp_f32_e32 v26, v12
	v_div_fmas_f32 v7, v7, v8, v14
	v_div_fixup_f32 v25, v7, v25, v29
	v_lshlrev_b32_e32 v28, 16, v9
	v_fma_f32 v7, -v12, v26, 1.0
	v_fmac_f32_e32 v26, v7, v26
	v_div_scale_f32 v7, vcc, v10, v24, v10
	v_mul_f32_e32 v14, v7, v26
	v_fma_f32 v8, -v12, v14, v7
	v_fmac_f32_e32 v14, v8, v26
	v_mul_f32_e32 v8, 0xbfb8aa3b, v28
	v_mul_f32_e32 v9, 0xbfb8aa3b, v27
	v_exp_f32_e32 v8, v8
	v_exp_f32_e32 v9, v9
	v_fma_f32 v7, -v12, v14, v7
	v_div_fmas_f32 v7, v7, v26, v14
	v_div_fixup_f32 v24, v7, v24, v10
	v_pk_add_f32 v[8:9], v[8:9], 1.0 op_sel_hi:[1,0]
	v_pk_mul_f32 v[20:21], v[20:21], v[24:25]
	v_div_scale_f32 v7, s[2:3], v9, v9, v27
	v_rcp_f32_e32 v10, v7
	v_and_b32_e32 v25, 0xffff0000, v13
	v_lshlrev_b32_e32 v24, 16, v13
	v_pk_mul_f32 v[12:13], v[18:19], v[24:25]
	v_fma_f32 v14, -v7, v10, 1.0
	v_fmac_f32_e32 v10, v14, v10
	v_div_scale_f32 v14, vcc, v27, v9, v27
	v_mul_f32_e32 v18, v14, v10
	v_fma_f32 v19, -v7, v18, v14
	v_fmac_f32_e32 v18, v19, v10
	v_fma_f32 v7, -v7, v18, v14
	v_div_scale_f32 v14, s[2:3], v8, v8, v28
	v_rcp_f32_e32 v19, v14
	v_div_fmas_f32 v7, v7, v10, v18
	v_div_fixup_f32 v9, v7, v9, v27
	v_lshlrev_b32_e32 v24, 16, v11
	v_fma_f32 v7, -v14, v19, 1.0
	v_fmac_f32_e32 v19, v7, v19
	v_div_scale_f32 v7, vcc, v28, v8, v28
	v_mul_f32_e32 v18, v7, v19
	v_fma_f32 v10, -v14, v18, v7
	v_fmac_f32_e32 v18, v10, v19
	v_fma_f32 v7, -v14, v18, v7
	v_and_b32_e32 v14, 0xffff0000, v11
	v_mul_f32_e32 v10, 0xbfb8aa3b, v24
	v_mul_f32_e32 v11, 0xbfb8aa3b, v14
	v_exp_f32_e32 v10, v10
	v_exp_f32_e32 v11, v11
	v_div_fmas_f32 v7, v7, v19, v18
	v_div_fixup_f32 v8, v7, v8, v28
	v_pk_mul_f32 v[12:13], v[12:13], v[8:9]
	v_pk_add_f32 v[8:9], v[10:11], 1.0 op_sel_hi:[1,0]
	v_and_b32_e32 v11, 0xffff0000, v15
	v_div_scale_f32 v7, s[2:3], v9, v9, v14
	v_rcp_f32_e32 v18, v7
	v_lshlrev_b32_e32 v10, 16, v15
	v_pk_mul_f32 v[10:11], v[22:23], v[10:11]
	v_fma_f32 v15, -v7, v18, 1.0
	v_fmac_f32_e32 v18, v15, v18
	v_div_scale_f32 v15, vcc, v14, v9, v14
	v_mul_f32_e32 v19, v15, v18
	v_fma_f32 v22, -v7, v19, v15
	v_fmac_f32_e32 v19, v22, v18
	v_fma_f32 v7, -v7, v19, v15
	v_div_scale_f32 v15, s[2:3], v8, v8, v24
	v_rcp_f32_e32 v22, v15
	v_div_fmas_f32 v7, v7, v18, v19
	v_div_fixup_f32 v9, v7, v9, v14
	v_fma_f32 v7, -v15, v22, 1.0
	v_fmac_f32_e32 v22, v7, v22
	v_div_scale_f32 v7, vcc, v24, v8, v24
	v_mul_f32_e32 v14, v7, v22
	v_fma_f32 v18, -v15, v14, v7
	v_fmac_f32_e32 v14, v18, v22
	v_fma_f32 v7, -v15, v14, v7
	v_div_fmas_f32 v7, v7, v22, v14
	v_div_fixup_f32 v8, v7, v8, v24
	v_pk_mul_f32 v[14:15], v[10:11], v[8:9]
	v_cvt_pk_bf16_f32 v9, v12, v13
	v_lshlrev_b64 v[12:13], 13, v[92:93]
	v_lshl_add_u64 v[12:13], s[48:49], 0, v[12:13]
	v_lshl_add_u64 v[12:13], v[12:13], 0, v[2:3]
	v_add_co_u32_e32 v12, vcc, s5, v12
	v_cvt_pk_bf16_f32 v8, v16, v17
	v_cvt_pk_bf16_f32 v10, v20, v21
	v_cvt_pk_bf16_f32 v11, v14, v15
	v_addc_co_u32_e32 v13, vcc, 0, v13, vcc
	v_or_b32_e32 v92, v6, v115
	global_store_dwordx4 v[12:13], v[8:11], off
	s_nop 1
	v_mad_u64_u32 v[8:9], s[2:3], v92, s52, v[4:5]
	v_lshl_add_u64 v[12:13], v[8:9], 0, v[2:3]
	v_add_co_u32_e32 v8, vcc, s50, v12
	s_nop 1
	v_addc_co_u32_e32 v9, vcc, 0, v13, vcc
	global_load_dwordx4 v[8:11], v[8:9], off offset:2048
	v_add_co_u32_e32 v12, vcc, s23, v12
	s_nop 1
	v_addc_co_u32_e32 v13, vcc, 0, v13, vcc
	global_load_dwordx4 v[12:15], v[12:13], off offset:2048
	s_waitcnt vmcnt(1)
	v_and_b32_e32 v7, 0xffff0000, v8
	v_lshlrev_b32_e32 v8, 16, v8
	v_mul_f32_e32 v16, 0xbfb8aa3b, v8
	v_exp_f32_e32 v24, v16
	v_mul_f32_e32 v16, 0xbfb8aa3b, v7
	v_exp_f32_e32 v25, v16
	ds_read_b128 v[16:19], v140
	ds_read_b128 v[20:23], v140 offset:16
	s_waitcnt vmcnt(0)
	v_and_b32_e32 v27, 0xffff0000, v12
	v_lshlrev_b32_e32 v26, 16, v12
	v_pk_add_f32 v[24:25], v[24:25], 1.0 op_sel_hi:[1,0]
	s_waitcnt lgkmcnt(1)
; __device__ __forceinline__ float bf2f(unsigned short u) { return __uint_as_float(((unsigned)u) << 16); }
; __device__ __forceinline__ float silu_f(float z) { return z / (1.f + __expf(-z)); }
; __device__ void gmlp_item(const Params& p, int ch, int gg, char* smem) {
;     ...
;     for (int i = 0; i < 8; ++i) {
;       const int c = i * 64 + lane, row = c >> 4, col8 = (c & 15) * 8;
;       const long t = t0 + 32 * rb + row; const int d = gg * 256 + chh * 128 + col8;
;       const f32x4 a0 = *reinterpret_cast<const f32x4*>(wl + row * 128 + col8), a1 = *reinterpret_cast<const f32x4*>(wl + row * 128 + col8 + 4);
;       const bf16x8 uv = ld8(p.P + t * LDP + C_U + d), zv = ld8(p.P + t * LDP + C_ZG + d);
;       float f[8];
; #pragma unroll
;       for (int j = 0; j < 4; ++j) { f[j] = bf2f((unsigned short)uv[j]) * a0[j] * silu_f(bf2f((unsigned short)zv[j]));
;                                     f[4 + j] = bf2f((unsigned short)uv[4 + j]) * a1[j] * silu_f(bf2f((unsigned short)zv[4 + j])); }
;       u32x4 w = {cvtpk(f[0], f[1]), cvtpk(f[2], f[3]), cvtpk(f[4], f[5]), cvtpk(f[6], f[7])};
;       *reinterpret_cast<u32x4*>(p.y + t * DM + 2048 + d) = w;
	v_pk_mul_f32 v[16:17], v[16:17], v[26:27]
	v_div_scale_f32 v28, s[2:3], v25, v25, v7
	v_rcp_f32_e32 v29, v28
	s_nop 0
	v_fma_f32 v12, -v28, v29, 1.0
	v_fmac_f32_e32 v29, v12, v29
	v_div_scale_f32 v12, vcc, v7, v25, v7
	v_mul_f32_e32 v26, v12, v29
	v_fma_f32 v27, -v28, v26, v12
	v_fmac_f32_e32 v26, v27, v29
	v_div_scale_f32 v27, s[2:3], v24, v24, v8
	v_fma_f32 v12, -v28, v26, v12
	v_rcp_f32_e32 v28, v27
	v_div_fmas_f32 v12, v12, v29, v26
	v_div_fixup_f32 v25, v12, v25, v7
	v_and_b32_e32 v29, 0xffff0000, v10
	v_fma_f32 v7, -v27, v28, 1.0
	v_fmac_f32_e32 v28, v7, v28
	v_div_scale_f32 v7, vcc, v8, v24, v8
	v_mul_f32_e32 v12, v7, v28
	v_fma_f32 v26, -v27, v12, v7
	v_fmac_f32_e32 v12, v26, v28
	v_lshlrev_b32_e32 v10, 16, v10
	v_fma_f32 v7, -v27, v12, v7
	v_mul_f32_e32 v26, 0xbfb8aa3b, v10
	v_mul_f32_e32 v27, 0xbfb8aa3b, v29
	v_exp_f32_e32 v26, v26
	v_exp_f32_e32 v27, v27
	v_div_fmas_f32 v7, v7, v28, v12
	v_div_fixup_f32 v24, v7, v24, v8
	v_pk_mul_f32 v[16:17], v[16:17], v[24:25]
	v_pk_add_f32 v[24:25], v[26:27], 1.0 op_sel_hi:[1,0]
	v_and_b32_e32 v27, 0xffff0000, v14
	v_div_scale_f32 v7, s[2:3], v25, v25, v29
	v_rcp_f32_e32 v8, v7
	v_lshlrev_b32_e32 v26, 16, v14
	s_waitcnt lgkmcnt(0)
	v_pk_mul_f32 v[20:21], v[20:21], v[26:27]
	v_and_b32_e32 v27, 0xffff0000, v9
	v_fma_f32 v12, -v7, v8, 1.0
	v_fmac_f32_e32 v8, v12, v8
	v_div_scale_f32 v12, vcc, v29, v25, v29
	v_mul_f32_e32 v14, v12, v8
	v_fma_f32 v26, -v7, v14, v12
	v_fmac_f32_e32 v14, v26, v8
	v_fma_f32 v7, -v7, v14, v12
	v_div_scale_f32 v12, s[2:3], v24, v24, v10
	v_rcp_f32_e32 v26, v12
	v_div_fmas_f32 v7, v7, v8, v14
	v_div_fixup_f32 v25, v7, v25, v29
	v_lshlrev_b32_e32 v28, 16, v9
	v_fma_f32 v7, -v12, v26, 1.0
	v_fmac_f32_e32 v26, v7, v26
	v_div_scale_f32 v7, vcc, v10, v24, v10
	v_mul_f32_e32 v14, v7, v26
	v_fma_f32 v8, -v12, v14, v7
	v_fmac_f32_e32 v14, v8, v26
	v_mul_f32_e32 v8, 0xbfb8aa3b, v28
	v_mul_f32_e32 v9, 0xbfb8aa3b, v27
	v_exp_f32_e32 v8, v8
	v_exp_f32_e32 v9, v9
	v_fma_f32 v7, -v12, v14, v7
	v_div_fmas_f32 v7, v7, v26, v14
	v_div_fixup_f32 v24, v7, v24, v10
	v_pk_add_f32 v[8:9], v[8:9], 1.0 op_sel_hi:[1,0]
	v_pk_mul_f32 v[20:21], v[20:21], v[24:25]
	v_div_scale_f32 v7, s[2:3], v9, v9, v27
	v_rcp_f32_e32 v10, v7
	v_and_b32_e32 v25, 0xffff0000, v13
	v_lshlrev_b32_e32 v24, 16, v13
	v_pk_mul_f32 v[12:13], v[18:19], v[24:25]
	v_fma_f32 v14, -v7, v10, 1.0
	v_fmac_f32_e32 v10, v14, v10
	v_div_scale_f32 v14, vcc, v27, v9, v27
	v_mul_f32_e32 v18, v14, v10
	v_fma_f32 v19, -v7, v18, v14
	v_fmac_f32_e32 v18, v19, v10
	v_fma_f32 v7, -v7, v18, v14
	v_div_scale_f32 v14, s[2:3], v8, v8, v28
	v_rcp_f32_e32 v19, v14
	v_div_fmas_f32 v7, v7, v10, v18
	v_div_fixup_f32 v9, v7, v9, v27
	v_lshlrev_b32_e32 v24, 16, v11
	v_fma_f32 v7, -v14, v19, 1.0
	v_fmac_f32_e32 v19, v7, v19
	v_div_scale_f32 v7, vcc, v28, v8, v28
	v_mul_f32_e32 v18, v7, v19
	v_fma_f32 v10, -v14, v18, v7
	v_fmac_f32_e32 v18, v10, v19
	v_fma_f32 v7, -v14, v18, v7
	v_and_b32_e32 v14, 0xffff0000, v11
	v_mul_f32_e32 v10, 0xbfb8aa3b, v24
	v_mul_f32_e32 v11, 0xbfb8aa3b, v14
	v_exp_f32_e32 v10, v10
	v_exp_f32_e32 v11, v11
	v_div_fmas_f32 v7, v7, v19, v18
	v_div_fixup_f32 v8, v7, v8, v28
	v_pk_mul_f32 v[12:13], v[12:13], v[8:9]
	v_pk_add_f32 v[8:9], v[10:11], 1.0 op_sel_hi:[1,0]
	v_and_b32_e32 v11, 0xffff0000, v15
	v_div_scale_f32 v7, s[2:3], v9, v9, v14
	v_rcp_f32_e32 v18, v7
	v_lshlrev_b32_e32 v10, 16, v15
	v_pk_mul_f32 v[10:11], v[22:23], v[10:11]
	v_fma_f32 v15, -v7, v18, 1.0
	v_fmac_f32_e32 v18, v15, v18
	v_div_scale_f32 v15, vcc, v14, v9, v14
	v_mul_f32_e32 v19, v15, v18
	v_fma_f32 v22, -v7, v19, v15
	v_fmac_f32_e32 v19, v22, v18
	v_fma_f32 v7, -v7, v19, v15
	v_div_scale_f32 v15, s[2:3], v8, v8, v24
	v_rcp_f32_e32 v22, v15
	v_div_fmas_f32 v7, v7, v18, v19
	v_div_fixup_f32 v9, v7, v9, v14
	v_fma_f32 v7, -v15, v22, 1.0
	v_fmac_f32_e32 v22, v7, v22
	v_div_scale_f32 v7, vcc, v24, v8, v24
	v_mul_f32_e32 v14, v7, v22
	v_fma_f32 v18, -v15, v14, v7
	v_fmac_f32_e32 v14, v18, v22
	v_fma_f32 v7, -v15, v14, v7
	v_div_fmas_f32 v7, v7, v22, v14
	v_div_fixup_f32 v8, v7, v8, v24
	v_pk_mul_f32 v[14:15], v[10:11], v[8:9]
	v_cvt_pk_bf16_f32 v9, v12, v13
	v_lshlrev_b64 v[12:13], 13, v[92:93]
	v_lshl_add_u64 v[12:13], s[48:49], 0, v[12:13]
	v_lshl_add_u64 v[12:13], v[12:13], 0, v[2:3]
	v_add_co_u32_e32 v12, vcc, s5, v12
	v_cvt_pk_bf16_f32 v8, v16, v17
	v_cvt_pk_bf16_f32 v10, v20, v21
	v_cvt_pk_bf16_f32 v11, v14, v15
	v_addc_co_u32_e32 v13, vcc, 0, v13, vcc
	v_or_b32_e32 v92, v6, v116
	global_store_dwordx4 v[12:13], v[8:11], off
	s_nop 1
	v_mad_u64_u32 v[8:9], s[2:3], v92, s52, v[4:5]
	v_lshl_add_u64 v[12:13], v[8:9], 0, v[2:3]
	v_add_co_u32_e32 v8, vcc, s50, v12
	s_nop 1
	v_addc_co_u32_e32 v9, vcc, 0, v13, vcc
	global_load_dwordx4 v[8:11], v[8:9], off offset:2048
	v_add_co_u32_e32 v12, vcc, s23, v12
	s_nop 1
	v_addc_co_u32_e32 v13, vcc, 0, v13, vcc
	global_load_dwordx4 v[12:15], v[12:13], off offset:2048
	s_waitcnt vmcnt(1)
	v_and_b32_e32 v7, 0xffff0000, v8
	v_lshlrev_b32_e32 v8, 16, v8
	v_mul_f32_e32 v16, 0xbfb8aa3b, v8
	v_exp_f32_e32 v24, v16
	v_mul_f32_e32 v16, 0xbfb8aa3b, v7
	v_exp_f32_e32 v25, v16
	ds_read_b128 v[16:19], v141
	ds_read_b128 v[20:23], v141 offset:16
	s_waitcnt vmcnt(0)
	v_and_b32_e32 v27, 0xffff0000, v12
	v_lshlrev_b32_e32 v26, 16, v12
	v_pk_add_f32 v[24:25], v[24:25], 1.0 op_sel_hi:[1,0]
	s_waitcnt lgkmcnt(1)
; __device__ __forceinline__ float bf2f(unsigned short u) { return __uint_as_float(((unsigned)u) << 16); }
; __device__ __forceinline__ float silu_f(float z) { return z / (1.f + __expf(-z)); }
; __device__ void gmlp_item(const Params& p, int ch, int gg, char* smem) {
;     ...
;     for (int i = 0; i < 8; ++i) {
;       const int c = i * 64 + lane, row = c >> 4, col8 = (c & 15) * 8;
;       const long t = t0 + 32 * rb + row; const int d = gg * 256 + chh * 128 + col8;
;       const f32x4 a0 = *reinterpret_cast<const f32x4*>(wl + row * 128 + col8), a1 = *reinterpret_cast<const f32x4*>(wl + row * 128 + col8 + 4);
;       const bf16x8 uv = ld8(p.P + t * LDP + C_U + d), zv = ld8(p.P + t * LDP + C_ZG + d);
;       float f[8];
; #pragma unroll
;       for (int j = 0; j < 4; ++j) { f[j] = bf2f((unsigned short)uv[j]) * a0[j] * silu_f(bf2f((unsigned short)zv[j]));
;                                     f[4 + j] = bf2f((unsigned short)uv[4 + j]) * a1[j] * silu_f(bf2f((unsigned short)zv[4 + j])); }
;       u32x4 w = {cvtpk(f[0], f[1]), cvtpk(f[2], f[3]), cvtpk(f[4], f[5]), cvtpk(f[6], f[7])};
;       *reinterpret_cast<u32x4*>(p.y + t * DM + 2048 + d) = w;
	v_pk_mul_f32 v[16:17], v[16:17], v[26:27]
	v_div_scale_f32 v28, s[2:3], v25, v25, v7
	v_rcp_f32_e32 v29, v28
	s_nop 0
	v_fma_f32 v12, -v28, v29, 1.0
	v_fmac_f32_e32 v29, v12, v29
	v_div_scale_f32 v12, vcc, v7, v25, v7
	v_mul_f32_e32 v26, v12, v29
	v_fma_f32 v27, -v28, v26, v12
	v_fmac_f32_e32 v26, v27, v29
	v_div_scale_f32 v27, s[2:3], v24, v24, v8
	v_fma_f32 v12, -v28, v26, v12
	v_rcp_f32_e32 v28, v27
	v_div_fmas_f32 v12, v12, v29, v26
	v_div_fixup_f32 v25, v12, v25, v7
	v_and_b32_e32 v29, 0xffff0000, v10
	v_fma_f32 v7, -v27, v28, 1.0
	v_fmac_f32_e32 v28, v7, v28
	v_div_scale_f32 v7, vcc, v8, v24, v8
	v_mul_f32_e32 v12, v7, v28
	v_fma_f32 v26, -v27, v12, v7
	v_fmac_f32_e32 v12, v26, v28
	v_lshlrev_b32_e32 v10, 16, v10
	v_fma_f32 v7, -v27, v12, v7
	v_mul_f32_e32 v26, 0xbfb8aa3b, v10
	v_mul_f32_e32 v27, 0xbfb8aa3b, v29
	v_exp_f32_e32 v26, v26
	v_exp_f32_e32 v27, v27
	v_div_fmas_f32 v7, v7, v28, v12
	v_div_fixup_f32 v24, v7, v24, v8
	v_pk_mul_f32 v[16:17], v[16:17], v[24:25]
	v_pk_add_f32 v[24:25], v[26:27], 1.0 op_sel_hi:[1,0]
	v_and_b32_e32 v27, 0xffff0000, v14
	v_div_scale_f32 v7, s[2:3], v25, v25, v29
	v_rcp_f32_e32 v8, v7
	v_lshlrev_b32_e32 v26, 16, v14
	s_waitcnt lgkmcnt(0)
	v_pk_mul_f32 v[20:21], v[20:21], v[26:27]
	v_and_b32_e32 v27, 0xffff0000, v9
	v_fma_f32 v12, -v7, v8, 1.0
	v_fmac_f32_e32 v8, v12, v8
	v_div_scale_f32 v12, vcc, v29, v25, v29
	v_mul_f32_e32 v14, v12, v8
	v_fma_f32 v26, -v7, v14, v12
	v_fmac_f32_e32 v14, v26, v8
	v_fma_f32 v7, -v7, v14, v12
	v_div_scale_f32 v12, s[2:3], v24, v24, v10
	v_rcp_f32_e32 v26, v12
	v_div_fmas_f32 v7, v7, v8, v14
	v_div_fixup_f32 v25, v7, v25, v29
	v_lshlrev_b32_e32 v28, 16, v9
	v_fma_f32 v7, -v12, v26, 1.0
	v_fmac_f32_e32 v26, v7, v26
	v_div_scale_f32 v7, vcc, v10, v24, v10
	v_mul_f32_e32 v14, v7, v26
	v_fma_f32 v8, -v12, v14, v7
	v_fmac_f32_e32 v14, v8, v26
	v_mul_f32_e32 v8, 0xbfb8aa3b, v28
	v_mul_f32_e32 v9, 0xbfb8aa3b, v27
	v_exp_f32_e32 v8, v8
	v_exp_f32_e32 v9, v9
	v_fma_f32 v7, -v12, v14, v7
	v_div_fmas_f32 v7, v7, v26, v14
	v_div_fixup_f32 v24, v7, v24, v10
	v_pk_add_f32 v[8:9], v[8:9], 1.0 op_sel_hi:[1,0]
	v_pk_mul_f32 v[20:21], v[20:21], v[24:25]
	v_div_scale_f32 v7, s[2:3], v9, v9, v27
	v_rcp_f32_e32 v10, v7
	v_and_b32_e32 v25, 0xffff0000, v13
	v_lshlrev_b32_e32 v24, 16, v13
	v_pk_mul_f32 v[12:13], v[18:19], v[24:25]
	v_fma_f32 v14, -v7, v10, 1.0
	v_fmac_f32_e32 v10, v14, v10
	v_div_scale_f32 v14, vcc, v27, v9, v27
	v_mul_f32_e32 v18, v14, v10
	v_fma_f32 v19, -v7, v18, v14
	v_fmac_f32_e32 v18, v19, v10
	v_fma_f32 v7, -v7, v18, v14
	v_div_scale_f32 v14, s[2:3], v8, v8, v28
	v_rcp_f32_e32 v19, v14
	v_div_fmas_f32 v7, v7, v10, v18
	v_div_fixup_f32 v9, v7, v9, v27
	v_lshlrev_b32_e32 v24, 16, v11
	v_fma_f32 v7, -v14, v19, 1.0
	v_fmac_f32_e32 v19, v7, v19
	v_div_scale_f32 v7, vcc, v28, v8, v28
	v_mul_f32_e32 v18, v7, v19
	v_fma_f32 v10, -v14, v18, v7
	v_fmac_f32_e32 v18, v10, v19
	v_fma_f32 v7, -v14, v18, v7
	v_and_b32_e32 v14, 0xffff0000, v11
	v_mul_f32_e32 v10, 0xbfb8aa3b, v24
	v_mul_f32_e32 v11, 0xbfb8aa3b, v14
	v_exp_f32_e32 v10, v10
	v_exp_f32_e32 v11, v11
	v_div_fmas_f32 v7, v7, v19, v18
	v_div_fixup_f32 v8, v7, v8, v28
	v_pk_mul_f32 v[12:13], v[12:13], v[8:9]
	v_pk_add_f32 v[8:9], v[10:11], 1.0 op_sel_hi:[1,0]
	v_and_b32_e32 v11, 0xffff0000, v15
	v_div_scale_f32 v7, s[2:3], v9, v9, v14
	v_rcp_f32_e32 v18, v7
	v_lshlrev_b32_e32 v10, 16, v15
	v_pk_mul_f32 v[10:11], v[22:23], v[10:11]
	v_fma_f32 v15, -v7, v18, 1.0
	v_fmac_f32_e32 v18, v15, v18
	v_div_scale_f32 v15, vcc, v14, v9, v14
	v_mul_f32_e32 v19, v15, v18
	v_fma_f32 v22, -v7, v19, v15
	v_fmac_f32_e32 v19, v22, v18
	v_fma_f32 v7, -v7, v19, v15
	v_div_scale_f32 v15, s[2:3], v8, v8, v24
	v_rcp_f32_e32 v22, v15
	v_div_fmas_f32 v7, v7, v18, v19
	v_div_fixup_f32 v9, v7, v9, v14
	v_fma_f32 v7, -v15, v22, 1.0
	v_fmac_f32_e32 v22, v7, v22
	v_div_scale_f32 v7, vcc, v24, v8, v24
	v_mul_f32_e32 v14, v7, v22
	v_fma_f32 v18, -v15, v14, v7
	v_fmac_f32_e32 v14, v18, v22
	v_fma_f32 v7, -v15, v14, v7
	v_div_fmas_f32 v7, v7, v22, v14
	v_div_fixup_f32 v8, v7, v8, v24
	v_pk_mul_f32 v[14:15], v[10:11], v[8:9]
	v_cvt_pk_bf16_f32 v9, v12, v13
	v_lshlrev_b64 v[12:13], 13, v[92:93]
	v_lshl_add_u64 v[12:13], s[48:49], 0, v[12:13]
	v_lshl_add_u64 v[12:13], v[12:13], 0, v[2:3]
	v_add_co_u32_e32 v12, vcc, s5, v12
	v_cvt_pk_bf16_f32 v8, v16, v17
	v_cvt_pk_bf16_f32 v10, v20, v21
	v_cvt_pk_bf16_f32 v11, v14, v15
	v_addc_co_u32_e32 v13, vcc, 0, v13, vcc
	v_or_b32_e32 v92, v6, v117
	global_store_dwordx4 v[12:13], v[8:11], off
	s_nop 1
	v_mad_u64_u32 v[8:9], s[2:3], v92, s52, v[4:5]
	v_lshl_add_u64 v[12:13], v[8:9], 0, v[2:3]
	v_add_co_u32_e32 v8, vcc, s50, v12
	s_nop 1
	v_addc_co_u32_e32 v9, vcc, 0, v13, vcc
	global_load_dwordx4 v[8:11], v[8:9], off offset:2048
	v_add_co_u32_e32 v12, vcc, s23, v12
	s_nop 1
	v_addc_co_u32_e32 v13, vcc, 0, v13, vcc
	global_load_dwordx4 v[12:15], v[12:13], off offset:2048
	s_waitcnt vmcnt(1)
	v_and_b32_e32 v7, 0xffff0000, v8
	v_lshlrev_b32_e32 v8, 16, v8
	v_mul_f32_e32 v16, 0xbfb8aa3b, v8
	v_exp_f32_e32 v24, v16
	v_mul_f32_e32 v16, 0xbfb8aa3b, v7
	v_exp_f32_e32 v25, v16
	ds_read_b128 v[16:19], v142
	ds_read_b128 v[20:23], v142 offset:16
	s_waitcnt vmcnt(0)
	v_and_b32_e32 v27, 0xffff0000, v12
	v_lshlrev_b32_e32 v26, 16, v12
	v_pk_add_f32 v[24:25], v[24:25], 1.0 op_sel_hi:[1,0]
	s_waitcnt lgkmcnt(1)
; __device__ __forceinline__ float bf2f(unsigned short u) { return __uint_as_float(((unsigned)u) << 16); }
; __device__ __forceinline__ float silu_f(float z) { return z / (1.f + __expf(-z)); }
; __device__ void gmlp_item(const Params& p, int ch, int gg, char* smem) {
;     ...
;     for (int i = 0; i < 8; ++i) {
;       const int c = i * 64 + lane, row = c >> 4, col8 = (c & 15) * 8;
;       const long t = t0 + 32 * rb + row; const int d = gg * 256 + chh * 128 + col8;
;       const f32x4 a0 = *reinterpret_cast<const f32x4*>(wl + row * 128 + col8), a1 = *reinterpret_cast<const f32x4*>(wl + row * 128 + col8 + 4);
;       const bf16x8 uv = ld8(p.P + t * LDP + C_U + d), zv = ld8(p.P + t * LDP + C_ZG + d);
;       float f[8];
; #pragma unroll
;       for (int j = 0; j < 4; ++j) { f[j] = bf2f((unsigned short)uv[j]) * a0[j] * silu_f(bf2f((unsigned short)zv[j]));
;                                     f[4 + j] = bf2f((unsigned short)uv[4 + j]) * a1[j] * silu_f(bf2f((unsigned short)zv[4 + j])); }
;       u32x4 w = {cvtpk(f[0], f[1]), cvtpk(f[2], f[3]), cvtpk(f[4], f[5]), cvtpk(f[6], f[7])};
;       *reinterpret_cast<u32x4*>(p.y + t * DM + 2048 + d) = w;
	v_pk_mul_f32 v[16:17], v[16:17], v[26:27]
	v_div_scale_f32 v28, s[2:3], v25, v25, v7
	v_rcp_f32_e32 v29, v28
	s_nop 0
	v_fma_f32 v12, -v28, v29, 1.0
	v_fmac_f32_e32 v29, v12, v29
	v_div_scale_f32 v12, vcc, v7, v25, v7
	v_mul_f32_e32 v26, v12, v29
	v_fma_f32 v27, -v28, v26, v12
	v_fmac_f32_e32 v26, v27, v29
	v_div_scale_f32 v27, s[2:3], v24, v24, v8
	v_fma_f32 v12, -v28, v26, v12
	v_rcp_f32_e32 v28, v27
	v_div_fmas_f32 v12, v12, v29, v26
	v_div_fixup_f32 v25, v12, v25, v7
	v_and_b32_e32 v29, 0xffff0000, v10
	v_fma_f32 v7, -v27, v28, 1.0
	v_fmac_f32_e32 v28, v7, v28
	v_div_scale_f32 v7, vcc, v8, v24, v8
	v_mul_f32_e32 v12, v7, v28
	v_fma_f32 v26, -v27, v12, v7
	v_fmac_f32_e32 v12, v26, v28
	v_lshlrev_b32_e32 v10, 16, v10
	v_fma_f32 v7, -v27, v12, v7
	v_mul_f32_e32 v26, 0xbfb8aa3b, v10
	v_mul_f32_e32 v27, 0xbfb8aa3b, v29
	v_exp_f32_e32 v26, v26
	v_exp_f32_e32 v27, v27
	v_div_fmas_f32 v7, v7, v28, v12
	v_div_fixup_f32 v24, v7, v24, v8
	v_pk_mul_f32 v[16:17], v[16:17], v[24:25]
	v_pk_add_f32 v[24:25], v[26:27], 1.0 op_sel_hi:[1,0]
	v_and_b32_e32 v27, 0xffff0000, v14
	v_div_scale_f32 v7, s[2:3], v25, v25, v29
	v_rcp_f32_e32 v8, v7
	v_lshlrev_b32_e32 v26, 16, v14
	s_waitcnt lgkmcnt(0)
	v_pk_mul_f32 v[20:21], v[20:21], v[26:27]
	v_and_b32_e32 v27, 0xffff0000, v9
	v_fma_f32 v12, -v7, v8, 1.0
	v_fmac_f32_e32 v8, v12, v8
	v_div_scale_f32 v12, vcc, v29, v25, v29
	v_mul_f32_e32 v14, v12, v8
	v_fma_f32 v26, -v7, v14, v12
	v_fmac_f32_e32 v14, v26, v8
	v_fma_f32 v7, -v7, v14, v12
	v_div_scale_f32 v12, s[2:3], v24, v24, v10
	v_rcp_f32_e32 v26, v12
	v_div_fmas_f32 v7, v7, v8, v14
	v_div_fixup_f32 v25, v7, v25, v29
	v_lshlrev_b32_e32 v28, 16, v9
	v_fma_f32 v7, -v12, v26, 1.0
	v_fmac_f32_e32 v26, v7, v26
	v_div_scale_f32 v7, vcc, v10, v24, v10
	v_mul_f32_e32 v14, v7, v26
	v_fma_f32 v8, -v12, v14, v7
	v_fmac_f32_e32 v14, v8, v26
	v_mul_f32_e32 v8, 0xbfb8aa3b, v28
	v_mul_f32_e32 v9, 0xbfb8aa3b, v27
	v_exp_f32_e32 v8, v8
	v_exp_f32_e32 v9, v9
	v_fma_f32 v7, -v12, v14, v7
	v_div_fmas_f32 v7, v7, v26, v14
	v_div_fixup_f32 v24, v7, v24, v10
	v_pk_add_f32 v[8:9], v[8:9], 1.0 op_sel_hi:[1,0]
	v_pk_mul_f32 v[20:21], v[20:21], v[24:25]
	v_div_scale_f32 v7, s[2:3], v9, v9, v27
	v_rcp_f32_e32 v10, v7
	v_and_b32_e32 v25, 0xffff0000, v13
	v_lshlrev_b32_e32 v24, 16, v13
	v_pk_mul_f32 v[12:13], v[18:19], v[24:25]
	v_fma_f32 v14, -v7, v10, 1.0
	v_fmac_f32_e32 v10, v14, v10
	v_div_scale_f32 v14, vcc, v27, v9, v27
	v_mul_f32_e32 v18, v14, v10
	v_fma_f32 v19, -v7, v18, v14
	v_fmac_f32_e32 v18, v19, v10
	v_fma_f32 v7, -v7, v18, v14
	v_div_scale_f32 v14, s[2:3], v8, v8, v28
	v_rcp_f32_e32 v19, v14
	v_div_fmas_f32 v7, v7, v10, v18
	v_div_fixup_f32 v9, v7, v9, v27
	v_lshlrev_b32_e32 v24, 16, v11
	v_fma_f32 v7, -v14, v19, 1.0
	v_fmac_f32_e32 v19, v7, v19
	v_div_scale_f32 v7, vcc, v28, v8, v28
	v_mul_f32_e32 v18, v7, v19
	v_fma_f32 v10, -v14, v18, v7
	v_fmac_f32_e32 v18, v10, v19
	v_fma_f32 v7, -v14, v18, v7
	v_and_b32_e32 v14, 0xffff0000, v11
	v_mul_f32_e32 v10, 0xbfb8aa3b, v24
	v_mul_f32_e32 v11, 0xbfb8aa3b, v14
	v_exp_f32_e32 v10, v10
	v_exp_f32_e32 v11, v11
	v_div_fmas_f32 v7, v7, v19, v18
	v_div_fixup_f32 v8, v7, v8, v28
	v_pk_mul_f32 v[12:13], v[12:13], v[8:9]
	v_pk_add_f32 v[8:9], v[10:11], 1.0 op_sel_hi:[1,0]
	v_and_b32_e32 v11, 0xffff0000, v15
	v_div_scale_f32 v7, s[2:3], v9, v9, v14
	v_rcp_f32_e32 v18, v7
	v_lshlrev_b32_e32 v10, 16, v15
	v_pk_mul_f32 v[10:11], v[22:23], v[10:11]
	v_fma_f32 v15, -v7, v18, 1.0
	v_fmac_f32_e32 v18, v15, v18
	v_div_scale_f32 v15, vcc, v14, v9, v14
	v_mul_f32_e32 v19, v15, v18
	v_fma_f32 v22, -v7, v19, v15
	v_fmac_f32_e32 v19, v22, v18
	v_fma_f32 v7, -v7, v19, v15
	v_div_scale_f32 v15, s[2:3], v8, v8, v24
	v_rcp_f32_e32 v22, v15
	v_div_fmas_f32 v7, v7, v18, v19
	v_div_fixup_f32 v9, v7, v9, v14
	v_fma_f32 v7, -v15, v22, 1.0
	v_fmac_f32_e32 v22, v7, v22
	v_div_scale_f32 v7, vcc, v24, v8, v24
	v_mul_f32_e32 v14, v7, v22
	v_fma_f32 v18, -v15, v14, v7
	v_fmac_f32_e32 v14, v18, v22
	v_fma_f32 v7, -v15, v14, v7
	v_div_fmas_f32 v7, v7, v22, v14
	v_div_fixup_f32 v8, v7, v8, v24
	v_pk_mul_f32 v[14:15], v[10:11], v[8:9]
	v_cvt_pk_bf16_f32 v9, v12, v13
	v_lshlrev_b64 v[12:13], 13, v[92:93]
	v_lshl_add_u64 v[12:13], s[48:49], 0, v[12:13]
	v_lshl_add_u64 v[12:13], v[12:13], 0, v[2:3]
	v_add_co_u32_e32 v12, vcc, s5, v12
	v_cvt_pk_bf16_f32 v8, v16, v17
	v_cvt_pk_bf16_f32 v10, v20, v21
	v_cvt_pk_bf16_f32 v11, v14, v15
	v_addc_co_u32_e32 v13, vcc, 0, v13, vcc
	v_or_b32_e32 v92, v6, v118
	global_store_dwordx4 v[12:13], v[8:11], off
	s_nop 1
	v_mad_u64_u32 v[8:9], s[2:3], v92, s52, v[4:5]
	v_lshl_add_u64 v[12:13], v[8:9], 0, v[2:3]
	v_add_co_u32_e32 v8, vcc, s50, v12
	s_nop 1
	v_addc_co_u32_e32 v9, vcc, 0, v13, vcc
	global_load_dwordx4 v[8:11], v[8:9], off offset:2048
	v_add_co_u32_e32 v12, vcc, s23, v12
	s_nop 1
	v_addc_co_u32_e32 v13, vcc, 0, v13, vcc
	global_load_dwordx4 v[12:15], v[12:13], off offset:2048
	s_waitcnt vmcnt(1)
	v_and_b32_e32 v7, 0xffff0000, v8
	v_lshlrev_b32_e32 v8, 16, v8
	v_mul_f32_e32 v16, 0xbfb8aa3b, v8
	v_exp_f32_e32 v24, v16
	v_mul_f32_e32 v16, 0xbfb8aa3b, v7
	v_exp_f32_e32 v25, v16
	ds_read_b128 v[16:19], v143
	ds_read_b128 v[20:23], v143 offset:16
	s_waitcnt vmcnt(0)
	v_and_b32_e32 v27, 0xffff0000, v12
	v_lshlrev_b32_e32 v26, 16, v12
	v_pk_add_f32 v[24:25], v[24:25], 1.0 op_sel_hi:[1,0]
	s_waitcnt lgkmcnt(1)
; __device__ __forceinline__ float bf2f(unsigned short u) { return __uint_as_float(((unsigned)u) << 16); }
; __device__ __forceinline__ float silu_f(float z) { return z / (1.f + __expf(-z)); }
; __device__ void gmlp_item(const Params& p, int ch, int gg, char* smem) {
;     ...
;     for (int i = 0; i < 8; ++i) {
;       const int c = i * 64 + lane, row = c >> 4, col8 = (c & 15) * 8;
;       const long t = t0 + 32 * rb + row; const int d = gg * 256 + chh * 128 + col8;
;       const f32x4 a0 = *reinterpret_cast<const f32x4*>(wl + row * 128 + col8), a1 = *reinterpret_cast<const f32x4*>(wl + row * 128 + col8 + 4);
;       const bf16x8 uv = ld8(p.P + t * LDP + C_U + d), zv = ld8(p.P + t * LDP + C_ZG + d);
;       float f[8];
; #pragma unroll
;       for (int j = 0; j < 4; ++j) { f[j] = bf2f((unsigned short)uv[j]) * a0[j] * silu_f(bf2f((unsigned short)zv[j]));
;                                     f[4 + j] = bf2f((unsigned short)uv[4 + j]) * a1[j] * silu_f(bf2f((unsigned short)zv[4 + j])); }
;       u32x4 w = {cvtpk(f[0], f[1]), cvtpk(f[2], f[3]), cvtpk(f[4], f[5]), cvtpk(f[6], f[7])};
;       *reinterpret_cast<u32x4*>(p.y + t * DM + 2048 + d) = w;
	v_pk_mul_f32 v[16:17], v[16:17], v[26:27]
	v_div_scale_f32 v28, s[2:3], v25, v25, v7
	v_rcp_f32_e32 v29, v28
	s_nop 0
	v_fma_f32 v12, -v28, v29, 1.0
	v_fmac_f32_e32 v29, v12, v29
	v_div_scale_f32 v12, vcc, v7, v25, v7
	v_mul_f32_e32 v26, v12, v29
	v_fma_f32 v27, -v28, v26, v12
	v_fmac_f32_e32 v26, v27, v29
	v_div_scale_f32 v27, s[2:3], v24, v24, v8
	v_fma_f32 v12, -v28, v26, v12
	v_rcp_f32_e32 v28, v27
	v_div_fmas_f32 v12, v12, v29, v26
	v_div_fixup_f32 v25, v12, v25, v7
	v_and_b32_e32 v29, 0xffff0000, v10
	v_fma_f32 v7, -v27, v28, 1.0
	v_fmac_f32_e32 v28, v7, v28
	v_div_scale_f32 v7, vcc, v8, v24, v8
	v_mul_f32_e32 v12, v7, v28
	v_fma_f32 v26, -v27, v12, v7
	v_fmac_f32_e32 v12, v26, v28
	v_lshlrev_b32_e32 v10, 16, v10
	v_fma_f32 v7, -v27, v12, v7
	v_mul_f32_e32 v26, 0xbfb8aa3b, v10
	v_mul_f32_e32 v27, 0xbfb8aa3b, v29
	v_exp_f32_e32 v26, v26
	v_exp_f32_e32 v27, v27
	v_div_fmas_f32 v7, v7, v28, v12
	v_div_fixup_f32 v24, v7, v24, v8
	v_pk_mul_f32 v[16:17], v[16:17], v[24:25]
	v_pk_add_f32 v[24:25], v[26:27], 1.0 op_sel_hi:[1,0]
	v_and_b32_e32 v27, 0xffff0000, v14
	v_div_scale_f32 v7, s[2:3], v25, v25, v29
	v_rcp_f32_e32 v8, v7
	v_lshlrev_b32_e32 v26, 16, v14
	s_waitcnt lgkmcnt(0)
	v_pk_mul_f32 v[20:21], v[20:21], v[26:27]
	v_and_b32_e32 v27, 0xffff0000, v9
	v_fma_f32 v12, -v7, v8, 1.0
	v_fmac_f32_e32 v8, v12, v8
	v_div_scale_f32 v12, vcc, v29, v25, v29
	v_mul_f32_e32 v14, v12, v8
	v_fma_f32 v26, -v7, v14, v12
	v_fmac_f32_e32 v14, v26, v8
	v_fma_f32 v7, -v7, v14, v12
	v_div_scale_f32 v12, s[2:3], v24, v24, v10
	v_rcp_f32_e32 v26, v12
	v_div_fmas_f32 v7, v7, v8, v14
	v_div_fixup_f32 v25, v7, v25, v29
	v_lshlrev_b32_e32 v28, 16, v9
	v_fma_f32 v7, -v12, v26, 1.0
	v_fmac_f32_e32 v26, v7, v26
	v_div_scale_f32 v7, vcc, v10, v24, v10
	v_mul_f32_e32 v14, v7, v26
	v_fma_f32 v8, -v12, v14, v7
	v_fmac_f32_e32 v14, v8, v26
	v_mul_f32_e32 v8, 0xbfb8aa3b, v28
	v_mul_f32_e32 v9, 0xbfb8aa3b, v27
	v_exp_f32_e32 v8, v8
	v_exp_f32_e32 v9, v9
	v_fma_f32 v7, -v12, v14, v7
	v_div_fmas_f32 v7, v7, v26, v14
	v_div_fixup_f32 v24, v7, v24, v10
	v_pk_add_f32 v[8:9], v[8:9], 1.0 op_sel_hi:[1,0]
	v_pk_mul_f32 v[20:21], v[20:21], v[24:25]
	v_div_scale_f32 v7, s[2:3], v9, v9, v27
	v_rcp_f32_e32 v10, v7
	v_and_b32_e32 v25, 0xffff0000, v13
	v_lshlrev_b32_e32 v24, 16, v13
	v_pk_mul_f32 v[12:13], v[18:19], v[24:25]
	v_fma_f32 v14, -v7, v10, 1.0
	v_fmac_f32_e32 v10, v14, v10
	v_div_scale_f32 v14, vcc, v27, v9, v27
	v_mul_f32_e32 v18, v14, v10
	v_fma_f32 v19, -v7, v18, v14
	v_fmac_f32_e32 v18, v19, v10
	v_fma_f32 v7, -v7, v18, v14
	v_div_scale_f32 v14, s[2:3], v8, v8, v28
	v_rcp_f32_e32 v19, v14
	v_div_fmas_f32 v7, v7, v10, v18
	v_div_fixup_f32 v9, v7, v9, v27
	v_lshlrev_b32_e32 v24, 16, v11
	v_fma_f32 v7, -v14, v19, 1.0
	v_fmac_f32_e32 v19, v7, v19
	v_div_scale_f32 v7, vcc, v28, v8, v28
	v_mul_f32_e32 v18, v7, v19
	v_fma_f32 v10, -v14, v18, v7
	v_fmac_f32_e32 v18, v10, v19
	v_fma_f32 v7, -v14, v18, v7
	v_and_b32_e32 v14, 0xffff0000, v11
	v_mul_f32_e32 v10, 0xbfb8aa3b, v24
	v_mul_f32_e32 v11, 0xbfb8aa3b, v14
	v_exp_f32_e32 v10, v10
	v_exp_f32_e32 v11, v11
	v_div_fmas_f32 v7, v7, v19, v18
	v_div_fixup_f32 v8, v7, v8, v28
	v_pk_mul_f32 v[12:13], v[12:13], v[8:9]
	v_pk_add_f32 v[8:9], v[10:11], 1.0 op_sel_hi:[1,0]
	v_and_b32_e32 v11, 0xffff0000, v15
	v_div_scale_f32 v7, s[2:3], v9, v9, v14
	v_rcp_f32_e32 v18, v7
	v_lshlrev_b32_e32 v10, 16, v15
	v_pk_mul_f32 v[10:11], v[22:23], v[10:11]
	v_fma_f32 v15, -v7, v18, 1.0
	v_fmac_f32_e32 v18, v15, v18
	v_div_scale_f32 v15, vcc, v14, v9, v14
	v_mul_f32_e32 v19, v15, v18
	v_fma_f32 v22, -v7, v19, v15
	v_fmac_f32_e32 v19, v22, v18
	v_fma_f32 v7, -v7, v19, v15
	v_div_scale_f32 v15, s[2:3], v8, v8, v24
	v_rcp_f32_e32 v22, v15
	v_div_fmas_f32 v7, v7, v18, v19
	v_div_fixup_f32 v9, v7, v9, v14
	v_fma_f32 v7, -v15, v22, 1.0
	v_fmac_f32_e32 v22, v7, v22
	v_div_scale_f32 v7, vcc, v24, v8, v24
	v_mul_f32_e32 v14, v7, v22
	v_fma_f32 v18, -v15, v14, v7
	v_fmac_f32_e32 v14, v18, v22
	v_fma_f32 v7, -v15, v14, v7
	v_div_fmas_f32 v7, v7, v22, v14
	v_div_fixup_f32 v8, v7, v8, v24
	v_pk_mul_f32 v[14:15], v[10:11], v[8:9]
	v_cvt_pk_bf16_f32 v9, v12, v13
	v_lshlrev_b64 v[12:13], 13, v[92:93]
	v_lshl_add_u64 v[12:13], s[48:49], 0, v[12:13]
	v_lshl_add_u64 v[12:13], v[12:13], 0, v[2:3]
	v_add_co_u32_e32 v12, vcc, s5, v12
	v_or_b32_e32 v92, v6, v119
	v_cvt_pk_bf16_f32 v8, v16, v17
	v_cvt_pk_bf16_f32 v10, v20, v21
	v_cvt_pk_bf16_f32 v11, v14, v15
	v_addc_co_u32_e32 v13, vcc, 0, v13, vcc
	v_mad_u64_u32 v[4:5], s[2:3], v92, s52, v[4:5]
	global_store_dwordx4 v[12:13], v[8:11], off
	s_nop 1
	v_lshl_add_u64 v[8:9], v[4:5], 0, v[2:3]
	v_add_co_u32_e32 v4, vcc, s50, v8
	s_nop 1
	v_addc_co_u32_e32 v5, vcc, 0, v9, vcc
	global_load_dwordx4 v[4:7], v[4:5], off offset:2048
	v_add_co_u32_e32 v8, vcc, s23, v8
	s_nop 1
	v_addc_co_u32_e32 v9, vcc, 0, v9, vcc
	global_load_dwordx4 v[8:11], v[8:9], off offset:2048
	s_waitcnt vmcnt(1)
; __device__ __forceinline__ float bf2f(unsigned short u) { return __uint_as_float(((unsigned)u) << 16); }
; __device__ __forceinline__ float silu_f(float z) { return z / (1.f + __expf(-z)); }
; __device__ void gmlp_item(const Params& p, int ch, int gg, char* smem) {
;     ...
;     for (int i = 0; i < 8; ++i) {
;       const int c = i * 64 + lane, row = c >> 4, col8 = (c & 15) * 8;
;       const long t = t0 + 32 * rb + row; const int d = gg * 256 + chh * 128 + col8;
;       const f32x4 a0 = *reinterpret_cast<const f32x4*>(wl + row * 128 + col8), a1 = *reinterpret_cast<const f32x4*>(wl + row * 128 + col8 + 4);
;       const bf16x8 uv = ld8(p.P + t * LDP + C_U + d), zv = ld8(p.P + t * LDP + C_ZG + d);
;       float f[8];
; #pragma unroll
;       for (int j = 0; j < 4; ++j) { f[j] = bf2f((unsigned short)uv[j]) * a0[j] * silu_f(bf2f((unsigned short)zv[j]));
;                                     f[4 + j] = bf2f((unsigned short)uv[4 + j]) * a1[j] * silu_f(bf2f((unsigned short)zv[4 + j])); }
;       u32x4 w = {cvtpk(f[0], f[1]), cvtpk(f[2], f[3]), cvtpk(f[4], f[5]), cvtpk(f[6], f[7])};
;       *reinterpret_cast<u32x4*>(p.y + t * DM + 2048 + d) = w;
;     }
	v_and_b32_e32 v24, 0xffff0000, v4
	v_lshlrev_b32_e32 v4, 16, v4
	v_mul_f32_e32 v12, 0xbfb8aa3b, v4
	v_exp_f32_e32 v20, v12
	v_mul_f32_e32 v12, 0xbfb8aa3b, v24
	v_exp_f32_e32 v21, v12
	ds_read_b128 v[12:15], v144
	ds_read_b128 v[16:19], v144 offset:16
	s_waitcnt vmcnt(0)
	v_and_b32_e32 v23, 0xffff0000, v8
	v_lshlrev_b32_e32 v22, 16, v8
	v_pk_add_f32 v[20:21], v[20:21], 1.0 op_sel_hi:[1,0]
	s_waitcnt lgkmcnt(1)
	v_pk_mul_f32 v[12:13], v[12:13], v[22:23]
	v_div_scale_f32 v25, s[2:3], v21, v21, v24
	v_rcp_f32_e32 v26, v25
	s_nop 0
	v_fma_f32 v8, -v25, v26, 1.0
	v_fmac_f32_e32 v26, v8, v26
	v_div_scale_f32 v8, vcc, v24, v21, v24
	v_mul_f32_e32 v22, v8, v26
	v_fma_f32 v23, -v25, v22, v8
	v_fmac_f32_e32 v22, v23, v26
	v_div_scale_f32 v23, s[2:3], v20, v20, v4
	v_fma_f32 v8, -v25, v22, v8
	v_rcp_f32_e32 v25, v23
	v_div_fmas_f32 v8, v8, v26, v22
	v_div_fixup_f32 v21, v8, v21, v24
	v_and_b32_e32 v26, 0xffff0000, v6
	v_fma_f32 v8, -v23, v25, 1.0
	v_fmac_f32_e32 v25, v8, v25
	v_div_scale_f32 v8, vcc, v4, v20, v4
	v_mul_f32_e32 v24, v8, v25
	v_fma_f32 v22, -v23, v24, v8
	v_fmac_f32_e32 v24, v22, v25
	v_lshlrev_b32_e32 v6, 16, v6
	v_fma_f32 v8, -v23, v24, v8
	v_mul_f32_e32 v22, 0xbfb8aa3b, v6
	v_mul_f32_e32 v23, 0xbfb8aa3b, v26
	v_exp_f32_e32 v22, v22
	v_exp_f32_e32 v23, v23
	v_div_fmas_f32 v8, v8, v25, v24
	v_div_fixup_f32 v20, v8, v20, v4
	v_pk_mul_f32 v[12:13], v[12:13], v[20:21]
	v_pk_add_f32 v[20:21], v[22:23], 1.0 op_sel_hi:[1,0]
	v_and_b32_e32 v23, 0xffff0000, v10
	v_div_scale_f32 v4, s[2:3], v21, v21, v26
	v_rcp_f32_e32 v8, v4
	v_lshlrev_b32_e32 v22, 16, v10
	s_waitcnt lgkmcnt(0)
	v_pk_mul_f32 v[16:17], v[16:17], v[22:23]
	v_lshlrev_b32_e32 v24, 16, v5
	v_fma_f32 v10, -v4, v8, 1.0
	v_fmac_f32_e32 v8, v10, v8
	v_div_scale_f32 v10, vcc, v26, v21, v26
	v_mul_f32_e32 v22, v10, v8
	v_fma_f32 v23, -v4, v22, v10
	v_fmac_f32_e32 v22, v23, v8
	v_fma_f32 v4, -v4, v22, v10
	v_div_scale_f32 v10, s[2:3], v20, v20, v6
	v_rcp_f32_e32 v23, v10
	v_div_fmas_f32 v4, v4, v8, v22
	v_div_fixup_f32 v21, v4, v21, v26
	v_fma_f32 v4, -v10, v23, 1.0
	v_fmac_f32_e32 v23, v4, v23
	v_div_scale_f32 v4, vcc, v6, v20, v6
	v_mul_f32_e32 v8, v4, v23
	v_fma_f32 v22, -v10, v8, v4
	v_fmac_f32_e32 v8, v22, v23
	v_and_b32_e32 v22, 0xffff0000, v5
	v_fma_f32 v10, -v10, v8, v4
	v_mul_f32_e32 v4, 0xbfb8aa3b, v24
	v_mul_f32_e32 v5, 0xbfb8aa3b, v22
	v_exp_f32_e32 v4, v4
	v_exp_f32_e32 v5, v5
	v_div_fmas_f32 v8, v10, v23, v8
	v_div_fixup_f32 v20, v8, v20, v6
	v_pk_mul_f32 v[16:17], v[16:17], v[20:21]
	v_pk_add_f32 v[4:5], v[4:5], 1.0 op_sel_hi:[1,0]
	v_and_b32_e32 v21, 0xffff0000, v9
	v_div_scale_f32 v6, s[2:3], v5, v5, v22
	v_rcp_f32_e32 v10, v6
	v_lshlrev_b32_e32 v20, 16, v9
	v_pk_mul_f32 v[8:9], v[14:15], v[20:21]
	v_lshlrev_b32_e32 v21, 16, v7
	v_fma_f32 v14, -v6, v10, 1.0
	v_fmac_f32_e32 v10, v14, v10
	v_div_scale_f32 v14, vcc, v22, v5, v22
	v_mul_f32_e32 v15, v14, v10
	v_fma_f32 v20, -v6, v15, v14
	v_fmac_f32_e32 v15, v20, v10
	v_fma_f32 v6, -v6, v15, v14
	v_div_scale_f32 v14, s[2:3], v4, v4, v24
	v_rcp_f32_e32 v20, v14
	v_div_fmas_f32 v6, v6, v10, v15
	v_div_fixup_f32 v5, v6, v5, v22
	v_fma_f32 v6, -v14, v20, 1.0
	v_fmac_f32_e32 v20, v6, v20
	v_div_scale_f32 v6, vcc, v24, v4, v24
	v_mul_f32_e32 v10, v6, v20
	v_fma_f32 v15, -v14, v10, v6
	v_fmac_f32_e32 v10, v15, v20
	v_and_b32_e32 v15, 0xffff0000, v7
	v_fma_f32 v14, -v14, v10, v6
	v_mul_f32_e32 v6, 0xbfb8aa3b, v21
	v_mul_f32_e32 v7, 0xbfb8aa3b, v15
	v_exp_f32_e32 v6, v6
	v_exp_f32_e32 v7, v7
	v_div_fmas_f32 v10, v14, v20, v10
	v_div_fixup_f32 v4, v10, v4, v24
	v_pk_mul_f32 v[8:9], v[8:9], v[4:5]
	v_pk_add_f32 v[4:5], v[6:7], 1.0 op_sel_hi:[1,0]
	v_and_b32_e32 v7, 0xffff0000, v11
	v_div_scale_f32 v10, s[2:3], v5, v5, v15
	v_rcp_f32_e32 v14, v10
	v_lshlrev_b32_e32 v6, 16, v11
	v_pk_mul_f32 v[6:7], v[18:19], v[6:7]
	v_fma_f32 v11, -v10, v14, 1.0
	v_fmac_f32_e32 v14, v11, v14
	v_div_scale_f32 v11, vcc, v15, v5, v15
	v_mul_f32_e32 v18, v11, v14
	v_fma_f32 v19, -v10, v18, v11
	v_fmac_f32_e32 v18, v19, v14
	v_fma_f32 v10, -v10, v18, v11
	v_div_scale_f32 v11, s[2:3], v4, v4, v21
	v_rcp_f32_e32 v19, v11
	v_div_fmas_f32 v10, v10, v14, v18
	v_div_fixup_f32 v5, v10, v5, v15
	s_mov_b64 s[2:3], 0
	v_fma_f32 v10, -v11, v19, 1.0
	v_fmac_f32_e32 v19, v10, v19
	v_div_scale_f32 v10, vcc, v21, v4, v21
	v_mul_f32_e32 v14, v10, v19
	v_fma_f32 v15, -v11, v14, v10
	v_fmac_f32_e32 v14, v15, v19
	v_fma_f32 v10, -v11, v14, v10
	v_div_fmas_f32 v10, v10, v19, v14
	v_div_fixup_f32 v4, v10, v4, v21
	v_pk_mul_f32 v[10:11], v[6:7], v[4:5]
	v_cvt_pk_bf16_f32 v5, v8, v9
	v_lshlrev_b64 v[8:9], 13, v[92:93]
	v_lshl_add_u64 v[8:9], s[48:49], 0, v[8:9]
	v_lshl_add_u64 v[2:3], v[8:9], 0, v[2:3]
	v_add_co_u32_e32 v2, vcc, 0x1000, v2
	v_cvt_pk_bf16_f32 v4, v12, v13
	v_cvt_pk_bf16_f32 v6, v16, v17
	v_cvt_pk_bf16_f32 v7, v10, v11
	v_addc_co_u32_e32 v3, vcc, 0, v3, vcc
	global_store_dwordx4 v[2:3], v[4:7], off

; __device__ __forceinline__ void unpark_fma(f32x16* o, const char* pk, int lane, const f32x4* f4) {
; #pragma unroll
;   for (int d0 = 0; d0 < 4; ++d0)
; #pragma unroll
;     for (int a = 0; a < 4; ++a) { const u32x2 w = *reinterpret_cast<const u32x2*>(pk + ((d0 * 4 + a) * 64 + lane) * 8);
;       o[d0][4 * a + 0] = fmaf(o[d0][4 * a + 0], f4[a][0], __uint_as_float(w[0] << 16));
;       o[d0][4 * a + 1] = fmaf(o[d0][4 * a + 1], f4[a][1], __uint_as_float(w[0] & 0xffff0000u));
;       o[d0][4 * a + 2] = fmaf(o[d0][4 * a + 2], f4[a][2], __uint_as_float(w[1] << 16));
;       o[d0][4 * a + 3] = fmaf(o[d0][4 * a + 3], f4[a][3], __uint_as_float(w[1] & 0xffff0000u)); }
; }
; template <int MODE>
; __device__ __forceinline__ void nsa_single(const Params& p, const LaneId& L, int q0, int g, int ntiles, int first, char* smem, const bf16x8* qr, float gate, f32x16* o) {
;     ...
;   { const float f = (l > 0.f) ? gate / l : 0.f; f32x4 f4[4]; row_bcast(fac, L, f, f4); unpark_fma(o, pk, L.lane, f4); }
;   __syncthreads();
.LBB0_239:
	s_or_b64 exec, exec, s[10:11]
	v_add_u32_e32 v88, v144, v145
	ds_read_b128 v[80:83], v147
	ds_read_b128 v[76:79], v147 offset:32
	ds_read_b128 v[72:75], v147 offset:64
	ds_read_b128 v[68:71], v147 offset:96
	ds_read2st64_b64 v[90:93], v88 offset1:1
	s_movk_i32 s0, 0x78
	s_waitcnt lgkmcnt(0)
	v_lshlrev_b32_e32 v86, 16, v90
	v_and_b32_e32 v87, 0xffff0000, v90
	v_lshlrev_b32_e32 v84, 16, v91
	v_fmac_f32_e32 v86, v52, v80
	v_fmac_f32_e32 v87, v53, v81
	v_fmac_f32_e32 v84, v54, v82
	v_lshlrev_b32_e32 v53, 16, v92
	v_and_b32_e32 v54, 0xffff0000, v92
	v_lshlrev_b32_e32 v2, 16, v93
	v_and_b32_e32 v52, 0xffff0000, v93
	v_fmac_f32_e32 v53, v56, v76
	v_fmac_f32_e32 v54, v57, v77
	v_fmac_f32_e32 v2, v58, v78
	v_fmac_f32_e32 v52, v59, v79
	ds_read2st64_b64 v[56:59], v88 offset0:2 offset1:3
	v_and_b32_e32 v85, 0xffff0000, v91
	v_fmac_f32_e32 v85, v55, v83
	s_waitcnt lgkmcnt(0)
	v_lshlrev_b32_e32 v55, 16, v56
	v_fmac_f32_e32 v55, v60, v72
	v_and_b32_e32 v60, 0xffff0000, v56
	v_fmac_f32_e32 v60, v61, v73
	v_lshlrev_b32_e32 v61, 16, v57
	v_fmac_f32_e32 v61, v62, v74
	v_and_b32_e32 v62, 0xffff0000, v57
	v_fmac_f32_e32 v62, v63, v75
	v_lshlrev_b32_e32 v63, 16, v58
	v_fmac_f32_e32 v63, v64, v68
	v_and_b32_e32 v64, 0xffff0000, v58
	v_fmac_f32_e32 v64, v65, v69
	v_lshlrev_b32_e32 v65, 16, v59
	v_fmac_f32_e32 v65, v66, v70
	v_and_b32_e32 v66, 0xffff0000, v59
	ds_read2st64_b64 v[56:59], v88 offset0:4 offset1:5
	v_fmac_f32_e32 v66, v67, v71
	s_waitcnt lgkmcnt(0)
	v_lshlrev_b32_e32 v67, 16, v56
	v_and_b32_e32 v56, 0xffff0000, v56
	v_lshlrev_b32_e32 v89, 16, v57
	v_and_b32_e32 v57, 0xffff0000, v57
	v_fmac_f32_e32 v67, v36, v80
	v_fmac_f32_e32 v56, v37, v81
	v_fmac_f32_e32 v89, v38, v82
	v_fmac_f32_e32 v57, v39, v83
	ds_read2st64_b64 v[36:39], v88 offset0:6 offset1:7
	v_lshlrev_b32_e32 v90, 16, v58
	v_fmac_f32_e32 v90, v40, v76
	v_and_b32_e32 v40, 0xffff0000, v58
	v_fmac_f32_e32 v40, v41, v77
	v_lshlrev_b32_e32 v41, 16, v59
	v_fmac_f32_e32 v41, v42, v78
	v_and_b32_e32 v42, 0xffff0000, v59
	v_fmac_f32_e32 v42, v43, v79
	s_waitcnt lgkmcnt(0)
	v_lshlrev_b32_e32 v43, 16, v36
	v_fmac_f32_e32 v43, v44, v72
	v_and_b32_e32 v44, 0xffff0000, v36
	v_fmac_f32_e32 v44, v45, v73
	v_lshlrev_b32_e32 v45, 16, v37
	v_fmac_f32_e32 v45, v46, v74
	v_and_b32_e32 v46, 0xffff0000, v37
	v_fmac_f32_e32 v46, v47, v75
	v_lshlrev_b32_e32 v47, 16, v38
	v_fmac_f32_e32 v47, v48, v68
	v_and_b32_e32 v48, 0xffff0000, v38
	v_fmac_f32_e32 v48, v49, v69
	v_lshlrev_b32_e32 v49, 16, v39
	v_fmac_f32_e32 v49, v50, v70
	v_and_b32_e32 v50, 0xffff0000, v39
	ds_read2st64_b64 v[36:39], v88 offset0:8 offset1:9
	v_fmac_f32_e32 v50, v51, v71
	s_waitcnt lgkmcnt(0)
	v_lshlrev_b32_e32 v51, 16, v36
	v_and_b32_e32 v36, 0xffff0000, v36
	v_lshlrev_b32_e32 v58, 16, v37
	v_and_b32_e32 v37, 0xffff0000, v37
	v_fmac_f32_e32 v51, v20, v80
	v_fmac_f32_e32 v36, v21, v81
	v_fmac_f32_e32 v58, v22, v82
	v_fmac_f32_e32 v37, v23, v83
	ds_read2st64_b64 v[20:23], v88 offset0:10 offset1:11
	v_lshlrev_b32_e32 v59, 16, v38
	v_fmac_f32_e32 v59, v24, v76
	v_and_b32_e32 v24, 0xffff0000, v38
	v_fmac_f32_e32 v24, v25, v77
	v_lshlrev_b32_e32 v25, 16, v39
	v_fmac_f32_e32 v25, v26, v78
	v_and_b32_e32 v26, 0xffff0000, v39
	v_fmac_f32_e32 v26, v27, v79
	s_waitcnt lgkmcnt(0)
	v_lshlrev_b32_e32 v27, 16, v20
	v_fmac_f32_e32 v27, v28, v72
	v_and_b32_e32 v28, 0xffff0000, v20
	v_fmac_f32_e32 v28, v29, v73
	v_lshlrev_b32_e32 v29, 16, v21
	v_fmac_f32_e32 v29, v30, v74
	v_and_b32_e32 v30, 0xffff0000, v21
	v_fmac_f32_e32 v30, v31, v75
	v_lshlrev_b32_e32 v31, 16, v22
	v_fmac_f32_e32 v31, v32, v68
	v_and_b32_e32 v32, 0xffff0000, v22
	v_fmac_f32_e32 v32, v33, v69
	v_lshlrev_b32_e32 v33, 16, v23
	v_fmac_f32_e32 v33, v34, v70
	v_and_b32_e32 v34, 0xffff0000, v23
	ds_read2st64_b64 v[20:23], v88 offset0:12 offset1:13
	v_fmac_f32_e32 v34, v35, v71
	s_waitcnt lgkmcnt(0)
	v_lshlrev_b32_e32 v35, 16, v20
	v_and_b32_e32 v20, 0xffff0000, v20
	v_lshlrev_b32_e32 v38, 16, v21
	v_and_b32_e32 v21, 0xffff0000, v21
	v_fmac_f32_e32 v35, v4, v80
	v_fmac_f32_e32 v20, v5, v81
	v_fmac_f32_e32 v38, v6, v82
	v_fmac_f32_e32 v21, v7, v83
	ds_read2st64_b64 v[4:7], v88 offset0:14 offset1:15
	v_lshlrev_b32_e32 v39, 16, v22
	v_fmac_f32_e32 v39, v8, v76
	v_and_b32_e32 v8, 0xffff0000, v22
	v_fmac_f32_e32 v8, v9, v77
	v_lshlrev_b32_e32 v9, 16, v23
	v_fmac_f32_e32 v9, v10, v78
	v_and_b32_e32 v10, 0xffff0000, v23
	v_fmac_f32_e32 v10, v11, v79
	s_waitcnt lgkmcnt(0)
	v_lshlrev_b32_e32 v11, 16, v4
	v_fmac_f32_e32 v11, v12, v72
	v_and_b32_e32 v4, 0xffff0000, v4
	v_lshlrev_b32_e32 v12, 16, v5
	v_and_b32_e32 v5, 0xffff0000, v5
	v_fmac_f32_e32 v4, v13, v73
	v_fmac_f32_e32 v12, v14, v74
	v_fmac_f32_e32 v5, v15, v75
	v_lshlrev_b32_e32 v13, 16, v6
	v_and_b32_e32 v6, 0xffff0000, v6
	v_lshlrev_b32_e32 v14, 16, v7
	v_and_b32_e32 v7, 0xffff0000, v7
	v_mov_b32_e32 v15, v1
	v_fmac_f32_e32 v13, v16, v68
	v_fmac_f32_e32 v6, v17, v69
	v_fmac_f32_e32 v7, v19, v71
	s_waitcnt vmcnt(0)
	s_barrier
; __device__ __forceinline__ float bf2f(unsigned short u) { return __uint_as_float(((unsigned)u) << 16); }
; __device__ __forceinline__ float silu_f(float z) { return z / (1.f + __expf(-z)); }
; __device__ __forceinline__ int crow(int r, int hi) { return (r & 3) + 8 * (r >> 2) + 4 * hi; }
; __device__ __forceinline__ const bf16* p32(const bf16* base, unsigned elem_off) { return (const bf16*)((const char*)base + (size_t)(elem_off * 2u)); }
; __device__ void nsa_item(const Params& p, int qb, int g, char* smem) {
;     ...
;     for (int r = 0; r < 16; ++r) { const int row = crow(r, L.hi);
; #pragma unroll
;       for (int d0 = 0; d0 < 4; ++d0) wl[row * 128 + 32 * d0 + L.r32] = o[d0][r]; }
;     asm volatile("s_waitcnt lgkmcnt(0)" ::: "memory");
; #pragma unroll
;     for (int i = 0; i < 8; ++i) {
;       const int c = i * 64 + L.lane, row = c >> 4, col8 = (c & 15) * 8;
;       const int t = q0 + L.wid * 8 + (row >> 2), hc = (g * 4 + (row & 3)) * 128 + col8;
;       const f32x4 a0 = *reinterpret_cast<const f32x4*>(wl + row * 128 + col8), a1 = *reinterpret_cast<const f32x4*>(wl + row * 128 + col8 + 4);
;       const bf16x8 zv = ld8(p32(p.P, (unsigned)(t * LDP + C_ZN + hc)));
;       float f[8];
; #pragma unroll
;       for (int j = 0; j < 4; ++j) { f[j] = a0[j] * silu_f(bf2f((unsigned short)zv[j])); f[4 + j] = a1[j] * silu_f(bf2f((unsigned short)zv[4 + j])); }
	v_fmac_f32_e32 v14, v18, v70
	v_ashrrev_i32_e32 v16, 6, v15
	v_and_b32_e32 v17, 31, v15
	v_lshlrev_b32_e32 v19, 6, v15
	v_lshlrev_b32_e32 v18, 14, v16
	v_lshlrev_b32_e32 v17, 2, v17
	v_and_b32_e32 v19, 0x800, v19
	v_or3_b32 v17, v18, v17, v19
	v_add_u32_e32 v19, 0x400, v17
	ds_write2_b32 v17, v86, v67 offset1:32
	ds_write2_b32 v17, v51, v35 offset0:64 offset1:96
	ds_write2_b32 v17, v87, v56 offset0:128 offset1:160
	ds_write2_b32 v17, v36, v20 offset0:192 offset1:224
	ds_write2_b32 v19, v84, v89 offset1:32
	ds_write2_b32 v19, v58, v38 offset0:64 offset1:96
	ds_write2_b32 v19, v85, v57 offset0:128 offset1:160
	ds_write2_b32 v19, v37, v21 offset0:192 offset1:224
	v_add_u32_e32 v19, 0x1000, v17
	ds_write2_b32 v19, v53, v90 offset1:32
	ds_write2_b32 v19, v59, v39 offset0:64 offset1:96
	ds_write2_b32 v19, v54, v40 offset0:128 offset1:160
	ds_write2_b32 v19, v24, v8 offset0:192 offset1:224
	v_add_u32_e32 v8, 0x1400, v17
	ds_write2_b32 v8, v2, v41 offset1:32
	ds_write2_b32 v8, v25, v9 offset0:64 offset1:96
	ds_write2_b32 v8, v52, v42 offset0:128 offset1:160
	ds_write2_b32 v8, v26, v10 offset0:192 offset1:224
	v_add_u32_e32 v2, 0x2000, v17
	ds_write2_b32 v2, v55, v43 offset1:32
	ds_write2_b32 v2, v27, v11 offset0:64 offset1:96
	ds_write2_b32 v2, v60, v44 offset0:128 offset1:160
	ds_write2_b32 v2, v28, v4 offset0:192 offset1:224
	v_add_u32_e32 v2, 0x2400, v17
	ds_write2_b32 v2, v61, v45 offset1:32
	ds_write2_b32 v2, v29, v12 offset0:64 offset1:96
	ds_write2_b32 v2, v62, v46 offset0:128 offset1:160
	ds_write2_b32 v2, v30, v5 offset0:192 offset1:224
	v_add_u32_e32 v2, 0x3000, v17
	ds_write2_b32 v2, v63, v47 offset1:32
	ds_write2_b32 v2, v31, v13 offset0:64 offset1:96
	ds_write2_b32 v2, v64, v48 offset0:128 offset1:160
	ds_write2_b32 v2, v32, v6 offset0:192 offset1:224
	v_add_u32_e32 v2, 0x3400, v17
	ds_write2_b32 v2, v65, v49 offset1:32
	ds_write2_b32 v2, v33, v14 offset0:64 offset1:96
	ds_write2_b32 v2, v66, v50 offset0:128 offset1:160
	ds_write2_b32 v2, v34, v7 offset0:192 offset1:224
	v_lshlrev_b32_e32 v2, 3, v15
	v_lshl_add_u32 v17, v16, 3, s5
	v_bitop3_b32 v2, v2, s0, v193 bitop3:0xe0
	v_lshl_or_b32 v20, s96, 9, v2
	v_mul_lo_u32 v8, v17, s25
	v_add_lshl_u32 v16, v20, v8, 1
	s_waitcnt lgkmcnt(0)
	v_lshl_or_b32 v2, v2, 2, v18
	v_add_u32_e32 v8, 0x2800, v16
	ds_read_b128 v[12:15], v2
	ds_read_b128 v[4:7], v2 offset:16
	v_add_u32_e32 v19, 0x8a00, v16
	global_load_dword v21, v19, s[46:47]
	v_add_u32_e32 v18, 0xec00, v16
	global_load_dword v21, v18, s[46:47]
	v_add_u32_e32 v19, 0x14e00, v16
	global_load_dword v21, v19, s[46:47]
	v_add_u32_e32 v18, 0x1b000, v16
	global_load_dword v21, v18, s[46:47]
	v_add_u32_e32 v19, 0x21200, v16
	global_load_dword v21, v19, s[46:47]
	v_add_u32_e32 v18, 0x27400, v16
	global_load_dword v21, v18, s[46:47]
	v_add_u32_e32 v19, 0x2d600, v16
	global_load_dword v21, v19, s[46:47]
	global_load_dwordx4 v[8:11], v8, s[46:47]
	s_waitcnt vmcnt(0)
	v_and_b32_e32 v21, 0xffff0000, v8
	v_lshlrev_b32_e32 v8, 16, v8
	v_mul_f32_e32 v18, 0xbfb8aa3b, v8
	v_mul_f32_e32 v19, 0xbfb8aa3b, v21
	v_exp_f32_e32 v18, v18
	v_exp_f32_e32 v19, v19
	s_nop 0
	v_pk_add_f32 v[18:19], v[18:19], 1.0 op_sel_hi:[1,0]
	s_nop 0
	v_div_scale_f32 v22, s[0:1], v19, v19, v21
	v_rcp_f32_e32 v23, v22
	s_nop 0
	v_fma_f32 v24, -v22, v23, 1.0
	v_fmac_f32_e32 v23, v24, v23
	v_div_scale_f32 v24, vcc, v21, v19, v21
	v_mul_f32_e32 v25, v24, v23
	v_fma_f32 v26, -v22, v25, v24
	v_fmac_f32_e32 v25, v26, v23
	v_fma_f32 v22, -v22, v25, v24
	v_div_fmas_f32 v22, v22, v23, v25
	v_div_fixup_f32 v19, v22, v19, v21
	v_div_scale_f32 v21, s[0:1], v18, v18, v8
	v_rcp_f32_e32 v22, v21
	s_nop 0
	v_fma_f32 v23, -v21, v22, 1.0
	v_fmac_f32_e32 v22, v23, v22
	v_div_scale_f32 v23, vcc, v8, v18, v8
	v_mul_f32_e32 v24, v23, v22
	v_fma_f32 v25, -v21, v24, v23
	v_fmac_f32_e32 v24, v25, v22
	v_fma_f32 v21, -v21, v24, v23
	v_div_fmas_f32 v21, v21, v22, v24
	v_div_fixup_f32 v18, v21, v18, v8
	v_and_b32_e32 v8, 0xffff0000, v10
	v_lshlrev_b32_e32 v10, 16, v10
	s_waitcnt lgkmcnt(1)
	v_pk_mul_f32 v[12:13], v[12:13], v[18:19]
	v_mul_f32_e32 v18, 0xbfb8aa3b, v10
	v_mul_f32_e32 v19, 0xbfb8aa3b, v8
	v_exp_f32_e32 v18, v18
	v_exp_f32_e32 v19, v19
	s_nop 0
	v_pk_add_f32 v[18:19], v[18:19], 1.0 op_sel_hi:[1,0]
	s_nop 0
	v_div_scale_f32 v21, s[0:1], v19, v19, v8
	v_rcp_f32_e32 v22, v21
	s_nop 0
	v_fma_f32 v23, -v21, v22, 1.0
	v_fmac_f32_e32 v22, v23, v22
	v_div_scale_f32 v23, vcc, v8, v19, v8
	v_mul_f32_e32 v24, v23, v22
	v_fma_f32 v25, -v21, v24, v23
	v_fmac_f32_e32 v24, v25, v22
	v_fma_f32 v21, -v21, v24, v23
	v_div_fmas_f32 v21, v21, v22, v24
	v_div_fixup_f32 v19, v21, v19, v8
	v_div_scale_f32 v8, s[0:1], v18, v18, v10
	v_rcp_f32_e32 v21, v8
	s_nop 0
	v_fma_f32 v22, -v8, v21, 1.0
	v_fmac_f32_e32 v21, v22, v21
	v_div_scale_f32 v22, vcc, v10, v18, v10
	v_mul_f32_e32 v23, v22, v21
	v_fma_f32 v24, -v8, v23, v22
	v_fmac_f32_e32 v23, v24, v21
	v_fma_f32 v8, -v8, v23, v22
	v_div_fmas_f32 v8, v8, v21, v23
	v_div_fixup_f32 v18, v8, v18, v10
	v_and_b32_e32 v8, 0xffff0000, v9
	v_lshlrev_b32_e32 v9, 16, v9
	s_waitcnt lgkmcnt(0)
; __device__ __forceinline__ float bf2f(unsigned short u) { return __uint_as_float(((unsigned)u) << 16); }
; __device__ __forceinline__ float silu_f(float z) { return z / (1.f + __expf(-z)); }
; __device__ __forceinline__ const bf16* p32(const bf16* base, unsigned elem_off) { return (const bf16*)((const char*)base + (size_t)(elem_off * 2u)); }
; __device__ void nsa_item(const Params& p, int qb, int g, char* smem) {
;     ...
;     for (int i = 0; i < 8; ++i) {
;       const int c = i * 64 + L.lane, row = c >> 4, col8 = (c & 15) * 8;
;       const int t = q0 + L.wid * 8 + (row >> 2), hc = (g * 4 + (row & 3)) * 128 + col8;
;       const f32x4 a0 = *reinterpret_cast<const f32x4*>(wl + row * 128 + col8), a1 = *reinterpret_cast<const f32x4*>(wl + row * 128 + col8 + 4);
;       const bf16x8 zv = ld8(p32(p.P, (unsigned)(t * LDP + C_ZN + hc)));
;       float f[8];
; #pragma unroll
;       for (int j = 0; j < 4; ++j) { f[j] = a0[j] * silu_f(bf2f((unsigned short)zv[j])); f[4 + j] = a1[j] * silu_f(bf2f((unsigned short)zv[4 + j])); }
;       u32x4 w = {cvtpk(f[0], f[1]), cvtpk(f[2], f[3]), cvtpk(f[4], f[5]), cvtpk(f[6], f[7])};
;       *reinterpret_cast<u32x4*>((char*)p.y + (size_t)((unsigned)(t * DM + hc) * 2u)) = w;
	v_pk_mul_f32 v[18:19], v[4:5], v[18:19]
	v_mul_f32_e32 v4, 0xbfb8aa3b, v9
	v_mul_f32_e32 v5, 0xbfb8aa3b, v8
	v_exp_f32_e32 v4, v4
	v_exp_f32_e32 v5, v5
	s_nop 0
	v_pk_add_f32 v[4:5], v[4:5], 1.0 op_sel_hi:[1,0]
	s_nop 0
	v_div_scale_f32 v10, s[0:1], v5, v5, v8
	v_rcp_f32_e32 v21, v10
	s_nop 0
	v_fma_f32 v22, -v10, v21, 1.0
	v_fmac_f32_e32 v21, v22, v21
	v_div_scale_f32 v22, vcc, v8, v5, v8
	v_mul_f32_e32 v23, v22, v21
	v_fma_f32 v24, -v10, v23, v22
	v_fmac_f32_e32 v23, v24, v21
	v_fma_f32 v10, -v10, v23, v22
	v_div_fmas_f32 v10, v10, v21, v23
	v_div_fixup_f32 v5, v10, v5, v8
	v_div_scale_f32 v8, s[0:1], v4, v4, v9
	v_rcp_f32_e32 v10, v8
	s_nop 0
	v_fma_f32 v21, -v8, v10, 1.0
	v_fmac_f32_e32 v10, v21, v10
	v_div_scale_f32 v21, vcc, v9, v4, v9
	v_mul_f32_e32 v22, v21, v10
	v_fma_f32 v23, -v8, v22, v21
	v_fmac_f32_e32 v22, v23, v10
	v_fma_f32 v8, -v8, v22, v21
	v_div_fmas_f32 v8, v8, v10, v22
	v_div_fixup_f32 v4, v8, v4, v9
	v_and_b32_e32 v10, 0xffff0000, v11
	v_lshlrev_b32_e32 v11, 16, v11
	v_pk_mul_f32 v[8:9], v[14:15], v[4:5]
	v_mul_f32_e32 v4, 0xbfb8aa3b, v11
	v_mul_f32_e32 v5, 0xbfb8aa3b, v10
	v_exp_f32_e32 v4, v4
	v_exp_f32_e32 v5, v5
	s_nop 0
	v_pk_add_f32 v[4:5], v[4:5], 1.0 op_sel_hi:[1,0]
	s_nop 0
	v_div_scale_f32 v14, s[0:1], v5, v5, v10
	v_rcp_f32_e32 v15, v14
	s_nop 0
	v_fma_f32 v21, -v14, v15, 1.0
	v_fmac_f32_e32 v15, v21, v15
	v_div_scale_f32 v21, vcc, v10, v5, v10
	v_mul_f32_e32 v22, v21, v15
	v_fma_f32 v23, -v14, v22, v21
	v_fmac_f32_e32 v22, v23, v15
	v_fma_f32 v14, -v14, v22, v21
	v_div_fmas_f32 v14, v14, v15, v22
	v_div_fixup_f32 v5, v14, v5, v10
	v_div_scale_f32 v10, s[0:1], v4, v4, v11
	v_rcp_f32_e32 v14, v10
	s_nop 0
	v_fma_f32 v15, -v10, v14, 1.0
	v_fmac_f32_e32 v14, v15, v14
	v_div_scale_f32 v15, vcc, v11, v4, v11
	v_mul_f32_e32 v21, v15, v14
	v_fma_f32 v22, -v10, v21, v15
	v_fmac_f32_e32 v21, v22, v14
	v_fma_f32 v10, -v10, v21, v15
	v_div_fmas_f32 v10, v10, v14, v21
	v_div_fixup_f32 v4, v10, v4, v11
	v_pk_mul_f32 v[10:11], v[6:7], v[4:5]
	v_cvt_pk_bf16_f32 v5, v8, v9
	v_lshlrev_b32_e32 v8, 13, v17
	v_cvt_pk_bf16_f32 v4, v12, v13
	v_cvt_pk_bf16_f32 v6, v18, v19
	v_cvt_pk_bf16_f32 v7, v10, v11
	v_lshl_add_u32 v17, v20, 1, v8
	global_store_dwordx4 v17, v[4:7], s[48:49]
	v_add_u32_e32 v8, 0x8a00, v16
	ds_read_b128 v[12:15], v2 offset:2048
	ds_read_b128 v[4:7], v2 offset:2064
	global_load_dwordx4 v[8:11], v8, s[46:47]
	s_waitcnt vmcnt(0)
	v_and_b32_e32 v20, 0xffff0000, v8
	v_lshlrev_b32_e32 v8, 16, v8
	v_mul_f32_e32 v18, 0xbfb8aa3b, v8
	v_mul_f32_e32 v19, 0xbfb8aa3b, v20
	v_exp_f32_e32 v18, v18
	v_exp_f32_e32 v19, v19
	s_nop 0
	v_pk_add_f32 v[18:19], v[18:19], 1.0 op_sel_hi:[1,0]
	s_nop 0
	v_div_scale_f32 v21, s[0:1], v19, v19, v20
	v_rcp_f32_e32 v22, v21
	s_nop 0
	v_fma_f32 v23, -v21, v22, 1.0
	v_fmac_f32_e32 v22, v23, v22
	v_div_scale_f32 v23, vcc, v20, v19, v20
	v_mul_f32_e32 v24, v23, v22
	v_fma_f32 v25, -v21, v24, v23
	v_fmac_f32_e32 v24, v25, v22
	v_fma_f32 v21, -v21, v24, v23
	v_div_fmas_f32 v21, v21, v22, v24
	v_div_fixup_f32 v19, v21, v19, v20
	v_div_scale_f32 v20, s[0:1], v18, v18, v8
	v_rcp_f32_e32 v21, v20
	s_nop 0
	v_fma_f32 v22, -v20, v21, 1.0
	v_fmac_f32_e32 v21, v22, v21
	v_div_scale_f32 v22, vcc, v8, v18, v8
	v_mul_f32_e32 v23, v22, v21
	v_fma_f32 v24, -v20, v23, v22
	v_fmac_f32_e32 v23, v24, v21
	v_fma_f32 v20, -v20, v23, v22
	v_div_fmas_f32 v20, v20, v21, v23
	v_div_fixup_f32 v18, v20, v18, v8
	v_and_b32_e32 v8, 0xffff0000, v10
	v_lshlrev_b32_e32 v10, 16, v10
	s_waitcnt lgkmcnt(1)
	v_pk_mul_f32 v[12:13], v[12:13], v[18:19]
	v_mul_f32_e32 v18, 0xbfb8aa3b, v10
	v_mul_f32_e32 v19, 0xbfb8aa3b, v8
	v_exp_f32_e32 v18, v18
	v_exp_f32_e32 v19, v19
	s_nop 0
	v_pk_add_f32 v[18:19], v[18:19], 1.0 op_sel_hi:[1,0]
	s_nop 0
	v_div_scale_f32 v20, s[0:1], v19, v19, v8
	v_rcp_f32_e32 v21, v20
	s_nop 0
	v_fma_f32 v22, -v20, v21, 1.0
	v_fmac_f32_e32 v21, v22, v21
	v_div_scale_f32 v22, vcc, v8, v19, v8
	v_mul_f32_e32 v23, v22, v21
	v_fma_f32 v24, -v20, v23, v22
	v_fmac_f32_e32 v23, v24, v21
	v_fma_f32 v20, -v20, v23, v22
	v_div_fmas_f32 v20, v20, v21, v23
	v_div_fixup_f32 v19, v20, v19, v8
	v_div_scale_f32 v8, s[0:1], v18, v18, v10
	v_rcp_f32_e32 v20, v8
	s_nop 0
	v_fma_f32 v21, -v8, v20, 1.0
	v_fmac_f32_e32 v20, v21, v20
	v_div_scale_f32 v21, vcc, v10, v18, v10
	v_mul_f32_e32 v22, v21, v20
	v_fma_f32 v23, -v8, v22, v21
	v_fmac_f32_e32 v22, v23, v20
	v_fma_f32 v8, -v8, v22, v21
	v_div_fmas_f32 v8, v8, v20, v22
	v_div_fixup_f32 v18, v8, v18, v10
	v_and_b32_e32 v8, 0xffff0000, v9
	v_lshlrev_b32_e32 v9, 16, v9
	s_waitcnt lgkmcnt(0)
; __device__ __forceinline__ float bf2f(unsigned short u) { return __uint_as_float(((unsigned)u) << 16); }
; __device__ __forceinline__ float silu_f(float z) { return z / (1.f + __expf(-z)); }
; __device__ __forceinline__ const bf16* p32(const bf16* base, unsigned elem_off) { return (const bf16*)((const char*)base + (size_t)(elem_off * 2u)); }
; __device__ void nsa_item(const Params& p, int qb, int g, char* smem) {
;     ...
;     for (int i = 0; i < 8; ++i) {
;       const int c = i * 64 + L.lane, row = c >> 4, col8 = (c & 15) * 8;
;       const int t = q0 + L.wid * 8 + (row >> 2), hc = (g * 4 + (row & 3)) * 128 + col8;
;       const f32x4 a0 = *reinterpret_cast<const f32x4*>(wl + row * 128 + col8), a1 = *reinterpret_cast<const f32x4*>(wl + row * 128 + col8 + 4);
;       const bf16x8 zv = ld8(p32(p.P, (unsigned)(t * LDP + C_ZN + hc)));
;       float f[8];
; #pragma unroll
;       for (int j = 0; j < 4; ++j) { f[j] = a0[j] * silu_f(bf2f((unsigned short)zv[j])); f[4 + j] = a1[j] * silu_f(bf2f((unsigned short)zv[4 + j])); }
;       u32x4 w = {cvtpk(f[0], f[1]), cvtpk(f[2], f[3]), cvtpk(f[4], f[5]), cvtpk(f[6], f[7])};
;       *reinterpret_cast<u32x4*>((char*)p.y + (size_t)((unsigned)(t * DM + hc) * 2u)) = w;
	v_pk_mul_f32 v[18:19], v[4:5], v[18:19]
	v_mul_f32_e32 v4, 0xbfb8aa3b, v9
	v_mul_f32_e32 v5, 0xbfb8aa3b, v8
	v_exp_f32_e32 v4, v4
	v_exp_f32_e32 v5, v5
	s_nop 0
	v_pk_add_f32 v[4:5], v[4:5], 1.0 op_sel_hi:[1,0]
	s_nop 0
	v_div_scale_f32 v10, s[0:1], v5, v5, v8
	v_rcp_f32_e32 v20, v10
	s_nop 0
	v_fma_f32 v21, -v10, v20, 1.0
	v_fmac_f32_e32 v20, v21, v20
	v_div_scale_f32 v21, vcc, v8, v5, v8
	v_mul_f32_e32 v22, v21, v20
	v_fma_f32 v23, -v10, v22, v21
	v_fmac_f32_e32 v22, v23, v20
	v_fma_f32 v10, -v10, v22, v21
	v_div_fmas_f32 v10, v10, v20, v22
	v_div_fixup_f32 v5, v10, v5, v8
	v_div_scale_f32 v8, s[0:1], v4, v4, v9
	v_rcp_f32_e32 v10, v8
	s_nop 0
	v_fma_f32 v20, -v8, v10, 1.0
	v_fmac_f32_e32 v10, v20, v10
	v_div_scale_f32 v20, vcc, v9, v4, v9
	v_mul_f32_e32 v21, v20, v10
	v_fma_f32 v22, -v8, v21, v20
	v_fmac_f32_e32 v21, v22, v10
	v_fma_f32 v8, -v8, v21, v20
	v_div_fmas_f32 v8, v8, v10, v21
	v_div_fixup_f32 v4, v8, v4, v9
	v_and_b32_e32 v10, 0xffff0000, v11
	v_lshlrev_b32_e32 v11, 16, v11
	v_pk_mul_f32 v[8:9], v[14:15], v[4:5]
	v_mul_f32_e32 v4, 0xbfb8aa3b, v11
	v_mul_f32_e32 v5, 0xbfb8aa3b, v10
	v_exp_f32_e32 v4, v4
	v_exp_f32_e32 v5, v5
	s_nop 0
	v_pk_add_f32 v[4:5], v[4:5], 1.0 op_sel_hi:[1,0]
	s_nop 0
	v_div_scale_f32 v14, s[0:1], v5, v5, v10
	v_rcp_f32_e32 v15, v14
	s_nop 0
	v_fma_f32 v20, -v14, v15, 1.0
	v_fmac_f32_e32 v15, v20, v15
	v_div_scale_f32 v20, vcc, v10, v5, v10
	v_mul_f32_e32 v21, v20, v15
	v_fma_f32 v22, -v14, v21, v20
	v_fmac_f32_e32 v21, v22, v15
	v_fma_f32 v14, -v14, v21, v20
	v_div_fmas_f32 v14, v14, v15, v21
	v_div_fixup_f32 v5, v14, v5, v10
	v_div_scale_f32 v10, s[0:1], v4, v4, v11
	v_rcp_f32_e32 v14, v10
	s_nop 0
	v_fma_f32 v15, -v10, v14, 1.0
	v_fmac_f32_e32 v14, v15, v14
	v_div_scale_f32 v15, vcc, v11, v4, v11
	v_mul_f32_e32 v20, v15, v14
	v_fma_f32 v21, -v10, v20, v15
	v_fmac_f32_e32 v20, v21, v14
	v_fma_f32 v10, -v10, v20, v15
	v_div_fmas_f32 v10, v10, v14, v20
	v_div_fixup_f32 v4, v10, v4, v11
	v_pk_mul_f32 v[10:11], v[6:7], v[4:5]
	v_cvt_pk_bf16_f32 v4, v12, v13
	v_cvt_pk_bf16_f32 v5, v8, v9
	v_cvt_pk_bf16_f32 v6, v18, v19
	v_cvt_pk_bf16_f32 v7, v10, v11
	v_add_u32_e32 v8, 0x2000, v17
	global_store_dwordx4 v8, v[4:7], s[48:49]
	v_add_u32_e32 v8, 0xec00, v16
	ds_read_b128 v[12:15], v2 offset:4096
	ds_read_b128 v[4:7], v2 offset:4112
	global_load_dwordx4 v[8:11], v8, s[46:47]
	s_waitcnt vmcnt(0)
	v_and_b32_e32 v20, 0xffff0000, v8
	v_lshlrev_b32_e32 v8, 16, v8
	v_mul_f32_e32 v18, 0xbfb8aa3b, v8
	v_mul_f32_e32 v19, 0xbfb8aa3b, v20
	v_exp_f32_e32 v18, v18
	v_exp_f32_e32 v19, v19
	s_nop 0
	v_pk_add_f32 v[18:19], v[18:19], 1.0 op_sel_hi:[1,0]
	s_nop 0
	v_div_scale_f32 v21, s[0:1], v19, v19, v20
	v_rcp_f32_e32 v22, v21
	s_nop 0
	v_fma_f32 v23, -v21, v22, 1.0
	v_fmac_f32_e32 v22, v23, v22
	v_div_scale_f32 v23, vcc, v20, v19, v20
	v_mul_f32_e32 v24, v23, v22
	v_fma_f32 v25, -v21, v24, v23
	v_fmac_f32_e32 v24, v25, v22
	v_fma_f32 v21, -v21, v24, v23
	v_div_fmas_f32 v21, v21, v22, v24
	v_div_fixup_f32 v19, v21, v19, v20
	v_div_scale_f32 v20, s[0:1], v18, v18, v8
	v_rcp_f32_e32 v21, v20
	s_nop 0
	v_fma_f32 v22, -v20, v21, 1.0
	v_fmac_f32_e32 v21, v22, v21
	v_div_scale_f32 v22, vcc, v8, v18, v8
	v_mul_f32_e32 v23, v22, v21
	v_fma_f32 v24, -v20, v23, v22
	v_fmac_f32_e32 v23, v24, v21
	v_fma_f32 v20, -v20, v23, v22
	v_div_fmas_f32 v20, v20, v21, v23
	v_div_fixup_f32 v18, v20, v18, v8
	v_and_b32_e32 v8, 0xffff0000, v10
	v_lshlrev_b32_e32 v10, 16, v10
	s_waitcnt lgkmcnt(1)
	v_pk_mul_f32 v[12:13], v[12:13], v[18:19]
	v_mul_f32_e32 v18, 0xbfb8aa3b, v10
	v_mul_f32_e32 v19, 0xbfb8aa3b, v8
	v_exp_f32_e32 v18, v18
	v_exp_f32_e32 v19, v19
	s_nop 0
	v_pk_add_f32 v[18:19], v[18:19], 1.0 op_sel_hi:[1,0]
	s_nop 0
	v_div_scale_f32 v20, s[0:1], v19, v19, v8
	v_rcp_f32_e32 v21, v20
	s_nop 0
	v_fma_f32 v22, -v20, v21, 1.0
	v_fmac_f32_e32 v21, v22, v21
	v_div_scale_f32 v22, vcc, v8, v19, v8
	v_mul_f32_e32 v23, v22, v21
	v_fma_f32 v24, -v20, v23, v22
	v_fmac_f32_e32 v23, v24, v21
	v_fma_f32 v20, -v20, v23, v22
	v_div_fmas_f32 v20, v20, v21, v23
	v_div_fixup_f32 v19, v20, v19, v8
	v_div_scale_f32 v8, s[0:1], v18, v18, v10
	v_rcp_f32_e32 v20, v8
	s_nop 0
	v_fma_f32 v21, -v8, v20, 1.0
	v_fmac_f32_e32 v20, v21, v20
	v_div_scale_f32 v21, vcc, v10, v18, v10
	v_mul_f32_e32 v22, v21, v20
	v_fma_f32 v23, -v8, v22, v21
	v_fmac_f32_e32 v22, v23, v20
	v_fma_f32 v8, -v8, v22, v21
	v_div_fmas_f32 v8, v8, v20, v22
	v_div_fixup_f32 v18, v8, v18, v10
	v_and_b32_e32 v8, 0xffff0000, v9
	v_lshlrev_b32_e32 v9, 16, v9
	s_waitcnt lgkmcnt(0)
; __device__ __forceinline__ float bf2f(unsigned short u) { return __uint_as_float(((unsigned)u) << 16); }
; __device__ __forceinline__ float silu_f(float z) { return z / (1.f + __expf(-z)); }
; __device__ __forceinline__ const bf16* p32(const bf16* base, unsigned elem_off) { return (const bf16*)((const char*)base + (size_t)(elem_off * 2u)); }
; __device__ void nsa_item(const Params& p, int qb, int g, char* smem) {
;     ...
;     for (int i = 0; i < 8; ++i) {
;       const int c = i * 64 + L.lane, row = c >> 4, col8 = (c & 15) * 8;
;       const int t = q0 + L.wid * 8 + (row >> 2), hc = (g * 4 + (row & 3)) * 128 + col8;
;       const f32x4 a0 = *reinterpret_cast<const f32x4*>(wl + row * 128 + col8), a1 = *reinterpret_cast<const f32x4*>(wl + row * 128 + col8 + 4);
;       const bf16x8 zv = ld8(p32(p.P, (unsigned)(t * LDP + C_ZN + hc)));
;       float f[8];
; #pragma unroll
;       for (int j = 0; j < 4; ++j) { f[j] = a0[j] * silu_f(bf2f((unsigned short)zv[j])); f[4 + j] = a1[j] * silu_f(bf2f((unsigned short)zv[4 + j])); }
;       u32x4 w = {cvtpk(f[0], f[1]), cvtpk(f[2], f[3]), cvtpk(f[4], f[5]), cvtpk(f[6], f[7])};
;       *reinterpret_cast<u32x4*>((char*)p.y + (size_t)((unsigned)(t * DM + hc) * 2u)) = w;
	v_pk_mul_f32 v[18:19], v[4:5], v[18:19]
	v_mul_f32_e32 v4, 0xbfb8aa3b, v9
	v_mul_f32_e32 v5, 0xbfb8aa3b, v8
	v_exp_f32_e32 v4, v4
	v_exp_f32_e32 v5, v5
	s_nop 0
	v_pk_add_f32 v[4:5], v[4:5], 1.0 op_sel_hi:[1,0]
	s_nop 0
	v_div_scale_f32 v10, s[0:1], v5, v5, v8
	v_rcp_f32_e32 v20, v10
	s_nop 0
	v_fma_f32 v21, -v10, v20, 1.0
	v_fmac_f32_e32 v20, v21, v20
	v_div_scale_f32 v21, vcc, v8, v5, v8
	v_mul_f32_e32 v22, v21, v20
	v_fma_f32 v23, -v10, v22, v21
	v_fmac_f32_e32 v22, v23, v20
	v_fma_f32 v10, -v10, v22, v21
	v_div_fmas_f32 v10, v10, v20, v22
	v_div_fixup_f32 v5, v10, v5, v8
	v_div_scale_f32 v8, s[0:1], v4, v4, v9
	v_rcp_f32_e32 v10, v8
	s_nop 0
	v_fma_f32 v20, -v8, v10, 1.0
	v_fmac_f32_e32 v10, v20, v10
	v_div_scale_f32 v20, vcc, v9, v4, v9
	v_mul_f32_e32 v21, v20, v10
	v_fma_f32 v22, -v8, v21, v20
	v_fmac_f32_e32 v21, v22, v10
	v_fma_f32 v8, -v8, v21, v20
	v_div_fmas_f32 v8, v8, v10, v21
	v_div_fixup_f32 v4, v8, v4, v9
	v_and_b32_e32 v10, 0xffff0000, v11
	v_lshlrev_b32_e32 v11, 16, v11
	v_pk_mul_f32 v[8:9], v[14:15], v[4:5]
	v_mul_f32_e32 v4, 0xbfb8aa3b, v11
	v_mul_f32_e32 v5, 0xbfb8aa3b, v10
	v_exp_f32_e32 v4, v4
	v_exp_f32_e32 v5, v5
	s_nop 0
	v_pk_add_f32 v[4:5], v[4:5], 1.0 op_sel_hi:[1,0]
	s_nop 0
	v_div_scale_f32 v14, s[0:1], v5, v5, v10
	v_rcp_f32_e32 v15, v14
	s_nop 0
	v_fma_f32 v20, -v14, v15, 1.0
	v_fmac_f32_e32 v15, v20, v15
	v_div_scale_f32 v20, vcc, v10, v5, v10
	v_mul_f32_e32 v21, v20, v15
	v_fma_f32 v22, -v14, v21, v20
	v_fmac_f32_e32 v21, v22, v15
	v_fma_f32 v14, -v14, v21, v20
	v_div_fmas_f32 v14, v14, v15, v21
	v_div_fixup_f32 v5, v14, v5, v10
	v_div_scale_f32 v10, s[0:1], v4, v4, v11
	v_rcp_f32_e32 v14, v10
	s_nop 0
	v_fma_f32 v15, -v10, v14, 1.0
	v_fmac_f32_e32 v14, v15, v14
	v_div_scale_f32 v15, vcc, v11, v4, v11
	v_mul_f32_e32 v20, v15, v14
	v_fma_f32 v21, -v10, v20, v15
	v_fmac_f32_e32 v20, v21, v14
	v_fma_f32 v10, -v10, v20, v15
	v_div_fmas_f32 v10, v10, v14, v20
	v_div_fixup_f32 v4, v10, v4, v11
	v_pk_mul_f32 v[10:11], v[6:7], v[4:5]
	v_cvt_pk_bf16_f32 v4, v12, v13
	v_cvt_pk_bf16_f32 v5, v8, v9
	v_cvt_pk_bf16_f32 v6, v18, v19
	v_cvt_pk_bf16_f32 v7, v10, v11
	v_add_u32_e32 v8, 0x4000, v17
	global_store_dwordx4 v8, v[4:7], s[48:49]
	v_add_u32_e32 v8, 0x14e00, v16
	ds_read_b128 v[12:15], v2 offset:6144
	ds_read_b128 v[4:7], v2 offset:6160
	global_load_dwordx4 v[8:11], v8, s[46:47]
	s_waitcnt vmcnt(0)
	v_and_b32_e32 v20, 0xffff0000, v8
	v_lshlrev_b32_e32 v8, 16, v8
	v_mul_f32_e32 v18, 0xbfb8aa3b, v8
	v_mul_f32_e32 v19, 0xbfb8aa3b, v20
	v_exp_f32_e32 v18, v18
	v_exp_f32_e32 v19, v19
	s_nop 0
	v_pk_add_f32 v[18:19], v[18:19], 1.0 op_sel_hi:[1,0]
	s_nop 0
	v_div_scale_f32 v21, s[0:1], v19, v19, v20
	v_rcp_f32_e32 v22, v21
	s_nop 0
	v_fma_f32 v23, -v21, v22, 1.0
	v_fmac_f32_e32 v22, v23, v22
	v_div_scale_f32 v23, vcc, v20, v19, v20
	v_mul_f32_e32 v24, v23, v22
	v_fma_f32 v25, -v21, v24, v23
	v_fmac_f32_e32 v24, v25, v22
	v_fma_f32 v21, -v21, v24, v23
	v_div_fmas_f32 v21, v21, v22, v24
	v_div_fixup_f32 v19, v21, v19, v20
	v_div_scale_f32 v20, s[0:1], v18, v18, v8
	v_rcp_f32_e32 v21, v20
	s_nop 0
	v_fma_f32 v22, -v20, v21, 1.0
	v_fmac_f32_e32 v21, v22, v21
	v_div_scale_f32 v22, vcc, v8, v18, v8
	v_mul_f32_e32 v23, v22, v21
	v_fma_f32 v24, -v20, v23, v22
	v_fmac_f32_e32 v23, v24, v21
	v_fma_f32 v20, -v20, v23, v22
	v_div_fmas_f32 v20, v20, v21, v23
	v_div_fixup_f32 v18, v20, v18, v8
	v_and_b32_e32 v8, 0xffff0000, v10
	v_lshlrev_b32_e32 v10, 16, v10
	s_waitcnt lgkmcnt(1)
	v_pk_mul_f32 v[12:13], v[12:13], v[18:19]
	v_mul_f32_e32 v18, 0xbfb8aa3b, v10
	v_mul_f32_e32 v19, 0xbfb8aa3b, v8
	v_exp_f32_e32 v18, v18
	v_exp_f32_e32 v19, v19
	s_nop 0
	v_pk_add_f32 v[18:19], v[18:19], 1.0 op_sel_hi:[1,0]
	s_nop 0
	v_div_scale_f32 v20, s[0:1], v19, v19, v8
	v_rcp_f32_e32 v21, v20
	s_nop 0
	v_fma_f32 v22, -v20, v21, 1.0
	v_fmac_f32_e32 v21, v22, v21
	v_div_scale_f32 v22, vcc, v8, v19, v8
	v_mul_f32_e32 v23, v22, v21
	v_fma_f32 v24, -v20, v23, v22
	v_fmac_f32_e32 v23, v24, v21
	v_fma_f32 v20, -v20, v23, v22
	v_div_fmas_f32 v20, v20, v21, v23
	v_div_fixup_f32 v19, v20, v19, v8
	v_div_scale_f32 v8, s[0:1], v18, v18, v10
	v_rcp_f32_e32 v20, v8
	s_nop 0
	v_fma_f32 v21, -v8, v20, 1.0
	v_fmac_f32_e32 v20, v21, v20
	v_div_scale_f32 v21, vcc, v10, v18, v10
	v_mul_f32_e32 v22, v21, v20
	v_fma_f32 v23, -v8, v22, v21
	v_fmac_f32_e32 v22, v23, v20
	v_fma_f32 v8, -v8, v22, v21
	v_div_fmas_f32 v8, v8, v20, v22
	v_div_fixup_f32 v18, v8, v18, v10
	v_and_b32_e32 v8, 0xffff0000, v9
	v_lshlrev_b32_e32 v9, 16, v9
	s_waitcnt lgkmcnt(0)
; __device__ __forceinline__ float bf2f(unsigned short u) { return __uint_as_float(((unsigned)u) << 16); }
; __device__ __forceinline__ float silu_f(float z) { return z / (1.f + __expf(-z)); }
; __device__ __forceinline__ const bf16* p32(const bf16* base, unsigned elem_off) { return (const bf16*)((const char*)base + (size_t)(elem_off * 2u)); }
; __device__ void nsa_item(const Params& p, int qb, int g, char* smem) {
;     ...
;     for (int i = 0; i < 8; ++i) {
;       const int c = i * 64 + L.lane, row = c >> 4, col8 = (c & 15) * 8;
;       const int t = q0 + L.wid * 8 + (row >> 2), hc = (g * 4 + (row & 3)) * 128 + col8;
;       const f32x4 a0 = *reinterpret_cast<const f32x4*>(wl + row * 128 + col8), a1 = *reinterpret_cast<const f32x4*>(wl + row * 128 + col8 + 4);
;       const bf16x8 zv = ld8(p32(p.P, (unsigned)(t * LDP + C_ZN + hc)));
;       float f[8];
; #pragma unroll
;       for (int j = 0; j < 4; ++j) { f[j] = a0[j] * silu_f(bf2f((unsigned short)zv[j])); f[4 + j] = a1[j] * silu_f(bf2f((unsigned short)zv[4 + j])); }
;       u32x4 w = {cvtpk(f[0], f[1]), cvtpk(f[2], f[3]), cvtpk(f[4], f[5]), cvtpk(f[6], f[7])};
;       *reinterpret_cast<u32x4*>((char*)p.y + (size_t)((unsigned)(t * DM + hc) * 2u)) = w;
	v_pk_mul_f32 v[18:19], v[4:5], v[18:19]
	v_mul_f32_e32 v4, 0xbfb8aa3b, v9
	v_mul_f32_e32 v5, 0xbfb8aa3b, v8
	v_exp_f32_e32 v4, v4
	v_exp_f32_e32 v5, v5
	s_nop 0
	v_pk_add_f32 v[4:5], v[4:5], 1.0 op_sel_hi:[1,0]
	s_nop 0
	v_div_scale_f32 v10, s[0:1], v5, v5, v8
	v_rcp_f32_e32 v20, v10
	s_nop 0
	v_fma_f32 v21, -v10, v20, 1.0
	v_fmac_f32_e32 v20, v21, v20
	v_div_scale_f32 v21, vcc, v8, v5, v8
	v_mul_f32_e32 v22, v21, v20
	v_fma_f32 v23, -v10, v22, v21
	v_fmac_f32_e32 v22, v23, v20
	v_fma_f32 v10, -v10, v22, v21
	v_div_fmas_f32 v10, v10, v20, v22
	v_div_fixup_f32 v5, v10, v5, v8
	v_div_scale_f32 v8, s[0:1], v4, v4, v9
	v_rcp_f32_e32 v10, v8
	s_nop 0
	v_fma_f32 v20, -v8, v10, 1.0
	v_fmac_f32_e32 v10, v20, v10
	v_div_scale_f32 v20, vcc, v9, v4, v9
	v_mul_f32_e32 v21, v20, v10
	v_fma_f32 v22, -v8, v21, v20
	v_fmac_f32_e32 v21, v22, v10
	v_fma_f32 v8, -v8, v21, v20
	v_div_fmas_f32 v8, v8, v10, v21
	v_div_fixup_f32 v4, v8, v4, v9
	v_and_b32_e32 v10, 0xffff0000, v11
	v_lshlrev_b32_e32 v11, 16, v11
	v_pk_mul_f32 v[8:9], v[14:15], v[4:5]
	v_mul_f32_e32 v4, 0xbfb8aa3b, v11
	v_mul_f32_e32 v5, 0xbfb8aa3b, v10
	v_exp_f32_e32 v4, v4
	v_exp_f32_e32 v5, v5
	s_nop 0
	v_pk_add_f32 v[4:5], v[4:5], 1.0 op_sel_hi:[1,0]
	s_nop 0
	v_div_scale_f32 v14, s[0:1], v5, v5, v10
	v_rcp_f32_e32 v15, v14
	s_nop 0
	v_fma_f32 v20, -v14, v15, 1.0
	v_fmac_f32_e32 v15, v20, v15
	v_div_scale_f32 v20, vcc, v10, v5, v10
	v_mul_f32_e32 v21, v20, v15
	v_fma_f32 v22, -v14, v21, v20
	v_fmac_f32_e32 v21, v22, v15
	v_fma_f32 v14, -v14, v21, v20
	v_div_fmas_f32 v14, v14, v15, v21
	v_div_fixup_f32 v5, v14, v5, v10
	v_div_scale_f32 v10, s[0:1], v4, v4, v11
	v_rcp_f32_e32 v14, v10
	s_nop 0
	v_fma_f32 v15, -v10, v14, 1.0
	v_fmac_f32_e32 v14, v15, v14
	v_div_scale_f32 v15, vcc, v11, v4, v11
	v_mul_f32_e32 v20, v15, v14
	v_fma_f32 v21, -v10, v20, v15
	v_fmac_f32_e32 v20, v21, v14
	v_fma_f32 v10, -v10, v20, v15
	v_div_fmas_f32 v10, v10, v14, v20
	v_div_fixup_f32 v4, v10, v4, v11
	v_pk_mul_f32 v[10:11], v[6:7], v[4:5]
	v_cvt_pk_bf16_f32 v4, v12, v13
	v_cvt_pk_bf16_f32 v5, v8, v9
	v_cvt_pk_bf16_f32 v6, v18, v19
	v_cvt_pk_bf16_f32 v7, v10, v11
	v_add_u32_e32 v8, 0x6000, v17
	global_store_dwordx4 v8, v[4:7], s[48:49]
	v_add_u32_e32 v8, 0x1b000, v16
	ds_read_b128 v[12:15], v2 offset:8192
	ds_read_b128 v[4:7], v2 offset:8208
	global_load_dwordx4 v[8:11], v8, s[46:47]
	s_waitcnt vmcnt(0)
	v_and_b32_e32 v20, 0xffff0000, v8
	v_lshlrev_b32_e32 v8, 16, v8
	v_mul_f32_e32 v18, 0xbfb8aa3b, v8
	v_mul_f32_e32 v19, 0xbfb8aa3b, v20
	v_exp_f32_e32 v18, v18
	v_exp_f32_e32 v19, v19
	s_nop 0
	v_pk_add_f32 v[18:19], v[18:19], 1.0 op_sel_hi:[1,0]
	s_nop 0
	v_div_scale_f32 v21, s[0:1], v19, v19, v20
	v_rcp_f32_e32 v22, v21
	s_nop 0
	v_fma_f32 v23, -v21, v22, 1.0
	v_fmac_f32_e32 v22, v23, v22
	v_div_scale_f32 v23, vcc, v20, v19, v20
	v_mul_f32_e32 v24, v23, v22
	v_fma_f32 v25, -v21, v24, v23
	v_fmac_f32_e32 v24, v25, v22
	v_fma_f32 v21, -v21, v24, v23
	v_div_fmas_f32 v21, v21, v22, v24
	v_div_fixup_f32 v19, v21, v19, v20
	v_div_scale_f32 v20, s[0:1], v18, v18, v8
	v_rcp_f32_e32 v21, v20
	s_nop 0
	v_fma_f32 v22, -v20, v21, 1.0
	v_fmac_f32_e32 v21, v22, v21
	v_div_scale_f32 v22, vcc, v8, v18, v8
	v_mul_f32_e32 v23, v22, v21
	v_fma_f32 v24, -v20, v23, v22
	v_fmac_f32_e32 v23, v24, v21
	v_fma_f32 v20, -v20, v23, v22
	v_div_fmas_f32 v20, v20, v21, v23
	v_div_fixup_f32 v18, v20, v18, v8
	v_and_b32_e32 v8, 0xffff0000, v10
	v_lshlrev_b32_e32 v10, 16, v10
	s_waitcnt lgkmcnt(1)
	v_pk_mul_f32 v[12:13], v[12:13], v[18:19]
	v_mul_f32_e32 v18, 0xbfb8aa3b, v10
	v_mul_f32_e32 v19, 0xbfb8aa3b, v8
	v_exp_f32_e32 v18, v18
	v_exp_f32_e32 v19, v19
	s_nop 0
	v_pk_add_f32 v[18:19], v[18:19], 1.0 op_sel_hi:[1,0]
	s_nop 0
	v_div_scale_f32 v20, s[0:1], v19, v19, v8
	v_rcp_f32_e32 v21, v20
	s_nop 0
	v_fma_f32 v22, -v20, v21, 1.0
	v_fmac_f32_e32 v21, v22, v21
	v_div_scale_f32 v22, vcc, v8, v19, v8
	v_mul_f32_e32 v23, v22, v21
	v_fma_f32 v24, -v20, v23, v22
	v_fmac_f32_e32 v23, v24, v21
	v_fma_f32 v20, -v20, v23, v22
	v_div_fmas_f32 v20, v20, v21, v23
	v_div_fixup_f32 v19, v20, v19, v8
	v_div_scale_f32 v8, s[0:1], v18, v18, v10
	v_rcp_f32_e32 v20, v8
	s_nop 0
	v_fma_f32 v21, -v8, v20, 1.0
	v_fmac_f32_e32 v20, v21, v20
	v_div_scale_f32 v21, vcc, v10, v18, v10
	v_mul_f32_e32 v22, v21, v20
	v_fma_f32 v23, -v8, v22, v21
	v_fmac_f32_e32 v22, v23, v20
	v_fma_f32 v8, -v8, v22, v21
	v_div_fmas_f32 v8, v8, v20, v22
	v_div_fixup_f32 v18, v8, v18, v10
	v_and_b32_e32 v8, 0xffff0000, v9
	v_lshlrev_b32_e32 v9, 16, v9
	s_waitcnt lgkmcnt(0)
; __device__ __forceinline__ float bf2f(unsigned short u) { return __uint_as_float(((unsigned)u) << 16); }
; __device__ __forceinline__ float silu_f(float z) { return z / (1.f + __expf(-z)); }
; __device__ __forceinline__ const bf16* p32(const bf16* base, unsigned elem_off) { return (const bf16*)((const char*)base + (size_t)(elem_off * 2u)); }
; __device__ void nsa_item(const Params& p, int qb, int g, char* smem) {
;     ...
;     for (int i = 0; i < 8; ++i) {
;       const int c = i * 64 + L.lane, row = c >> 4, col8 = (c & 15) * 8;
;       const int t = q0 + L.wid * 8 + (row >> 2), hc = (g * 4 + (row & 3)) * 128 + col8;
;       const f32x4 a0 = *reinterpret_cast<const f32x4*>(wl + row * 128 + col8), a1 = *reinterpret_cast<const f32x4*>(wl + row * 128 + col8 + 4);
;       const bf16x8 zv = ld8(p32(p.P, (unsigned)(t * LDP + C_ZN + hc)));
;       float f[8];
; #pragma unroll
;       for (int j = 0; j < 4; ++j) { f[j] = a0[j] * silu_f(bf2f((unsigned short)zv[j])); f[4 + j] = a1[j] * silu_f(bf2f((unsigned short)zv[4 + j])); }
;       u32x4 w = {cvtpk(f[0], f[1]), cvtpk(f[2], f[3]), cvtpk(f[4], f[5]), cvtpk(f[6], f[7])};
;       *reinterpret_cast<u32x4*>((char*)p.y + (size_t)((unsigned)(t * DM + hc) * 2u)) = w;
	v_pk_mul_f32 v[18:19], v[4:5], v[18:19]
	v_mul_f32_e32 v4, 0xbfb8aa3b, v9
	v_mul_f32_e32 v5, 0xbfb8aa3b, v8
	v_exp_f32_e32 v4, v4
	v_exp_f32_e32 v5, v5
	s_nop 0
	v_pk_add_f32 v[4:5], v[4:5], 1.0 op_sel_hi:[1,0]
	s_nop 0
	v_div_scale_f32 v10, s[0:1], v5, v5, v8
	v_rcp_f32_e32 v20, v10
	s_nop 0
	v_fma_f32 v21, -v10, v20, 1.0
	v_fmac_f32_e32 v20, v21, v20
	v_div_scale_f32 v21, vcc, v8, v5, v8
	v_mul_f32_e32 v22, v21, v20
	v_fma_f32 v23, -v10, v22, v21
	v_fmac_f32_e32 v22, v23, v20
	v_fma_f32 v10, -v10, v22, v21
	v_div_fmas_f32 v10, v10, v20, v22
	v_div_fixup_f32 v5, v10, v5, v8
	v_div_scale_f32 v8, s[0:1], v4, v4, v9
	v_rcp_f32_e32 v10, v8
	s_nop 0
	v_fma_f32 v20, -v8, v10, 1.0
	v_fmac_f32_e32 v10, v20, v10
	v_div_scale_f32 v20, vcc, v9, v4, v9
	v_mul_f32_e32 v21, v20, v10
	v_fma_f32 v22, -v8, v21, v20
	v_fmac_f32_e32 v21, v22, v10
	v_fma_f32 v8, -v8, v21, v20
	v_div_fmas_f32 v8, v8, v10, v21
	v_div_fixup_f32 v4, v8, v4, v9
	v_and_b32_e32 v10, 0xffff0000, v11
	v_lshlrev_b32_e32 v11, 16, v11
	v_pk_mul_f32 v[8:9], v[14:15], v[4:5]
	v_mul_f32_e32 v4, 0xbfb8aa3b, v11
	v_mul_f32_e32 v5, 0xbfb8aa3b, v10
	v_exp_f32_e32 v4, v4
	v_exp_f32_e32 v5, v5
	s_nop 0
	v_pk_add_f32 v[4:5], v[4:5], 1.0 op_sel_hi:[1,0]
	s_nop 0
	v_div_scale_f32 v14, s[0:1], v5, v5, v10
	v_rcp_f32_e32 v15, v14
	s_nop 0
	v_fma_f32 v20, -v14, v15, 1.0
	v_fmac_f32_e32 v15, v20, v15
	v_div_scale_f32 v20, vcc, v10, v5, v10
	v_mul_f32_e32 v21, v20, v15
	v_fma_f32 v22, -v14, v21, v20
	v_fmac_f32_e32 v21, v22, v15
	v_fma_f32 v14, -v14, v21, v20
	v_div_fmas_f32 v14, v14, v15, v21
	v_div_fixup_f32 v5, v14, v5, v10
	v_div_scale_f32 v10, s[0:1], v4, v4, v11
	v_rcp_f32_e32 v14, v10
	s_nop 0
	v_fma_f32 v15, -v10, v14, 1.0
	v_fmac_f32_e32 v14, v15, v14
	v_div_scale_f32 v15, vcc, v11, v4, v11
	v_mul_f32_e32 v20, v15, v14
	v_fma_f32 v21, -v10, v20, v15
	v_fmac_f32_e32 v20, v21, v14
	v_fma_f32 v10, -v10, v20, v15
	v_div_fmas_f32 v10, v10, v14, v20
	v_div_fixup_f32 v4, v10, v4, v11
	v_pk_mul_f32 v[10:11], v[6:7], v[4:5]
	v_cvt_pk_bf16_f32 v4, v12, v13
	v_cvt_pk_bf16_f32 v5, v8, v9
	v_cvt_pk_bf16_f32 v6, v18, v19
	v_cvt_pk_bf16_f32 v7, v10, v11
	v_add_u32_e32 v8, 0x8000, v17
	global_store_dwordx4 v8, v[4:7], s[48:49]
	v_add_u32_e32 v8, 0x21200, v16
	ds_read_b128 v[12:15], v2 offset:10240
	ds_read_b128 v[4:7], v2 offset:10256
	global_load_dwordx4 v[8:11], v8, s[46:47]
	s_waitcnt vmcnt(0)
	v_and_b32_e32 v20, 0xffff0000, v8
	v_lshlrev_b32_e32 v8, 16, v8
	v_mul_f32_e32 v18, 0xbfb8aa3b, v8
	v_mul_f32_e32 v19, 0xbfb8aa3b, v20
	v_exp_f32_e32 v18, v18
	v_exp_f32_e32 v19, v19
	s_nop 0
	v_pk_add_f32 v[18:19], v[18:19], 1.0 op_sel_hi:[1,0]
	s_nop 0
	v_div_scale_f32 v21, s[0:1], v19, v19, v20
	v_rcp_f32_e32 v22, v21
	s_nop 0
	v_fma_f32 v23, -v21, v22, 1.0
	v_fmac_f32_e32 v22, v23, v22
	v_div_scale_f32 v23, vcc, v20, v19, v20
	v_mul_f32_e32 v24, v23, v22
	v_fma_f32 v25, -v21, v24, v23
	v_fmac_f32_e32 v24, v25, v22
	v_fma_f32 v21, -v21, v24, v23
	v_div_fmas_f32 v21, v21, v22, v24
	v_div_fixup_f32 v19, v21, v19, v20
	v_div_scale_f32 v20, s[0:1], v18, v18, v8
	v_rcp_f32_e32 v21, v20
	s_nop 0
	v_fma_f32 v22, -v20, v21, 1.0
	v_fmac_f32_e32 v21, v22, v21
	v_div_scale_f32 v22, vcc, v8, v18, v8
	v_mul_f32_e32 v23, v22, v21
	v_fma_f32 v24, -v20, v23, v22
	v_fmac_f32_e32 v23, v24, v21
	v_fma_f32 v20, -v20, v23, v22
	v_div_fmas_f32 v20, v20, v21, v23
	v_div_fixup_f32 v18, v20, v18, v8
	v_and_b32_e32 v8, 0xffff0000, v10
	v_lshlrev_b32_e32 v10, 16, v10
	s_waitcnt lgkmcnt(1)
	v_pk_mul_f32 v[12:13], v[12:13], v[18:19]
	v_mul_f32_e32 v18, 0xbfb8aa3b, v10
	v_mul_f32_e32 v19, 0xbfb8aa3b, v8
	v_exp_f32_e32 v18, v18
	v_exp_f32_e32 v19, v19
	s_nop 0
	v_pk_add_f32 v[18:19], v[18:19], 1.0 op_sel_hi:[1,0]
	s_nop 0
	v_div_scale_f32 v20, s[0:1], v19, v19, v8
	v_rcp_f32_e32 v21, v20
	s_nop 0
	v_fma_f32 v22, -v20, v21, 1.0
	v_fmac_f32_e32 v21, v22, v21
	v_div_scale_f32 v22, vcc, v8, v19, v8
	v_mul_f32_e32 v23, v22, v21
	v_fma_f32 v24, -v20, v23, v22
	v_fmac_f32_e32 v23, v24, v21
	v_fma_f32 v20, -v20, v23, v22
	v_div_fmas_f32 v20, v20, v21, v23
	v_div_fixup_f32 v19, v20, v19, v8
	v_div_scale_f32 v8, s[0:1], v18, v18, v10
	v_rcp_f32_e32 v20, v8
	s_nop 0
	v_fma_f32 v21, -v8, v20, 1.0
	v_fmac_f32_e32 v20, v21, v20
	v_div_scale_f32 v21, vcc, v10, v18, v10
	v_mul_f32_e32 v22, v21, v20
	v_fma_f32 v23, -v8, v22, v21
	v_fmac_f32_e32 v22, v23, v20
	v_fma_f32 v8, -v8, v22, v21
	v_div_fmas_f32 v8, v8, v20, v22
	v_div_fixup_f32 v18, v8, v18, v10
	v_and_b32_e32 v8, 0xffff0000, v9
	v_lshlrev_b32_e32 v9, 16, v9
	s_waitcnt lgkmcnt(0)
; __device__ __forceinline__ float bf2f(unsigned short u) { return __uint_as_float(((unsigned)u) << 16); }
; __device__ __forceinline__ float silu_f(float z) { return z / (1.f + __expf(-z)); }
; __device__ __forceinline__ const bf16* p32(const bf16* base, unsigned elem_off) { return (const bf16*)((const char*)base + (size_t)(elem_off * 2u)); }
; __device__ void nsa_item(const Params& p, int qb, int g, char* smem) {
;     ...
;     for (int i = 0; i < 8; ++i) {
;       const int c = i * 64 + L.lane, row = c >> 4, col8 = (c & 15) * 8;
;       const int t = q0 + L.wid * 8 + (row >> 2), hc = (g * 4 + (row & 3)) * 128 + col8;
;       const f32x4 a0 = *reinterpret_cast<const f32x4*>(wl + row * 128 + col8), a1 = *reinterpret_cast<const f32x4*>(wl + row * 128 + col8 + 4);
;       const bf16x8 zv = ld8(p32(p.P, (unsigned)(t * LDP + C_ZN + hc)));
;       float f[8];
; #pragma unroll
;       for (int j = 0; j < 4; ++j) { f[j] = a0[j] * silu_f(bf2f((unsigned short)zv[j])); f[4 + j] = a1[j] * silu_f(bf2f((unsigned short)zv[4 + j])); }
;       u32x4 w = {cvtpk(f[0], f[1]), cvtpk(f[2], f[3]), cvtpk(f[4], f[5]), cvtpk(f[6], f[7])};
;       *reinterpret_cast<u32x4*>((char*)p.y + (size_t)((unsigned)(t * DM + hc) * 2u)) = w;
	v_pk_mul_f32 v[18:19], v[4:5], v[18:19]
	v_mul_f32_e32 v4, 0xbfb8aa3b, v9
	v_mul_f32_e32 v5, 0xbfb8aa3b, v8
	v_exp_f32_e32 v4, v4
	v_exp_f32_e32 v5, v5
	s_nop 0
	v_pk_add_f32 v[4:5], v[4:5], 1.0 op_sel_hi:[1,0]
	s_nop 0
	v_div_scale_f32 v10, s[0:1], v5, v5, v8
	v_rcp_f32_e32 v20, v10
	s_nop 0
	v_fma_f32 v21, -v10, v20, 1.0
	v_fmac_f32_e32 v20, v21, v20
	v_div_scale_f32 v21, vcc, v8, v5, v8
	v_mul_f32_e32 v22, v21, v20
	v_fma_f32 v23, -v10, v22, v21
	v_fmac_f32_e32 v22, v23, v20
	v_fma_f32 v10, -v10, v22, v21
	v_div_fmas_f32 v10, v10, v20, v22
	v_div_fixup_f32 v5, v10, v5, v8
	v_div_scale_f32 v8, s[0:1], v4, v4, v9
	v_rcp_f32_e32 v10, v8
	s_nop 0
	v_fma_f32 v20, -v8, v10, 1.0
	v_fmac_f32_e32 v10, v20, v10
	v_div_scale_f32 v20, vcc, v9, v4, v9
	v_mul_f32_e32 v21, v20, v10
	v_fma_f32 v22, -v8, v21, v20
	v_fmac_f32_e32 v21, v22, v10
	v_fma_f32 v8, -v8, v21, v20
	v_div_fmas_f32 v8, v8, v10, v21
	v_div_fixup_f32 v4, v8, v4, v9
	v_and_b32_e32 v10, 0xffff0000, v11
	v_lshlrev_b32_e32 v11, 16, v11
	v_pk_mul_f32 v[8:9], v[14:15], v[4:5]
	v_mul_f32_e32 v4, 0xbfb8aa3b, v11
	v_mul_f32_e32 v5, 0xbfb8aa3b, v10
	v_exp_f32_e32 v4, v4
	v_exp_f32_e32 v5, v5
	s_nop 0
	v_pk_add_f32 v[4:5], v[4:5], 1.0 op_sel_hi:[1,0]
	s_nop 0
	v_div_scale_f32 v14, s[0:1], v5, v5, v10
	v_rcp_f32_e32 v15, v14
	s_nop 0
	v_fma_f32 v20, -v14, v15, 1.0
	v_fmac_f32_e32 v15, v20, v15
	v_div_scale_f32 v20, vcc, v10, v5, v10
	v_mul_f32_e32 v21, v20, v15
	v_fma_f32 v22, -v14, v21, v20
	v_fmac_f32_e32 v21, v22, v15
	v_fma_f32 v14, -v14, v21, v20
	v_div_fmas_f32 v14, v14, v15, v21
	v_div_fixup_f32 v5, v14, v5, v10
	v_div_scale_f32 v10, s[0:1], v4, v4, v11
	v_rcp_f32_e32 v14, v10
	s_nop 0
	v_fma_f32 v15, -v10, v14, 1.0
	v_fmac_f32_e32 v14, v15, v14
	v_div_scale_f32 v15, vcc, v11, v4, v11
	v_mul_f32_e32 v20, v15, v14
	v_fma_f32 v21, -v10, v20, v15
	v_fmac_f32_e32 v20, v21, v14
	v_fma_f32 v10, -v10, v20, v15
	v_div_fmas_f32 v10, v10, v14, v20
	v_div_fixup_f32 v4, v10, v4, v11
	v_pk_mul_f32 v[10:11], v[6:7], v[4:5]
	v_cvt_pk_bf16_f32 v4, v12, v13
	v_cvt_pk_bf16_f32 v5, v8, v9
	v_cvt_pk_bf16_f32 v6, v18, v19
	v_cvt_pk_bf16_f32 v7, v10, v11
	v_add_u32_e32 v8, 0xa000, v17
	global_store_dwordx4 v8, v[4:7], s[48:49]
	v_add_u32_e32 v8, 0x27400, v16
	ds_read_b128 v[12:15], v2 offset:12288
	ds_read_b128 v[4:7], v2 offset:12304
	global_load_dwordx4 v[8:11], v8, s[46:47]
	s_waitcnt vmcnt(0)
	v_and_b32_e32 v20, 0xffff0000, v8
	v_lshlrev_b32_e32 v8, 16, v8
	v_mul_f32_e32 v18, 0xbfb8aa3b, v8
	v_mul_f32_e32 v19, 0xbfb8aa3b, v20
	v_exp_f32_e32 v18, v18
	v_exp_f32_e32 v19, v19
	s_nop 0
	v_pk_add_f32 v[18:19], v[18:19], 1.0 op_sel_hi:[1,0]
	s_nop 0
	v_div_scale_f32 v21, s[0:1], v19, v19, v20
	v_rcp_f32_e32 v22, v21
	s_nop 0
	v_fma_f32 v23, -v21, v22, 1.0
	v_fmac_f32_e32 v22, v23, v22
	v_div_scale_f32 v23, vcc, v20, v19, v20
	v_mul_f32_e32 v24, v23, v22
	v_fma_f32 v25, -v21, v24, v23
	v_fmac_f32_e32 v24, v25, v22
	v_fma_f32 v21, -v21, v24, v23
	v_div_fmas_f32 v21, v21, v22, v24
	v_div_fixup_f32 v19, v21, v19, v20
	v_div_scale_f32 v20, s[0:1], v18, v18, v8
	v_rcp_f32_e32 v21, v20
	s_nop 0
	v_fma_f32 v22, -v20, v21, 1.0
	v_fmac_f32_e32 v21, v22, v21
	v_div_scale_f32 v22, vcc, v8, v18, v8
	v_mul_f32_e32 v23, v22, v21
	v_fma_f32 v24, -v20, v23, v22
	v_fmac_f32_e32 v23, v24, v21
	v_fma_f32 v20, -v20, v23, v22
	v_div_fmas_f32 v20, v20, v21, v23
	v_div_fixup_f32 v18, v20, v18, v8
	v_and_b32_e32 v8, 0xffff0000, v10
	v_lshlrev_b32_e32 v10, 16, v10
	s_waitcnt lgkmcnt(1)
	v_pk_mul_f32 v[12:13], v[12:13], v[18:19]
	v_mul_f32_e32 v18, 0xbfb8aa3b, v10
	v_mul_f32_e32 v19, 0xbfb8aa3b, v8
	v_exp_f32_e32 v18, v18
	v_exp_f32_e32 v19, v19
	s_nop 0
	v_pk_add_f32 v[18:19], v[18:19], 1.0 op_sel_hi:[1,0]
	s_nop 0
	v_div_scale_f32 v20, s[0:1], v19, v19, v8
	v_rcp_f32_e32 v21, v20
	s_nop 0
	v_fma_f32 v22, -v20, v21, 1.0
	v_fmac_f32_e32 v21, v22, v21
	v_div_scale_f32 v22, vcc, v8, v19, v8
	v_mul_f32_e32 v23, v22, v21
	v_fma_f32 v24, -v20, v23, v22
	v_fmac_f32_e32 v23, v24, v21
	v_fma_f32 v20, -v20, v23, v22
	v_div_fmas_f32 v20, v20, v21, v23
	v_div_fixup_f32 v19, v20, v19, v8
	v_div_scale_f32 v8, s[0:1], v18, v18, v10
	v_rcp_f32_e32 v20, v8
	s_nop 0
	v_fma_f32 v21, -v8, v20, 1.0
	v_fmac_f32_e32 v20, v21, v20
	v_div_scale_f32 v21, vcc, v10, v18, v10
	v_mul_f32_e32 v22, v21, v20
	v_fma_f32 v23, -v8, v22, v21
	v_fmac_f32_e32 v22, v23, v20
	v_fma_f32 v8, -v8, v22, v21
	v_div_fmas_f32 v8, v8, v20, v22
	v_div_fixup_f32 v18, v8, v18, v10
	v_and_b32_e32 v8, 0xffff0000, v9
	v_lshlrev_b32_e32 v9, 16, v9
	s_waitcnt lgkmcnt(0)
; __device__ __forceinline__ float bf2f(unsigned short u) { return __uint_as_float(((unsigned)u) << 16); }
; __device__ __forceinline__ float silu_f(float z) { return z / (1.f + __expf(-z)); }
; __device__ __forceinline__ const bf16* p32(const bf16* base, unsigned elem_off) { return (const bf16*)((const char*)base + (size_t)(elem_off * 2u)); }
; __device__ void nsa_item(const Params& p, int qb, int g, char* smem) {
;     ...
;     for (int i = 0; i < 8; ++i) {
;       const int c = i * 64 + L.lane, row = c >> 4, col8 = (c & 15) * 8;
;       const int t = q0 + L.wid * 8 + (row >> 2), hc = (g * 4 + (row & 3)) * 128 + col8;
;       const f32x4 a0 = *reinterpret_cast<const f32x4*>(wl + row * 128 + col8), a1 = *reinterpret_cast<const f32x4*>(wl + row * 128 + col8 + 4);
;       const bf16x8 zv = ld8(p32(p.P, (unsigned)(t * LDP + C_ZN + hc)));
;       float f[8];
; #pragma unroll
;       for (int j = 0; j < 4; ++j) { f[j] = a0[j] * silu_f(bf2f((unsigned short)zv[j])); f[4 + j] = a1[j] * silu_f(bf2f((unsigned short)zv[4 + j])); }
;       u32x4 w = {cvtpk(f[0], f[1]), cvtpk(f[2], f[3]), cvtpk(f[4], f[5]), cvtpk(f[6], f[7])};
;       *reinterpret_cast<u32x4*>((char*)p.y + (size_t)((unsigned)(t * DM + hc) * 2u)) = w;
;     }
	v_pk_mul_f32 v[18:19], v[4:5], v[18:19]
	v_mul_f32_e32 v4, 0xbfb8aa3b, v9
	v_mul_f32_e32 v5, 0xbfb8aa3b, v8
	v_exp_f32_e32 v4, v4
	v_exp_f32_e32 v5, v5
	s_nop 0
	v_pk_add_f32 v[4:5], v[4:5], 1.0 op_sel_hi:[1,0]
	s_nop 0
	v_div_scale_f32 v10, s[0:1], v5, v5, v8
	v_rcp_f32_e32 v20, v10
	s_nop 0
	v_fma_f32 v21, -v10, v20, 1.0
	v_fmac_f32_e32 v20, v21, v20
	v_div_scale_f32 v21, vcc, v8, v5, v8
	v_mul_f32_e32 v22, v21, v20
	v_fma_f32 v23, -v10, v22, v21
	v_fmac_f32_e32 v22, v23, v20
	v_fma_f32 v10, -v10, v22, v21
	v_div_fmas_f32 v10, v10, v20, v22
	v_div_fixup_f32 v5, v10, v5, v8
	v_div_scale_f32 v8, s[0:1], v4, v4, v9
	v_rcp_f32_e32 v10, v8
	s_nop 0
	v_fma_f32 v20, -v8, v10, 1.0
	v_fmac_f32_e32 v10, v20, v10
	v_div_scale_f32 v20, vcc, v9, v4, v9
	v_mul_f32_e32 v21, v20, v10
	v_fma_f32 v22, -v8, v21, v20
	v_fmac_f32_e32 v21, v22, v10
	v_fma_f32 v8, -v8, v21, v20
	v_div_fmas_f32 v8, v8, v10, v21
	v_div_fixup_f32 v4, v8, v4, v9
	v_and_b32_e32 v10, 0xffff0000, v11
	v_lshlrev_b32_e32 v11, 16, v11
	v_pk_mul_f32 v[8:9], v[14:15], v[4:5]
	v_mul_f32_e32 v4, 0xbfb8aa3b, v11
	v_mul_f32_e32 v5, 0xbfb8aa3b, v10
	v_exp_f32_e32 v4, v4
	v_exp_f32_e32 v5, v5
	s_nop 0
	v_pk_add_f32 v[4:5], v[4:5], 1.0 op_sel_hi:[1,0]
	s_nop 0
	v_div_scale_f32 v14, s[0:1], v5, v5, v10
	v_rcp_f32_e32 v15, v14
	s_nop 0
	v_fma_f32 v20, -v14, v15, 1.0
	v_fmac_f32_e32 v15, v20, v15
	v_div_scale_f32 v20, vcc, v10, v5, v10
	v_mul_f32_e32 v21, v20, v15
	v_fma_f32 v22, -v14, v21, v20
	v_fmac_f32_e32 v21, v22, v15
	v_fma_f32 v14, -v14, v21, v20
	v_div_fmas_f32 v14, v14, v15, v21
	v_div_fixup_f32 v5, v14, v5, v10
	v_div_scale_f32 v10, s[0:1], v4, v4, v11
	v_rcp_f32_e32 v14, v10
	s_nop 0
	v_fma_f32 v15, -v10, v14, 1.0
	v_fmac_f32_e32 v14, v15, v14
	v_div_scale_f32 v15, vcc, v11, v4, v11
	v_mul_f32_e32 v20, v15, v14
	v_fma_f32 v21, -v10, v20, v15
	v_fmac_f32_e32 v20, v21, v14
	v_fma_f32 v10, -v10, v20, v15
	v_div_fmas_f32 v10, v10, v14, v20
	v_div_fixup_f32 v4, v10, v4, v11
	v_pk_mul_f32 v[10:11], v[6:7], v[4:5]
	v_cvt_pk_bf16_f32 v4, v12, v13
	v_cvt_pk_bf16_f32 v5, v8, v9
	v_cvt_pk_bf16_f32 v6, v18, v19
	v_cvt_pk_bf16_f32 v7, v10, v11
	v_add_u32_e32 v8, 0xc000, v17
	global_store_dwordx4 v8, v[4:7], s[48:49]
	ds_read_b128 v[12:15], v2 offset:14336
	ds_read_b128 v[4:7], v2 offset:14352
	v_add_u32_e32 v2, 0x2d600, v16
	global_load_dwordx4 v[8:11], v2, s[46:47]
	s_waitcnt vmcnt(0)
	v_and_b32_e32 v2, 0xffff0000, v8
	v_lshlrev_b32_e32 v8, 16, v8
	v_mul_f32_e32 v16, 0xbfb8aa3b, v8
	v_exp_f32_e32 v18, v16
	v_mul_f32_e32 v16, 0xbfb8aa3b, v2
	v_exp_f32_e32 v19, v16
	s_nop 0
	v_pk_add_f32 v[18:19], v[18:19], 1.0 op_sel_hi:[1,0]
	s_nop 0
	v_div_scale_f32 v16, s[0:1], v19, v19, v2
	v_rcp_f32_e32 v20, v16
	s_nop 0
	v_fma_f32 v21, -v16, v20, 1.0
	v_fmac_f32_e32 v20, v21, v20
	v_div_scale_f32 v21, vcc, v2, v19, v2
	v_mul_f32_e32 v22, v21, v20
	v_fma_f32 v23, -v16, v22, v21
	v_fmac_f32_e32 v22, v23, v20
	v_fma_f32 v16, -v16, v22, v21
	v_div_fmas_f32 v16, v16, v20, v22
	v_div_fixup_f32 v19, v16, v19, v2
	v_div_scale_f32 v2, s[0:1], v18, v18, v8
	v_rcp_f32_e32 v16, v2
	s_nop 0
	v_fma_f32 v20, -v2, v16, 1.0
	v_fmac_f32_e32 v16, v20, v16
	v_div_scale_f32 v20, vcc, v8, v18, v8
	v_mul_f32_e32 v21, v20, v16
	v_fma_f32 v22, -v2, v21, v20
	v_fmac_f32_e32 v21, v22, v16
	v_fma_f32 v2, -v2, v21, v20
	v_div_fmas_f32 v2, v2, v16, v21
	v_div_fixup_f32 v18, v2, v18, v8
	v_lshlrev_b32_e32 v8, 16, v10
	v_and_b32_e32 v2, 0xffff0000, v10
	v_mul_f32_e32 v10, 0xbfb8aa3b, v8
	s_waitcnt lgkmcnt(1)
	v_pk_mul_f32 v[12:13], v[12:13], v[18:19]
	v_exp_f32_e32 v18, v10
	v_mul_f32_e32 v10, 0xbfb8aa3b, v2
	v_exp_f32_e32 v19, v10
	s_nop 0
	v_pk_add_f32 v[18:19], v[18:19], 1.0 op_sel_hi:[1,0]
	s_nop 0
	v_div_scale_f32 v10, s[0:1], v19, v19, v2
	v_rcp_f32_e32 v16, v10
	s_nop 0
	v_fma_f32 v20, -v10, v16, 1.0
	v_fmac_f32_e32 v16, v20, v16
	v_div_scale_f32 v20, vcc, v2, v19, v2
	v_mul_f32_e32 v21, v20, v16
	v_fma_f32 v22, -v10, v21, v20
	v_fmac_f32_e32 v21, v22, v16
	v_fma_f32 v10, -v10, v21, v20
	v_div_fmas_f32 v10, v10, v16, v21
	v_div_fixup_f32 v19, v10, v19, v2
	v_div_scale_f32 v2, s[0:1], v18, v18, v8
	v_rcp_f32_e32 v10, v2
	s_nop 0
	v_fma_f32 v16, -v2, v10, 1.0
	v_fmac_f32_e32 v10, v16, v10
	v_div_scale_f32 v16, vcc, v8, v18, v8
	v_mul_f32_e32 v20, v16, v10
	v_fma_f32 v21, -v2, v20, v16
	v_fmac_f32_e32 v20, v21, v10
	v_fma_f32 v2, -v2, v20, v16
	v_div_fmas_f32 v2, v2, v10, v20
	v_div_fixup_f32 v18, v2, v18, v8
	v_and_b32_e32 v2, 0xffff0000, v9
	v_lshlrev_b32_e32 v8, 16, v9
	s_waitcnt lgkmcnt(0)
	v_pk_mul_f32 v[18:19], v[4:5], v[18:19]
	v_mul_f32_e32 v4, 0xbfb8aa3b, v8
	v_mul_f32_e32 v5, 0xbfb8aa3b, v2
	v_exp_f32_e32 v4, v4
	v_exp_f32_e32 v5, v5
	s_nop 0
	v_pk_add_f32 v[4:5], v[4:5], 1.0 op_sel_hi:[1,0]
	s_nop 0
	v_div_scale_f32 v9, s[0:1], v5, v5, v2
	v_rcp_f32_e32 v10, v9
	s_nop 0
	v_fma_f32 v16, -v9, v10, 1.0
	v_fmac_f32_e32 v10, v16, v10
	v_div_scale_f32 v16, vcc, v2, v5, v2
	v_mul_f32_e32 v20, v16, v10
	v_fma_f32 v21, -v9, v20, v16
	v_fmac_f32_e32 v20, v21, v10
	v_fma_f32 v9, -v9, v20, v16
	v_div_fmas_f32 v9, v9, v10, v20
	v_div_fixup_f32 v5, v9, v5, v2
	v_div_scale_f32 v2, s[0:1], v4, v4, v8
	v_rcp_f32_e32 v9, v2
	s_nop 0
	v_fma_f32 v10, -v2, v9, 1.0
	v_fmac_f32_e32 v9, v10, v9
	v_div_scale_f32 v10, vcc, v8, v4, v8
	v_mul_f32_e32 v16, v10, v9
	v_fma_f32 v20, -v2, v16, v10
	v_fmac_f32_e32 v16, v20, v9
	v_fma_f32 v2, -v2, v16, v10
	v_div_fmas_f32 v2, v2, v9, v16
	v_div_fixup_f32 v4, v2, v4, v8
	v_and_b32_e32 v2, 0xffff0000, v11
	v_lshlrev_b32_e32 v10, 16, v11
	v_pk_mul_f32 v[8:9], v[14:15], v[4:5]
	v_mul_f32_e32 v4, 0xbfb8aa3b, v10
	v_mul_f32_e32 v5, 0xbfb8aa3b, v2
	v_exp_f32_e32 v4, v4
	v_exp_f32_e32 v5, v5
	s_nop 0
	v_pk_add_f32 v[4:5], v[4:5], 1.0 op_sel_hi:[1,0]
	s_nop 0
	v_div_scale_f32 v11, s[0:1], v5, v5, v2
	v_rcp_f32_e32 v14, v11
	s_nop 0
	v_fma_f32 v15, -v11, v14, 1.0
	v_fmac_f32_e32 v14, v15, v14
	v_div_scale_f32 v15, vcc, v2, v5, v2
	v_mul_f32_e32 v16, v15, v14
	v_fma_f32 v20, -v11, v16, v15
	v_fmac_f32_e32 v16, v20, v14
	v_fma_f32 v11, -v11, v16, v15
	v_div_fmas_f32 v11, v11, v14, v16
	v_div_fixup_f32 v5, v11, v5, v2
	v_div_scale_f32 v2, s[0:1], v4, v4, v10
	v_rcp_f32_e32 v11, v2
	s_nop 0
	v_fma_f32 v14, -v2, v11, 1.0
	v_fmac_f32_e32 v11, v14, v11
	v_div_scale_f32 v14, vcc, v10, v4, v10
	v_mul_f32_e32 v15, v14, v11
	v_fma_f32 v16, -v2, v15, v14
	v_fmac_f32_e32 v15, v16, v11
	v_fma_f32 v2, -v2, v15, v14
	v_div_fmas_f32 v2, v2, v11, v15
	v_div_fixup_f32 v4, v2, v4, v10
	v_pk_mul_f32 v[10:11], v[6:7], v[4:5]
	v_cvt_pk_bf16_f32 v4, v12, v13
	v_cvt_pk_bf16_f32 v5, v8, v9
	v_cvt_pk_bf16_f32 v6, v18, v19
	v_cvt_pk_bf16_f32 v7, v10, v11
	v_add_u32_e32 v2, 0xe000, v17
	global_store_dwordx4 v2, v[4:7], s[48:49]

; __device__ __forceinline__ int crow(int r, int hi) { return (r & 3) + 8 * (r >> 2) + 4 * hi; }
; __device__ void memx_item(const Params& p, int qblk, int hm, char* smem) {
;     ...
;   float* fac = (float*)(smem + 131072) + wid * 32;
;   if (hi == 0) fac[r32] = 1.f / l;
;   f32x4 f4[4];
; #pragma unroll
;   for (int a = 0; a < 4; ++a) f4[a] = *reinterpret_cast<const f32x4*>(fac + 8 * a + 4 * hi);
;   __syncthreads();
;   {
;     float* wl = (float*)(smem + wid * 16384);
; #pragma unroll
;     for (int r = 0; r < 16; ++r) { const int row = crow(r, hi);
; #pragma unroll
;       for (int d0 = 0; d0 < 4; ++d0) wl[row * 128 + 32 * d0 + r32] = o[d0][r] * f4[r >> 2][r & 3]; }
;     asm volatile("s_waitcnt lgkmcnt(0)" ::: "memory");
; #pragma unroll
;     for (int i = 0; i < 8; ++i) {
;       const int c = i * 64 + lane, row = c >> 4, col8 = (c & 15) * 8;
;       const long tt = (long)qblk * 128 + 32 * rb + row; const int d = hm * 256 + dh * 128 + col8;
;       const f32x4 a0 = *reinterpret_cast<const f32x4*>(wl + row * 128 + col8), a1 = *reinterpret_cast<const f32x4*>(wl + row * 128 + col8 + 4);
;       const bf16x8 zv = ld8(p.P + tt * LDP + C_ZM + d);
.LBB0_254:
	s_or_b64 exec, exec, s[2:3]
	v_add_u32_e32 v2, v68, v2
	ds_read_b128 v[68:71], v2
	ds_read_b128 v[72:75], v2 offset:32
	ds_read_b128 v[76:79], v2 offset:64
	ds_read_b128 v[80:83], v2 offset:96
	v_lshlrev_b32_e32 v84, 14, v197
	s_waitcnt lgkmcnt(0)
	v_mul_f32_e32 v2, v4, v68
	v_lshlrev_b32_e32 v4, 11, v198
	v_lshlrev_b32_e32 v85, 2, v196
	v_or3_b32 v4, v84, v4, v85
	v_mul_f32_e32 v20, v20, v68
	s_waitcnt vmcnt(0)
	s_barrier
	ds_write2_b32 v4, v2, v20 offset1:32
	v_mul_f32_e32 v2, v36, v68
	v_mul_f32_e32 v20, v52, v68
	ds_write2_b32 v4, v2, v20 offset0:64 offset1:96
	v_mul_f32_e32 v2, v5, v69
	v_mul_f32_e32 v5, v21, v69
	ds_write2_b32 v4, v2, v5 offset0:128 offset1:160
	v_mul_f32_e32 v2, v37, v69
	v_mul_f32_e32 v5, v53, v69
	ds_write2_b32 v4, v2, v5 offset0:192 offset1:224
	v_mul_f32_e32 v2, v6, v70
	v_mul_f32_e32 v5, v22, v70
	v_add_u32_e32 v6, 0x400, v4
	ds_write2_b32 v6, v2, v5 offset1:32
	v_mul_f32_e32 v2, v38, v70
	v_mul_f32_e32 v5, v54, v70
	ds_write2_b32 v6, v2, v5 offset0:64 offset1:96
	v_mul_f32_e32 v2, v7, v71
	v_mul_f32_e32 v5, v23, v71
	ds_write2_b32 v6, v2, v5 offset0:128 offset1:160
	v_mul_f32_e32 v2, v39, v71
	v_mul_f32_e32 v5, v55, v71
	ds_write2_b32 v6, v2, v5 offset0:192 offset1:224
	v_mul_f32_e32 v2, v8, v72
	v_mul_f32_e32 v5, v24, v72
	v_add_u32_e32 v6, 0x1000, v4
	ds_write2_b32 v6, v2, v5 offset1:32
	v_mul_f32_e32 v2, v40, v72
	v_mul_f32_e32 v5, v56, v72
	ds_write2_b32 v6, v2, v5 offset0:64 offset1:96
	v_mul_f32_e32 v2, v9, v73
	v_mul_f32_e32 v5, v25, v73
	ds_write2_b32 v6, v2, v5 offset0:128 offset1:160
	v_mul_f32_e32 v2, v41, v73
	v_mul_f32_e32 v5, v57, v73
	ds_write2_b32 v6, v2, v5 offset0:192 offset1:224
	v_mul_f32_e32 v2, v10, v74
	v_mul_f32_e32 v5, v26, v74
	v_add_u32_e32 v6, 0x1400, v4
	ds_write2_b32 v6, v2, v5 offset1:32
	v_mul_f32_e32 v2, v42, v74
	v_mul_f32_e32 v5, v58, v74
	ds_write2_b32 v6, v2, v5 offset0:64 offset1:96
	v_mul_f32_e32 v2, v11, v75
	v_mul_f32_e32 v5, v27, v75
	ds_write2_b32 v6, v2, v5 offset0:128 offset1:160
	v_mul_f32_e32 v2, v43, v75
	v_mul_f32_e32 v5, v59, v75
	ds_write2_b32 v6, v2, v5 offset0:192 offset1:224
	v_mul_f32_e32 v2, v12, v76
	v_mul_f32_e32 v5, v28, v76
	v_add_u32_e32 v6, 0x2000, v4
	ds_write2_b32 v6, v2, v5 offset1:32
	v_mul_f32_e32 v2, v44, v76
	v_mul_f32_e32 v5, v60, v76
	ds_write2_b32 v6, v2, v5 offset0:64 offset1:96
	v_mul_f32_e32 v2, v13, v77
	v_mul_f32_e32 v5, v29, v77
	ds_write2_b32 v6, v2, v5 offset0:128 offset1:160
	v_mul_f32_e32 v2, v45, v77
	v_mul_f32_e32 v5, v61, v77
	ds_write2_b32 v6, v2, v5 offset0:192 offset1:224
	v_mul_f32_e32 v2, v14, v78
	v_mul_f32_e32 v5, v30, v78
	v_add_u32_e32 v6, 0x2400, v4
	ds_write2_b32 v6, v2, v5 offset1:32
	v_mul_f32_e32 v2, v46, v78
	v_mul_f32_e32 v5, v62, v78
	ds_write2_b32 v6, v2, v5 offset0:64 offset1:96
	v_mul_f32_e32 v2, v15, v79
	v_mul_f32_e32 v5, v31, v79
	ds_write2_b32 v6, v2, v5 offset0:128 offset1:160
	v_mul_f32_e32 v2, v47, v79
	v_mul_f32_e32 v5, v63, v79
	ds_write2_b32 v6, v2, v5 offset0:192 offset1:224
	v_mul_f32_e32 v2, v16, v80
	v_mul_f32_e32 v5, v32, v80
	v_add_u32_e32 v6, 0x3000, v4
	ds_write2_b32 v6, v2, v5 offset1:32
	v_mul_f32_e32 v2, v48, v80
	v_mul_f32_e32 v5, v64, v80
	ds_write2_b32 v6, v2, v5 offset0:64 offset1:96
	v_mul_f32_e32 v2, v17, v81
	v_mul_f32_e32 v5, v33, v81
	ds_write2_b32 v6, v2, v5 offset0:128 offset1:160
	v_mul_f32_e32 v2, v49, v81
	v_mul_f32_e32 v5, v65, v81
	ds_write2_b32 v6, v2, v5 offset0:192 offset1:224
	v_mul_f32_e32 v2, v18, v82
	v_mul_f32_e32 v5, v34, v82
	v_add_u32_e32 v4, 0x3400, v4
	ds_write2_b32 v4, v2, v5 offset1:32
	v_mul_f32_e32 v2, v50, v82
	v_mul_f32_e32 v5, v66, v82
	ds_write2_b32 v4, v2, v5 offset0:64 offset1:96
	v_mul_f32_e32 v2, v19, v83
	v_mul_f32_e32 v5, v35, v83
	ds_write2_b32 v4, v2, v5 offset0:128 offset1:160
	v_mul_f32_e32 v2, v51, v83
	v_mul_f32_e32 v5, v67, v83
	ds_write2_b32 v4, v2, v5 offset0:192 offset1:224
	v_and_b32_e32 v8, 0x78, v199
	v_lshl_add_u32 v2, v195, 7, s0
	v_or_b32_e32 v4, v2, v8
	v_lshrrev_b32_e32 v9, 4, v194
	v_ashrrev_i32_e32 v5, 31, v4
	v_or_b32_e32 v2, v165, v9
	v_mov_b64_e32 v[6:7], s[46:47]
	v_mad_u64_u32 v[10:11], s[0:1], v2, s33, v[6:7]
	v_lshlrev_b64 v[4:5], 1, v[4:5]
	v_lshl_add_u64 v[10:11], v[10:11], 0, v[4:5]
	v_add_co_u32_e32 v10, vcc, s4, v10
	s_waitcnt lgkmcnt(0)
	v_lshl_or_b32 v8, v8, 2, v84
	s_nop 0
	v_addc_co_u32_e32 v11, vcc, 0, v11, vcc
	s_lshl_b32 s0, s33, 2
	v_add_co_u32_e32 v14, vcc, s0, v10
	s_nop 1
	v_addc_co_u32_e32 v15, vcc, 0, v11, vcc
	global_load_dword v24, v[14:15], off offset:2048
	v_add_co_u32_e32 v14, vcc, s0, v14
	s_nop 1
	v_addc_co_u32_e32 v15, vcc, 0, v15, vcc
	global_load_dword v24, v[14:15], off offset:2048
	v_add_co_u32_e32 v14, vcc, s0, v14
	s_nop 1
	v_addc_co_u32_e32 v15, vcc, 0, v15, vcc
	global_load_dword v24, v[14:15], off offset:2048
	v_add_co_u32_e32 v14, vcc, s0, v14
	s_nop 1
	v_addc_co_u32_e32 v15, vcc, 0, v15, vcc
	global_load_dword v24, v[14:15], off offset:2048
	v_add_co_u32_e32 v14, vcc, s0, v14
	s_nop 1
	v_addc_co_u32_e32 v15, vcc, 0, v15, vcc
	global_load_dword v24, v[14:15], off offset:2048
	v_add_co_u32_e32 v14, vcc, s0, v14
	s_nop 1
	v_addc_co_u32_e32 v15, vcc, 0, v15, vcc
	global_load_dword v24, v[14:15], off offset:2048
	v_add_co_u32_e32 v14, vcc, s0, v14
	s_nop 1
	v_addc_co_u32_e32 v15, vcc, 0, v15, vcc
	global_load_dword v24, v[14:15], off offset:2048
	global_load_dwordx4 v[10:13], v[10:11], off offset:2048
	v_lshl_or_b32 v18, v9, 9, v8
	s_movk_i32 s2, 0x1000
	s_waitcnt vmcnt(0)
; __device__ __forceinline__ float bf2f(unsigned short u) { return __uint_as_float(((unsigned)u) << 16); }
; __device__ __forceinline__ float silu_f(float z) { return z / (1.f + __expf(-z)); }
; __device__ void memx_item(const Params& p, int qblk, int hm, char* smem) {
;     ...
;     for (int i = 0; i < 8; ++i) {
;       const int c = i * 64 + lane, row = c >> 4, col8 = (c & 15) * 8;
;       const long tt = (long)qblk * 128 + 32 * rb + row; const int d = hm * 256 + dh * 128 + col8;
;       const f32x4 a0 = *reinterpret_cast<const f32x4*>(wl + row * 128 + col8), a1 = *reinterpret_cast<const f32x4*>(wl + row * 128 + col8 + 4);
;       const bf16x8 zv = ld8(p.P + tt * LDP + C_ZM + d);
;       float f[8];
; #pragma unroll
;       for (int j = 0; j < 4; ++j) { f[j] = a0[j] * silu_f(bf2f((unsigned short)zv[j])); f[4 + j] = a1[j] * silu_f(bf2f((unsigned short)zv[4 + j])); }
;       u32x4 w = {cvtpk(f[0], f[1]), cvtpk(f[2], f[3]), cvtpk(f[4], f[5]), cvtpk(f[6], f[7])};
;       *reinterpret_cast<u32x4*>(p.y + tt * DM + 3072 + d) = w;
;     }
	v_and_b32_e32 v24, 0xffff0000, v10
	v_lshlrev_b32_e32 v10, 16, v10
	v_mul_f32_e32 v14, 0xbfb8aa3b, v10
	v_mul_f32_e32 v15, 0xbfb8aa3b, v24
	v_exp_f32_e32 v14, v14
	v_exp_f32_e32 v15, v15
	v_and_b32_e32 v30, 0xffff0000, v12
	v_lshlrev_b32_e32 v12, 16, v12
	v_pk_add_f32 v[22:23], v[14:15], 1.0 op_sel_hi:[1,0]
	s_nop 0
	v_div_scale_f32 v25, s[0:1], v23, v23, v24
	v_rcp_f32_e32 v26, v25
	ds_read_b128 v[14:17], v18
	ds_read_b128 v[18:21], v18 offset:16
	v_fma_f32 v27, -v25, v26, 1.0
	v_fmac_f32_e32 v26, v27, v26
	v_div_scale_f32 v27, vcc, v24, v23, v24
	v_mul_f32_e32 v28, v27, v26
	v_fma_f32 v29, -v25, v28, v27
	v_fmac_f32_e32 v28, v29, v26
	v_fma_f32 v25, -v25, v28, v27
	v_div_scale_f32 v27, s[0:1], v22, v22, v10
	v_rcp_f32_e32 v29, v27
	v_div_fmas_f32 v25, v25, v26, v28
	v_div_fixup_f32 v23, v25, v23, v24
	v_mul_f32_e32 v25, 0xbfb8aa3b, v30
	v_fma_f32 v24, -v27, v29, 1.0
	v_fmac_f32_e32 v29, v24, v29
	v_mul_f32_e32 v24, 0xbfb8aa3b, v12
	v_exp_f32_e32 v24, v24
	v_exp_f32_e32 v25, v25
	v_div_scale_f32 v26, vcc, v10, v22, v10
	v_mul_f32_e32 v28, v26, v29
	v_fma_f32 v31, -v27, v28, v26
	v_fmac_f32_e32 v28, v31, v29
	v_pk_add_f32 v[24:25], v[24:25], 1.0 op_sel_hi:[1,0]
	v_fma_f32 v26, -v27, v28, v26
	v_div_scale_f32 v27, s[0:1], v25, v25, v30
	v_rcp_f32_e32 v31, v27
	v_div_fmas_f32 v26, v26, v29, v28
	v_div_fixup_f32 v22, v26, v22, v10
	s_waitcnt lgkmcnt(1)
	v_pk_mul_f32 v[14:15], v[14:15], v[22:23]
	v_fma_f32 v10, -v27, v31, 1.0
	v_fmac_f32_e32 v31, v10, v31
	v_div_scale_f32 v10, vcc, v30, v25, v30
	v_mul_f32_e32 v22, v10, v31
	v_fma_f32 v23, -v27, v22, v10
	v_fmac_f32_e32 v22, v23, v31
	v_div_scale_f32 v26, s[0:1], v24, v24, v12
	v_fma_f32 v10, -v27, v22, v10
	v_rcp_f32_e32 v27, v26
	v_div_fmas_f32 v10, v10, v31, v22
	v_div_fixup_f32 v23, v10, v25, v30
	v_and_b32_e32 v28, 0xffff0000, v11
	v_fma_f32 v10, -v26, v27, 1.0
	v_lshlrev_b32_e32 v29, 16, v11
	v_fmac_f32_e32 v27, v10, v27
	v_mul_f32_e32 v10, 0xbfb8aa3b, v29
	v_mul_f32_e32 v11, 0xbfb8aa3b, v28
	v_exp_f32_e32 v10, v10
	v_exp_f32_e32 v11, v11
	v_div_scale_f32 v22, vcc, v12, v24, v12
	v_mul_f32_e32 v25, v22, v27
	v_fma_f32 v30, -v26, v25, v22
	v_fmac_f32_e32 v25, v30, v27
	v_pk_add_f32 v[10:11], v[10:11], 1.0 op_sel_hi:[1,0]
	v_fma_f32 v22, -v26, v25, v22
	v_div_scale_f32 v26, s[0:1], v11, v11, v28
	v_rcp_f32_e32 v30, v26
	v_div_fmas_f32 v22, v22, v27, v25
	v_div_fixup_f32 v22, v22, v24, v12
	s_waitcnt lgkmcnt(0)
	v_pk_mul_f32 v[18:19], v[18:19], v[22:23]
	v_fma_f32 v12, -v26, v30, 1.0
	v_fmac_f32_e32 v30, v12, v30
	v_div_scale_f32 v12, vcc, v28, v11, v28
	v_mul_f32_e32 v22, v12, v30
	v_fma_f32 v23, -v26, v22, v12
	v_fmac_f32_e32 v22, v23, v30
	v_div_scale_f32 v23, s[0:1], v10, v10, v29
	v_rcp_f32_e32 v24, v23
	v_fma_f32 v12, -v26, v22, v12
	v_div_fmas_f32 v12, v12, v30, v22
	v_div_fixup_f32 v11, v12, v11, v28
	v_fma_f32 v12, -v23, v24, 1.0
	v_and_b32_e32 v26, 0xffff0000, v13
	v_lshlrev_b32_e32 v27, 16, v13
	v_fmac_f32_e32 v24, v12, v24
	v_mul_f32_e32 v12, 0xbfb8aa3b, v27
	v_mul_f32_e32 v13, 0xbfb8aa3b, v26
	v_exp_f32_e32 v12, v12
	v_exp_f32_e32 v13, v13
	v_div_scale_f32 v22, vcc, v29, v10, v29
	v_mul_f32_e32 v25, v22, v24
	v_fma_f32 v28, -v23, v25, v22
	v_fmac_f32_e32 v25, v28, v24
	v_pk_add_f32 v[12:13], v[12:13], 1.0 op_sel_hi:[1,0]
	v_fma_f32 v22, -v23, v25, v22
	v_div_scale_f32 v23, s[0:1], v13, v13, v26
	v_rcp_f32_e32 v28, v23
	v_div_fmas_f32 v22, v22, v24, v25
	v_div_fixup_f32 v10, v22, v10, v29
	v_pk_mul_f32 v[16:17], v[16:17], v[10:11]
	v_fma_f32 v10, -v23, v28, 1.0
	v_fmac_f32_e32 v28, v10, v28
	v_div_scale_f32 v10, vcc, v26, v13, v26
	v_mul_f32_e32 v11, v10, v28
	v_fma_f32 v22, -v23, v11, v10
	v_fmac_f32_e32 v11, v22, v28
	v_div_scale_f32 v22, s[0:1], v12, v12, v27
	v_fma_f32 v10, -v23, v11, v10
	v_rcp_f32_e32 v23, v22
	v_div_fmas_f32 v10, v10, v28, v11
	v_div_fixup_f32 v11, v10, v13, v26
	v_fma_f32 v10, -v22, v23, 1.0
	v_fmac_f32_e32 v23, v10, v23
	v_div_scale_f32 v10, vcc, v27, v12, v27
	v_mul_f32_e32 v13, v10, v23
	v_fma_f32 v24, -v22, v13, v10
	v_fmac_f32_e32 v13, v24, v23
	v_fma_f32 v10, -v22, v13, v10
	v_div_fmas_f32 v10, v10, v23, v13
	v_div_fixup_f32 v10, v10, v12, v27
	v_pk_mul_f32 v[20:21], v[20:21], v[10:11]
	v_cvt_pk_bf16_f32 v10, v14, v15
	v_lshlrev_b64 v[14:15], 13, v[2:3]
	v_lshl_add_u64 v[14:15], s[48:49], 0, v[14:15]
	v_lshl_add_u64 v[14:15], v[14:15], 0, v[4:5]
	v_cvt_pk_bf16_f32 v11, v16, v17
	v_add_co_u32_e32 v14, vcc, s2, v14
	v_or_b32_e32 v16, 4, v9
	v_cvt_pk_bf16_f32 v12, v18, v19
	v_cvt_pk_bf16_f32 v13, v20, v21
	v_addc_co_u32_e32 v15, vcc, 0, v15, vcc
	v_or_b32_e32 v2, v165, v16
	global_store_dwordx4 v[14:15], v[10:13], off offset:2048
	v_lshl_or_b32 v18, v16, 9, v8
	s_nop 0
	v_mad_u64_u32 v[10:11], s[0:1], v2, s33, v[6:7]
	v_lshl_add_u64 v[10:11], v[10:11], 0, v[4:5]
	v_add_co_u32_e32 v10, vcc, s4, v10
	s_nop 1
	v_addc_co_u32_e32 v11, vcc, 0, v11, vcc
	global_load_dwordx4 v[10:13], v[10:11], off offset:2048
	s_waitcnt vmcnt(0)
	v_and_b32_e32 v24, 0xffff0000, v10
	v_lshlrev_b32_e32 v10, 16, v10
	v_mul_f32_e32 v14, 0xbfb8aa3b, v10
	v_mul_f32_e32 v15, 0xbfb8aa3b, v24
	v_exp_f32_e32 v14, v14
	v_exp_f32_e32 v15, v15
	v_and_b32_e32 v30, 0xffff0000, v12
	v_lshlrev_b32_e32 v12, 16, v12
	v_pk_add_f32 v[22:23], v[14:15], 1.0 op_sel_hi:[1,0]
	s_nop 0
	v_div_scale_f32 v25, s[0:1], v23, v23, v24
	v_rcp_f32_e32 v26, v25
	ds_read_b128 v[14:17], v18
	ds_read_b128 v[18:21], v18 offset:16
	v_fma_f32 v27, -v25, v26, 1.0
	v_fmac_f32_e32 v26, v27, v26
	v_div_scale_f32 v27, vcc, v24, v23, v24
	v_mul_f32_e32 v28, v27, v26
	v_fma_f32 v29, -v25, v28, v27
	v_fmac_f32_e32 v28, v29, v26
	v_fma_f32 v25, -v25, v28, v27
	v_div_scale_f32 v27, s[0:1], v22, v22, v10
	v_rcp_f32_e32 v29, v27
	v_div_fmas_f32 v25, v25, v26, v28
	v_div_fixup_f32 v23, v25, v23, v24
	v_mul_f32_e32 v25, 0xbfb8aa3b, v30
	v_fma_f32 v24, -v27, v29, 1.0
	v_fmac_f32_e32 v29, v24, v29
	v_mul_f32_e32 v24, 0xbfb8aa3b, v12
	v_exp_f32_e32 v24, v24
	v_exp_f32_e32 v25, v25
	v_div_scale_f32 v26, vcc, v10, v22, v10
	v_mul_f32_e32 v28, v26, v29
	v_fma_f32 v31, -v27, v28, v26
	v_fmac_f32_e32 v28, v31, v29
	v_pk_add_f32 v[24:25], v[24:25], 1.0 op_sel_hi:[1,0]
	v_fma_f32 v26, -v27, v28, v26
	v_div_scale_f32 v27, s[0:1], v25, v25, v30
	v_rcp_f32_e32 v31, v27
	v_div_fmas_f32 v26, v26, v29, v28
	v_div_fixup_f32 v22, v26, v22, v10
	s_waitcnt lgkmcnt(1)
; __device__ __forceinline__ float bf2f(unsigned short u) { return __uint_as_float(((unsigned)u) << 16); }
; __device__ __forceinline__ float silu_f(float z) { return z / (1.f + __expf(-z)); }
; __device__ void memx_item(const Params& p, int qblk, int hm, char* smem) {
;     ...
;     for (int i = 0; i < 8; ++i) {
;       const int c = i * 64 + lane, row = c >> 4, col8 = (c & 15) * 8;
;       const long tt = (long)qblk * 128 + 32 * rb + row; const int d = hm * 256 + dh * 128 + col8;
;       const f32x4 a0 = *reinterpret_cast<const f32x4*>(wl + row * 128 + col8), a1 = *reinterpret_cast<const f32x4*>(wl + row * 128 + col8 + 4);
;       const bf16x8 zv = ld8(p.P + tt * LDP + C_ZM + d);
;       float f[8];
; #pragma unroll
;       for (int j = 0; j < 4; ++j) { f[j] = a0[j] * silu_f(bf2f((unsigned short)zv[j])); f[4 + j] = a1[j] * silu_f(bf2f((unsigned short)zv[4 + j])); }
;       u32x4 w = {cvtpk(f[0], f[1]), cvtpk(f[2], f[3]), cvtpk(f[4], f[5]), cvtpk(f[6], f[7])};
;       *reinterpret_cast<u32x4*>(p.y + tt * DM + 3072 + d) = w;
;     }
	v_pk_mul_f32 v[14:15], v[14:15], v[22:23]
	v_fma_f32 v10, -v27, v31, 1.0
	v_fmac_f32_e32 v31, v10, v31
	v_div_scale_f32 v10, vcc, v30, v25, v30
	v_mul_f32_e32 v22, v10, v31
	v_fma_f32 v23, -v27, v22, v10
	v_fmac_f32_e32 v22, v23, v31
	v_div_scale_f32 v26, s[0:1], v24, v24, v12
	v_fma_f32 v10, -v27, v22, v10
	v_rcp_f32_e32 v27, v26
	v_div_fmas_f32 v10, v10, v31, v22
	v_div_fixup_f32 v23, v10, v25, v30
	v_and_b32_e32 v28, 0xffff0000, v11
	v_fma_f32 v10, -v26, v27, 1.0
	v_lshlrev_b32_e32 v29, 16, v11
	v_fmac_f32_e32 v27, v10, v27
	v_mul_f32_e32 v10, 0xbfb8aa3b, v29
	v_mul_f32_e32 v11, 0xbfb8aa3b, v28
	v_exp_f32_e32 v10, v10
	v_exp_f32_e32 v11, v11
	v_div_scale_f32 v22, vcc, v12, v24, v12
	v_mul_f32_e32 v25, v22, v27
	v_fma_f32 v30, -v26, v25, v22
	v_fmac_f32_e32 v25, v30, v27
	v_pk_add_f32 v[10:11], v[10:11], 1.0 op_sel_hi:[1,0]
	v_fma_f32 v22, -v26, v25, v22
	v_div_scale_f32 v26, s[0:1], v11, v11, v28
	v_rcp_f32_e32 v30, v26
	v_div_fmas_f32 v22, v22, v27, v25
	v_div_fixup_f32 v22, v22, v24, v12
	s_waitcnt lgkmcnt(0)
	v_pk_mul_f32 v[18:19], v[18:19], v[22:23]
	v_fma_f32 v12, -v26, v30, 1.0
	v_fmac_f32_e32 v30, v12, v30
	v_div_scale_f32 v12, vcc, v28, v11, v28
	v_mul_f32_e32 v22, v12, v30
	v_fma_f32 v23, -v26, v22, v12
	v_fmac_f32_e32 v22, v23, v30
	v_div_scale_f32 v23, s[0:1], v10, v10, v29
	v_rcp_f32_e32 v24, v23
	v_fma_f32 v12, -v26, v22, v12
	v_div_fmas_f32 v12, v12, v30, v22
	v_div_fixup_f32 v11, v12, v11, v28
	v_fma_f32 v12, -v23, v24, 1.0
	v_and_b32_e32 v26, 0xffff0000, v13
	v_lshlrev_b32_e32 v27, 16, v13
	v_fmac_f32_e32 v24, v12, v24
	v_mul_f32_e32 v12, 0xbfb8aa3b, v27
	v_mul_f32_e32 v13, 0xbfb8aa3b, v26
	v_exp_f32_e32 v12, v12
	v_exp_f32_e32 v13, v13
	v_div_scale_f32 v22, vcc, v29, v10, v29
	v_mul_f32_e32 v25, v22, v24
	v_fma_f32 v28, -v23, v25, v22
	v_fmac_f32_e32 v25, v28, v24
	v_pk_add_f32 v[12:13], v[12:13], 1.0 op_sel_hi:[1,0]
	v_fma_f32 v22, -v23, v25, v22
	v_div_scale_f32 v23, s[0:1], v13, v13, v26
	v_rcp_f32_e32 v28, v23
	v_div_fmas_f32 v22, v22, v24, v25
	v_div_fixup_f32 v10, v22, v10, v29
	v_pk_mul_f32 v[16:17], v[16:17], v[10:11]
	v_fma_f32 v10, -v23, v28, 1.0
	v_fmac_f32_e32 v28, v10, v28
	v_div_scale_f32 v10, vcc, v26, v13, v26
	v_mul_f32_e32 v11, v10, v28
	v_fma_f32 v22, -v23, v11, v10
	v_fmac_f32_e32 v11, v22, v28
	v_div_scale_f32 v22, s[0:1], v12, v12, v27
	v_fma_f32 v10, -v23, v11, v10
	v_rcp_f32_e32 v23, v22
	v_div_fmas_f32 v10, v10, v28, v11
	v_div_fixup_f32 v11, v10, v13, v26
	v_fma_f32 v10, -v22, v23, 1.0
	v_fmac_f32_e32 v23, v10, v23
	v_div_scale_f32 v10, vcc, v27, v12, v27
	v_mul_f32_e32 v13, v10, v23
	v_fma_f32 v24, -v22, v13, v10
	v_fmac_f32_e32 v13, v24, v23
	v_fma_f32 v10, -v22, v13, v10
	v_div_fmas_f32 v10, v10, v23, v13
	v_div_fixup_f32 v10, v10, v12, v27
	v_pk_mul_f32 v[20:21], v[20:21], v[10:11]
	v_cvt_pk_bf16_f32 v10, v14, v15
	v_lshlrev_b64 v[14:15], 13, v[2:3]
	v_lshl_add_u64 v[14:15], s[48:49], 0, v[14:15]
	v_lshl_add_u64 v[14:15], v[14:15], 0, v[4:5]
	v_cvt_pk_bf16_f32 v11, v16, v17
	v_add_co_u32_e32 v14, vcc, s2, v14
	v_or_b32_e32 v16, 8, v9
	v_cvt_pk_bf16_f32 v12, v18, v19
	v_cvt_pk_bf16_f32 v13, v20, v21
	v_addc_co_u32_e32 v15, vcc, 0, v15, vcc
	v_or_b32_e32 v2, v165, v16
	global_store_dwordx4 v[14:15], v[10:13], off offset:2048
	v_lshl_or_b32 v18, v16, 9, v8
	s_nop 0
	v_mad_u64_u32 v[10:11], s[0:1], v2, s33, v[6:7]
	v_lshl_add_u64 v[10:11], v[10:11], 0, v[4:5]
	v_add_co_u32_e32 v10, vcc, s4, v10
	s_nop 1
	v_addc_co_u32_e32 v11, vcc, 0, v11, vcc
	global_load_dwordx4 v[10:13], v[10:11], off offset:2048
	s_waitcnt vmcnt(0)
	v_and_b32_e32 v24, 0xffff0000, v10
	v_lshlrev_b32_e32 v10, 16, v10
	v_mul_f32_e32 v14, 0xbfb8aa3b, v10
	v_mul_f32_e32 v15, 0xbfb8aa3b, v24
	v_exp_f32_e32 v14, v14
	v_exp_f32_e32 v15, v15
	v_and_b32_e32 v30, 0xffff0000, v12
	v_lshlrev_b32_e32 v12, 16, v12
	v_pk_add_f32 v[22:23], v[14:15], 1.0 op_sel_hi:[1,0]
	s_nop 0
	v_div_scale_f32 v25, s[0:1], v23, v23, v24
	v_rcp_f32_e32 v26, v25
	ds_read_b128 v[14:17], v18
	ds_read_b128 v[18:21], v18 offset:16
	v_fma_f32 v27, -v25, v26, 1.0
	v_fmac_f32_e32 v26, v27, v26
	v_div_scale_f32 v27, vcc, v24, v23, v24
	v_mul_f32_e32 v28, v27, v26
	v_fma_f32 v29, -v25, v28, v27
	v_fmac_f32_e32 v28, v29, v26
	v_fma_f32 v25, -v25, v28, v27
	v_div_scale_f32 v27, s[0:1], v22, v22, v10
	v_rcp_f32_e32 v29, v27
	v_div_fmas_f32 v25, v25, v26, v28
	v_div_fixup_f32 v23, v25, v23, v24
	v_mul_f32_e32 v25, 0xbfb8aa3b, v30
	v_fma_f32 v24, -v27, v29, 1.0
	v_fmac_f32_e32 v29, v24, v29
	v_mul_f32_e32 v24, 0xbfb8aa3b, v12
	v_exp_f32_e32 v24, v24
	v_exp_f32_e32 v25, v25
	v_div_scale_f32 v26, vcc, v10, v22, v10
	v_mul_f32_e32 v28, v26, v29
	v_fma_f32 v31, -v27, v28, v26
	v_fmac_f32_e32 v28, v31, v29
	v_pk_add_f32 v[24:25], v[24:25], 1.0 op_sel_hi:[1,0]
	v_fma_f32 v26, -v27, v28, v26
	v_div_scale_f32 v27, s[0:1], v25, v25, v30
	v_rcp_f32_e32 v31, v27
	v_div_fmas_f32 v26, v26, v29, v28
	v_div_fixup_f32 v22, v26, v22, v10
	s_waitcnt lgkmcnt(1)
	v_pk_mul_f32 v[14:15], v[14:15], v[22:23]
	v_fma_f32 v10, -v27, v31, 1.0
	v_fmac_f32_e32 v31, v10, v31
	v_div_scale_f32 v10, vcc, v30, v25, v30
	v_mul_f32_e32 v22, v10, v31
	v_fma_f32 v23, -v27, v22, v10
	v_fmac_f32_e32 v22, v23, v31
	v_div_scale_f32 v26, s[0:1], v24, v24, v12
	v_fma_f32 v10, -v27, v22, v10
	v_rcp_f32_e32 v27, v26
	v_div_fmas_f32 v10, v10, v31, v22
	v_div_fixup_f32 v23, v10, v25, v30
	v_and_b32_e32 v28, 0xffff0000, v11
	v_fma_f32 v10, -v26, v27, 1.0
	v_lshlrev_b32_e32 v29, 16, v11
	v_fmac_f32_e32 v27, v10, v27
	v_mul_f32_e32 v10, 0xbfb8aa3b, v29
	v_mul_f32_e32 v11, 0xbfb8aa3b, v28
	v_exp_f32_e32 v10, v10
	v_exp_f32_e32 v11, v11
	v_div_scale_f32 v22, vcc, v12, v24, v12
	v_mul_f32_e32 v25, v22, v27
	v_fma_f32 v30, -v26, v25, v22
	v_fmac_f32_e32 v25, v30, v27
	v_pk_add_f32 v[10:11], v[10:11], 1.0 op_sel_hi:[1,0]
	v_fma_f32 v22, -v26, v25, v22
	v_div_scale_f32 v26, s[0:1], v11, v11, v28
	v_rcp_f32_e32 v30, v26
	v_div_fmas_f32 v22, v22, v27, v25
	v_div_fixup_f32 v22, v22, v24, v12
	s_waitcnt lgkmcnt(0)
; __device__ __forceinline__ float bf2f(unsigned short u) { return __uint_as_float(((unsigned)u) << 16); }
; __device__ __forceinline__ float silu_f(float z) { return z / (1.f + __expf(-z)); }
; __device__ void memx_item(const Params& p, int qblk, int hm, char* smem) {
;     ...
;     for (int i = 0; i < 8; ++i) {
;       const int c = i * 64 + lane, row = c >> 4, col8 = (c & 15) * 8;
;       const long tt = (long)qblk * 128 + 32 * rb + row; const int d = hm * 256 + dh * 128 + col8;
;       const f32x4 a0 = *reinterpret_cast<const f32x4*>(wl + row * 128 + col8), a1 = *reinterpret_cast<const f32x4*>(wl + row * 128 + col8 + 4);
;       const bf16x8 zv = ld8(p.P + tt * LDP + C_ZM + d);
;       float f[8];
; #pragma unroll
;       for (int j = 0; j < 4; ++j) { f[j] = a0[j] * silu_f(bf2f((unsigned short)zv[j])); f[4 + j] = a1[j] * silu_f(bf2f((unsigned short)zv[4 + j])); }
;       u32x4 w = {cvtpk(f[0], f[1]), cvtpk(f[2], f[3]), cvtpk(f[4], f[5]), cvtpk(f[6], f[7])};
;       *reinterpret_cast<u32x4*>(p.y + tt * DM + 3072 + d) = w;
;     }
	v_pk_mul_f32 v[18:19], v[18:19], v[22:23]
	v_fma_f32 v12, -v26, v30, 1.0
	v_fmac_f32_e32 v30, v12, v30
	v_div_scale_f32 v12, vcc, v28, v11, v28
	v_mul_f32_e32 v22, v12, v30
	v_fma_f32 v23, -v26, v22, v12
	v_fmac_f32_e32 v22, v23, v30
	v_div_scale_f32 v23, s[0:1], v10, v10, v29
	v_rcp_f32_e32 v24, v23
	v_fma_f32 v12, -v26, v22, v12
	v_div_fmas_f32 v12, v12, v30, v22
	v_div_fixup_f32 v11, v12, v11, v28
	v_fma_f32 v12, -v23, v24, 1.0
	v_and_b32_e32 v26, 0xffff0000, v13
	v_lshlrev_b32_e32 v27, 16, v13
	v_fmac_f32_e32 v24, v12, v24
	v_mul_f32_e32 v12, 0xbfb8aa3b, v27
	v_mul_f32_e32 v13, 0xbfb8aa3b, v26
	v_exp_f32_e32 v12, v12
	v_exp_f32_e32 v13, v13
	v_div_scale_f32 v22, vcc, v29, v10, v29
	v_mul_f32_e32 v25, v22, v24
	v_fma_f32 v28, -v23, v25, v22
	v_fmac_f32_e32 v25, v28, v24
	v_pk_add_f32 v[12:13], v[12:13], 1.0 op_sel_hi:[1,0]
	v_fma_f32 v22, -v23, v25, v22
	v_div_scale_f32 v23, s[0:1], v13, v13, v26
	v_rcp_f32_e32 v28, v23
	v_div_fmas_f32 v22, v22, v24, v25
	v_div_fixup_f32 v10, v22, v10, v29
	v_pk_mul_f32 v[16:17], v[16:17], v[10:11]
	v_fma_f32 v10, -v23, v28, 1.0
	v_fmac_f32_e32 v28, v10, v28
	v_div_scale_f32 v10, vcc, v26, v13, v26
	v_mul_f32_e32 v11, v10, v28
	v_fma_f32 v22, -v23, v11, v10
	v_fmac_f32_e32 v11, v22, v28
	v_div_scale_f32 v22, s[0:1], v12, v12, v27
	v_fma_f32 v10, -v23, v11, v10
	v_rcp_f32_e32 v23, v22
	v_div_fmas_f32 v10, v10, v28, v11
	v_div_fixup_f32 v11, v10, v13, v26
	v_fma_f32 v10, -v22, v23, 1.0
	v_fmac_f32_e32 v23, v10, v23
	v_div_scale_f32 v10, vcc, v27, v12, v27
	v_mul_f32_e32 v13, v10, v23
	v_fma_f32 v24, -v22, v13, v10
	v_fmac_f32_e32 v13, v24, v23
	v_fma_f32 v10, -v22, v13, v10
	v_div_fmas_f32 v10, v10, v23, v13
	v_div_fixup_f32 v10, v10, v12, v27
	v_pk_mul_f32 v[20:21], v[20:21], v[10:11]
	v_cvt_pk_bf16_f32 v10, v14, v15
	v_lshlrev_b64 v[14:15], 13, v[2:3]
	v_lshl_add_u64 v[14:15], s[48:49], 0, v[14:15]
	v_lshl_add_u64 v[14:15], v[14:15], 0, v[4:5]
	v_cvt_pk_bf16_f32 v11, v16, v17
	v_add_co_u32_e32 v14, vcc, s2, v14
	v_or_b32_e32 v16, 12, v9
	v_cvt_pk_bf16_f32 v12, v18, v19
	v_cvt_pk_bf16_f32 v13, v20, v21
	v_addc_co_u32_e32 v15, vcc, 0, v15, vcc
	v_or_b32_e32 v2, v165, v16
	global_store_dwordx4 v[14:15], v[10:13], off offset:2048
	v_lshl_or_b32 v18, v16, 9, v8
	s_nop 0
	v_mad_u64_u32 v[10:11], s[0:1], v2, s33, v[6:7]
	v_lshl_add_u64 v[10:11], v[10:11], 0, v[4:5]
	v_add_co_u32_e32 v10, vcc, s4, v10
	s_nop 1
	v_addc_co_u32_e32 v11, vcc, 0, v11, vcc
	global_load_dwordx4 v[10:13], v[10:11], off offset:2048
	s_waitcnt vmcnt(0)
	v_and_b32_e32 v24, 0xffff0000, v10
	v_lshlrev_b32_e32 v10, 16, v10
	v_mul_f32_e32 v14, 0xbfb8aa3b, v10
	v_mul_f32_e32 v15, 0xbfb8aa3b, v24
	v_exp_f32_e32 v14, v14
	v_exp_f32_e32 v15, v15
	v_and_b32_e32 v30, 0xffff0000, v12
	v_lshlrev_b32_e32 v12, 16, v12
	v_pk_add_f32 v[22:23], v[14:15], 1.0 op_sel_hi:[1,0]
	s_nop 0
	v_div_scale_f32 v25, s[0:1], v23, v23, v24
	v_rcp_f32_e32 v26, v25
	ds_read_b128 v[14:17], v18
	ds_read_b128 v[18:21], v18 offset:16
	v_fma_f32 v27, -v25, v26, 1.0
	v_fmac_f32_e32 v26, v27, v26
	v_div_scale_f32 v27, vcc, v24, v23, v24
	v_mul_f32_e32 v28, v27, v26
	v_fma_f32 v29, -v25, v28, v27
	v_fmac_f32_e32 v28, v29, v26
	v_fma_f32 v25, -v25, v28, v27
	v_div_scale_f32 v27, s[0:1], v22, v22, v10
	v_rcp_f32_e32 v29, v27
	v_div_fmas_f32 v25, v25, v26, v28
	v_div_fixup_f32 v23, v25, v23, v24
	v_mul_f32_e32 v25, 0xbfb8aa3b, v30
	v_fma_f32 v24, -v27, v29, 1.0
	v_fmac_f32_e32 v29, v24, v29
	v_mul_f32_e32 v24, 0xbfb8aa3b, v12
	v_exp_f32_e32 v24, v24
	v_exp_f32_e32 v25, v25
	v_div_scale_f32 v26, vcc, v10, v22, v10
	v_mul_f32_e32 v28, v26, v29
	v_fma_f32 v31, -v27, v28, v26
	v_fmac_f32_e32 v28, v31, v29
	v_pk_add_f32 v[24:25], v[24:25], 1.0 op_sel_hi:[1,0]
	v_fma_f32 v26, -v27, v28, v26
	v_div_scale_f32 v27, s[0:1], v25, v25, v30
	v_rcp_f32_e32 v31, v27
	v_div_fmas_f32 v26, v26, v29, v28
	v_div_fixup_f32 v22, v26, v22, v10
	s_waitcnt lgkmcnt(1)
	v_pk_mul_f32 v[14:15], v[14:15], v[22:23]
	v_fma_f32 v10, -v27, v31, 1.0
	v_fmac_f32_e32 v31, v10, v31
	v_div_scale_f32 v10, vcc, v30, v25, v30
	v_mul_f32_e32 v22, v10, v31
	v_fma_f32 v23, -v27, v22, v10
	v_fmac_f32_e32 v22, v23, v31
	v_div_scale_f32 v26, s[0:1], v24, v24, v12
	v_fma_f32 v10, -v27, v22, v10
	v_rcp_f32_e32 v27, v26
	v_div_fmas_f32 v10, v10, v31, v22
	v_div_fixup_f32 v23, v10, v25, v30
	v_and_b32_e32 v28, 0xffff0000, v11
	v_fma_f32 v10, -v26, v27, 1.0
	v_lshlrev_b32_e32 v29, 16, v11
	v_fmac_f32_e32 v27, v10, v27
	v_mul_f32_e32 v10, 0xbfb8aa3b, v29
	v_mul_f32_e32 v11, 0xbfb8aa3b, v28
	v_exp_f32_e32 v10, v10
	v_exp_f32_e32 v11, v11
	v_div_scale_f32 v22, vcc, v12, v24, v12
	v_mul_f32_e32 v25, v22, v27
	v_fma_f32 v30, -v26, v25, v22
	v_fmac_f32_e32 v25, v30, v27
	v_pk_add_f32 v[10:11], v[10:11], 1.0 op_sel_hi:[1,0]
	v_fma_f32 v22, -v26, v25, v22
	v_div_scale_f32 v26, s[0:1], v11, v11, v28
	v_rcp_f32_e32 v30, v26
	v_div_fmas_f32 v22, v22, v27, v25
	v_div_fixup_f32 v22, v22, v24, v12
	s_waitcnt lgkmcnt(0)
; __device__ __forceinline__ float bf2f(unsigned short u) { return __uint_as_float(((unsigned)u) << 16); }
; __device__ __forceinline__ float silu_f(float z) { return z / (1.f + __expf(-z)); }
; __device__ void memx_item(const Params& p, int qblk, int hm, char* smem) {
;     ...
;     for (int i = 0; i < 8; ++i) {
;       const int c = i * 64 + lane, row = c >> 4, col8 = (c & 15) * 8;
;       const long tt = (long)qblk * 128 + 32 * rb + row; const int d = hm * 256 + dh * 128 + col8;
;       const f32x4 a0 = *reinterpret_cast<const f32x4*>(wl + row * 128 + col8), a1 = *reinterpret_cast<const f32x4*>(wl + row * 128 + col8 + 4);
;       const bf16x8 zv = ld8(p.P + tt * LDP + C_ZM + d);
;       float f[8];
; #pragma unroll
;       for (int j = 0; j < 4; ++j) { f[j] = a0[j] * silu_f(bf2f((unsigned short)zv[j])); f[4 + j] = a1[j] * silu_f(bf2f((unsigned short)zv[4 + j])); }
;       u32x4 w = {cvtpk(f[0], f[1]), cvtpk(f[2], f[3]), cvtpk(f[4], f[5]), cvtpk(f[6], f[7])};
;       *reinterpret_cast<u32x4*>(p.y + tt * DM + 3072 + d) = w;
;     }
	v_pk_mul_f32 v[18:19], v[18:19], v[22:23]
	v_fma_f32 v12, -v26, v30, 1.0
	v_fmac_f32_e32 v30, v12, v30
	v_div_scale_f32 v12, vcc, v28, v11, v28
	v_mul_f32_e32 v22, v12, v30
	v_fma_f32 v23, -v26, v22, v12
	v_fmac_f32_e32 v22, v23, v30
	v_div_scale_f32 v23, s[0:1], v10, v10, v29
	v_rcp_f32_e32 v24, v23
	v_fma_f32 v12, -v26, v22, v12
	v_div_fmas_f32 v12, v12, v30, v22
	v_div_fixup_f32 v11, v12, v11, v28
	v_fma_f32 v12, -v23, v24, 1.0
	v_and_b32_e32 v26, 0xffff0000, v13
	v_lshlrev_b32_e32 v27, 16, v13
	v_fmac_f32_e32 v24, v12, v24
	v_mul_f32_e32 v12, 0xbfb8aa3b, v27
	v_mul_f32_e32 v13, 0xbfb8aa3b, v26
	v_exp_f32_e32 v12, v12
	v_exp_f32_e32 v13, v13
	v_div_scale_f32 v22, vcc, v29, v10, v29
	v_mul_f32_e32 v25, v22, v24
	v_fma_f32 v28, -v23, v25, v22
	v_fmac_f32_e32 v25, v28, v24
	v_pk_add_f32 v[12:13], v[12:13], 1.0 op_sel_hi:[1,0]
	v_fma_f32 v22, -v23, v25, v22
	v_div_scale_f32 v23, s[0:1], v13, v13, v26
	v_rcp_f32_e32 v28, v23
	v_div_fmas_f32 v22, v22, v24, v25
	v_div_fixup_f32 v10, v22, v10, v29
	v_pk_mul_f32 v[16:17], v[16:17], v[10:11]
	v_fma_f32 v10, -v23, v28, 1.0
	v_fmac_f32_e32 v28, v10, v28
	v_div_scale_f32 v10, vcc, v26, v13, v26
	v_mul_f32_e32 v11, v10, v28
	v_fma_f32 v22, -v23, v11, v10
	v_fmac_f32_e32 v11, v22, v28
	v_div_scale_f32 v22, s[0:1], v12, v12, v27
	v_fma_f32 v10, -v23, v11, v10
	v_rcp_f32_e32 v23, v22
	v_div_fmas_f32 v10, v10, v28, v11
	v_div_fixup_f32 v11, v10, v13, v26
	v_fma_f32 v10, -v22, v23, 1.0
	v_fmac_f32_e32 v23, v10, v23
	v_div_scale_f32 v10, vcc, v27, v12, v27
	v_mul_f32_e32 v13, v10, v23
	v_fma_f32 v24, -v22, v13, v10
	v_fmac_f32_e32 v13, v24, v23
	v_fma_f32 v10, -v22, v13, v10
	v_div_fmas_f32 v10, v10, v23, v13
	v_div_fixup_f32 v10, v10, v12, v27
	v_pk_mul_f32 v[20:21], v[20:21], v[10:11]
	v_cvt_pk_bf16_f32 v10, v14, v15
	v_lshlrev_b64 v[14:15], 13, v[2:3]
	v_lshl_add_u64 v[14:15], s[48:49], 0, v[14:15]
	v_lshl_add_u64 v[14:15], v[14:15], 0, v[4:5]
	v_cvt_pk_bf16_f32 v11, v16, v17
	v_add_co_u32_e32 v14, vcc, s2, v14
	v_or_b32_e32 v16, 16, v9
	v_cvt_pk_bf16_f32 v12, v18, v19
	v_cvt_pk_bf16_f32 v13, v20, v21
	v_addc_co_u32_e32 v15, vcc, 0, v15, vcc
	v_or_b32_e32 v2, v165, v16
	global_store_dwordx4 v[14:15], v[10:13], off offset:2048
	v_lshl_or_b32 v18, v16, 9, v8
	s_nop 0
	v_mad_u64_u32 v[10:11], s[0:1], v2, s33, v[6:7]
	v_lshl_add_u64 v[10:11], v[10:11], 0, v[4:5]
	v_add_co_u32_e32 v10, vcc, s4, v10
	s_nop 1
	v_addc_co_u32_e32 v11, vcc, 0, v11, vcc
	global_load_dwordx4 v[10:13], v[10:11], off offset:2048
	s_waitcnt vmcnt(0)
	v_and_b32_e32 v24, 0xffff0000, v10
	v_lshlrev_b32_e32 v10, 16, v10
	v_mul_f32_e32 v14, 0xbfb8aa3b, v10
	v_mul_f32_e32 v15, 0xbfb8aa3b, v24
	v_exp_f32_e32 v14, v14
	v_exp_f32_e32 v15, v15
	v_and_b32_e32 v30, 0xffff0000, v12
	v_lshlrev_b32_e32 v12, 16, v12
	v_pk_add_f32 v[22:23], v[14:15], 1.0 op_sel_hi:[1,0]
	s_nop 0
	v_div_scale_f32 v25, s[0:1], v23, v23, v24
	v_rcp_f32_e32 v26, v25
	ds_read_b128 v[14:17], v18
	ds_read_b128 v[18:21], v18 offset:16
	v_fma_f32 v27, -v25, v26, 1.0
	v_fmac_f32_e32 v26, v27, v26
	v_div_scale_f32 v27, vcc, v24, v23, v24
	v_mul_f32_e32 v28, v27, v26
	v_fma_f32 v29, -v25, v28, v27
	v_fmac_f32_e32 v28, v29, v26
	v_fma_f32 v25, -v25, v28, v27
	v_div_scale_f32 v27, s[0:1], v22, v22, v10
	v_rcp_f32_e32 v29, v27
	v_div_fmas_f32 v25, v25, v26, v28
	v_div_fixup_f32 v23, v25, v23, v24
	v_mul_f32_e32 v25, 0xbfb8aa3b, v30
	v_fma_f32 v24, -v27, v29, 1.0
	v_fmac_f32_e32 v29, v24, v29
	v_mul_f32_e32 v24, 0xbfb8aa3b, v12
	v_exp_f32_e32 v24, v24
	v_exp_f32_e32 v25, v25
	v_div_scale_f32 v26, vcc, v10, v22, v10
	v_mul_f32_e32 v28, v26, v29
	v_fma_f32 v31, -v27, v28, v26
	v_fmac_f32_e32 v28, v31, v29
	v_pk_add_f32 v[24:25], v[24:25], 1.0 op_sel_hi:[1,0]
	v_fma_f32 v26, -v27, v28, v26
	v_div_scale_f32 v27, s[0:1], v25, v25, v30
	v_rcp_f32_e32 v31, v27
	v_div_fmas_f32 v26, v26, v29, v28
	v_div_fixup_f32 v22, v26, v22, v10
	s_waitcnt lgkmcnt(1)
	v_pk_mul_f32 v[14:15], v[14:15], v[22:23]
	v_fma_f32 v10, -v27, v31, 1.0
	v_fmac_f32_e32 v31, v10, v31
	v_div_scale_f32 v10, vcc, v30, v25, v30
	v_mul_f32_e32 v22, v10, v31
	v_fma_f32 v23, -v27, v22, v10
	v_fmac_f32_e32 v22, v23, v31
	v_div_scale_f32 v26, s[0:1], v24, v24, v12
	v_fma_f32 v10, -v27, v22, v10
	v_rcp_f32_e32 v27, v26
	v_div_fmas_f32 v10, v10, v31, v22
	v_div_fixup_f32 v23, v10, v25, v30
	v_and_b32_e32 v28, 0xffff0000, v11
	v_fma_f32 v10, -v26, v27, 1.0
	v_lshlrev_b32_e32 v29, 16, v11
	v_fmac_f32_e32 v27, v10, v27
	v_mul_f32_e32 v10, 0xbfb8aa3b, v29
	v_mul_f32_e32 v11, 0xbfb8aa3b, v28
	v_exp_f32_e32 v10, v10
	v_exp_f32_e32 v11, v11
	v_div_scale_f32 v22, vcc, v12, v24, v12
	v_mul_f32_e32 v25, v22, v27
	v_fma_f32 v30, -v26, v25, v22
	v_fmac_f32_e32 v25, v30, v27
	v_pk_add_f32 v[10:11], v[10:11], 1.0 op_sel_hi:[1,0]
	v_fma_f32 v22, -v26, v25, v22
	v_div_scale_f32 v26, s[0:1], v11, v11, v28
	v_rcp_f32_e32 v30, v26
	v_div_fmas_f32 v22, v22, v27, v25
	v_div_fixup_f32 v22, v22, v24, v12
	s_waitcnt lgkmcnt(0)
; __device__ __forceinline__ float bf2f(unsigned short u) { return __uint_as_float(((unsigned)u) << 16); }
; __device__ __forceinline__ float silu_f(float z) { return z / (1.f + __expf(-z)); }
; __device__ void memx_item(const Params& p, int qblk, int hm, char* smem) {
;     ...
;     for (int i = 0; i < 8; ++i) {
;       const int c = i * 64 + lane, row = c >> 4, col8 = (c & 15) * 8;
;       const long tt = (long)qblk * 128 + 32 * rb + row; const int d = hm * 256 + dh * 128 + col8;
;       const f32x4 a0 = *reinterpret_cast<const f32x4*>(wl + row * 128 + col8), a1 = *reinterpret_cast<const f32x4*>(wl + row * 128 + col8 + 4);
;       const bf16x8 zv = ld8(p.P + tt * LDP + C_ZM + d);
;       float f[8];
; #pragma unroll
;       for (int j = 0; j < 4; ++j) { f[j] = a0[j] * silu_f(bf2f((unsigned short)zv[j])); f[4 + j] = a1[j] * silu_f(bf2f((unsigned short)zv[4 + j])); }
;       u32x4 w = {cvtpk(f[0], f[1]), cvtpk(f[2], f[3]), cvtpk(f[4], f[5]), cvtpk(f[6], f[7])};
;       *reinterpret_cast<u32x4*>(p.y + tt * DM + 3072 + d) = w;
;     }
	v_pk_mul_f32 v[18:19], v[18:19], v[22:23]
	v_fma_f32 v12, -v26, v30, 1.0
	v_fmac_f32_e32 v30, v12, v30
	v_div_scale_f32 v12, vcc, v28, v11, v28
	v_mul_f32_e32 v22, v12, v30
	v_fma_f32 v23, -v26, v22, v12
	v_fmac_f32_e32 v22, v23, v30
	v_div_scale_f32 v23, s[0:1], v10, v10, v29
	v_rcp_f32_e32 v24, v23
	v_fma_f32 v12, -v26, v22, v12
	v_div_fmas_f32 v12, v12, v30, v22
	v_div_fixup_f32 v11, v12, v11, v28
	v_fma_f32 v12, -v23, v24, 1.0
	v_and_b32_e32 v26, 0xffff0000, v13
	v_lshlrev_b32_e32 v27, 16, v13
	v_fmac_f32_e32 v24, v12, v24
	v_mul_f32_e32 v12, 0xbfb8aa3b, v27
	v_mul_f32_e32 v13, 0xbfb8aa3b, v26
	v_exp_f32_e32 v12, v12
	v_exp_f32_e32 v13, v13
	v_div_scale_f32 v22, vcc, v29, v10, v29
	v_mul_f32_e32 v25, v22, v24
	v_fma_f32 v28, -v23, v25, v22
	v_fmac_f32_e32 v25, v28, v24
	v_pk_add_f32 v[12:13], v[12:13], 1.0 op_sel_hi:[1,0]
	v_fma_f32 v22, -v23, v25, v22
	v_div_scale_f32 v23, s[0:1], v13, v13, v26
	v_rcp_f32_e32 v28, v23
	v_div_fmas_f32 v22, v22, v24, v25
	v_div_fixup_f32 v10, v22, v10, v29
	v_pk_mul_f32 v[16:17], v[16:17], v[10:11]
	v_fma_f32 v10, -v23, v28, 1.0
	v_fmac_f32_e32 v28, v10, v28
	v_div_scale_f32 v10, vcc, v26, v13, v26
	v_mul_f32_e32 v11, v10, v28
	v_fma_f32 v22, -v23, v11, v10
	v_fmac_f32_e32 v11, v22, v28
	v_div_scale_f32 v22, s[0:1], v12, v12, v27
	v_fma_f32 v10, -v23, v11, v10
	v_rcp_f32_e32 v23, v22
	v_div_fmas_f32 v10, v10, v28, v11
	v_div_fixup_f32 v11, v10, v13, v26
	v_fma_f32 v10, -v22, v23, 1.0
	v_fmac_f32_e32 v23, v10, v23
	v_div_scale_f32 v10, vcc, v27, v12, v27
	v_mul_f32_e32 v13, v10, v23
	v_fma_f32 v24, -v22, v13, v10
	v_fmac_f32_e32 v13, v24, v23
	v_fma_f32 v10, -v22, v13, v10
	v_div_fmas_f32 v10, v10, v23, v13
	v_div_fixup_f32 v10, v10, v12, v27
	v_pk_mul_f32 v[20:21], v[20:21], v[10:11]
	v_cvt_pk_bf16_f32 v10, v14, v15
	v_lshlrev_b64 v[14:15], 13, v[2:3]
	v_lshl_add_u64 v[14:15], s[48:49], 0, v[14:15]
	v_lshl_add_u64 v[14:15], v[14:15], 0, v[4:5]
	v_cvt_pk_bf16_f32 v11, v16, v17
	v_add_co_u32_e32 v14, vcc, s2, v14
	v_or_b32_e32 v16, 20, v9
	v_cvt_pk_bf16_f32 v12, v18, v19
	v_cvt_pk_bf16_f32 v13, v20, v21
	v_addc_co_u32_e32 v15, vcc, 0, v15, vcc
	v_or_b32_e32 v2, v165, v16
	global_store_dwordx4 v[14:15], v[10:13], off offset:2048
	v_lshl_or_b32 v18, v16, 9, v8
	s_nop 0
	v_mad_u64_u32 v[10:11], s[0:1], v2, s33, v[6:7]
	v_lshl_add_u64 v[10:11], v[10:11], 0, v[4:5]
	v_add_co_u32_e32 v10, vcc, s4, v10
	s_nop 1
	v_addc_co_u32_e32 v11, vcc, 0, v11, vcc
	global_load_dwordx4 v[10:13], v[10:11], off offset:2048
	s_waitcnt vmcnt(0)
	v_and_b32_e32 v24, 0xffff0000, v10
	v_lshlrev_b32_e32 v10, 16, v10
	v_mul_f32_e32 v14, 0xbfb8aa3b, v10
	v_mul_f32_e32 v15, 0xbfb8aa3b, v24
	v_exp_f32_e32 v14, v14
	v_exp_f32_e32 v15, v15
	v_and_b32_e32 v30, 0xffff0000, v12
	v_lshlrev_b32_e32 v12, 16, v12
	v_pk_add_f32 v[22:23], v[14:15], 1.0 op_sel_hi:[1,0]
	s_nop 0
	v_div_scale_f32 v25, s[0:1], v23, v23, v24
	v_rcp_f32_e32 v26, v25
	ds_read_b128 v[14:17], v18
	ds_read_b128 v[18:21], v18 offset:16
	v_fma_f32 v27, -v25, v26, 1.0
	v_fmac_f32_e32 v26, v27, v26
	v_div_scale_f32 v27, vcc, v24, v23, v24
	v_mul_f32_e32 v28, v27, v26
	v_fma_f32 v29, -v25, v28, v27
	v_fmac_f32_e32 v28, v29, v26
	v_fma_f32 v25, -v25, v28, v27
	v_div_scale_f32 v27, s[0:1], v22, v22, v10
	v_rcp_f32_e32 v29, v27
	v_div_fmas_f32 v25, v25, v26, v28
	v_div_fixup_f32 v23, v25, v23, v24
	v_mul_f32_e32 v25, 0xbfb8aa3b, v30
	v_fma_f32 v24, -v27, v29, 1.0
	v_fmac_f32_e32 v29, v24, v29
	v_mul_f32_e32 v24, 0xbfb8aa3b, v12
	v_exp_f32_e32 v24, v24
	v_exp_f32_e32 v25, v25
	v_div_scale_f32 v26, vcc, v10, v22, v10
	v_mul_f32_e32 v28, v26, v29
	v_fma_f32 v31, -v27, v28, v26
	v_fmac_f32_e32 v28, v31, v29
	v_pk_add_f32 v[24:25], v[24:25], 1.0 op_sel_hi:[1,0]
	v_fma_f32 v26, -v27, v28, v26
	v_div_scale_f32 v27, s[0:1], v25, v25, v30
	v_rcp_f32_e32 v31, v27
	v_div_fmas_f32 v26, v26, v29, v28
	v_div_fixup_f32 v22, v26, v22, v10
	s_waitcnt lgkmcnt(1)
	v_pk_mul_f32 v[14:15], v[14:15], v[22:23]
	v_fma_f32 v10, -v27, v31, 1.0
	v_fmac_f32_e32 v31, v10, v31
	v_div_scale_f32 v10, vcc, v30, v25, v30
	v_mul_f32_e32 v22, v10, v31
	v_fma_f32 v23, -v27, v22, v10
	v_fmac_f32_e32 v22, v23, v31
	v_div_scale_f32 v26, s[0:1], v24, v24, v12
	v_fma_f32 v10, -v27, v22, v10
	v_rcp_f32_e32 v27, v26
	v_div_fmas_f32 v10, v10, v31, v22
	v_div_fixup_f32 v23, v10, v25, v30
	v_and_b32_e32 v28, 0xffff0000, v11
	v_fma_f32 v10, -v26, v27, 1.0
	v_lshlrev_b32_e32 v29, 16, v11
	v_fmac_f32_e32 v27, v10, v27
	v_mul_f32_e32 v10, 0xbfb8aa3b, v29
	v_mul_f32_e32 v11, 0xbfb8aa3b, v28
	v_exp_f32_e32 v10, v10
	v_exp_f32_e32 v11, v11
	v_div_scale_f32 v22, vcc, v12, v24, v12
	v_mul_f32_e32 v25, v22, v27
	v_fma_f32 v30, -v26, v25, v22
	v_fmac_f32_e32 v25, v30, v27
	v_pk_add_f32 v[10:11], v[10:11], 1.0 op_sel_hi:[1,0]
	v_fma_f32 v22, -v26, v25, v22
	v_div_scale_f32 v26, s[0:1], v11, v11, v28
	v_rcp_f32_e32 v30, v26
	v_div_fmas_f32 v22, v22, v27, v25
	v_div_fixup_f32 v22, v22, v24, v12
	s_waitcnt lgkmcnt(0)
; __device__ __forceinline__ float bf2f(unsigned short u) { return __uint_as_float(((unsigned)u) << 16); }
; __device__ __forceinline__ float silu_f(float z) { return z / (1.f + __expf(-z)); }
; __device__ void memx_item(const Params& p, int qblk, int hm, char* smem) {
;     ...
;     for (int i = 0; i < 8; ++i) {
;       const int c = i * 64 + lane, row = c >> 4, col8 = (c & 15) * 8;
;       const long tt = (long)qblk * 128 + 32 * rb + row; const int d = hm * 256 + dh * 128 + col8;
;       const f32x4 a0 = *reinterpret_cast<const f32x4*>(wl + row * 128 + col8), a1 = *reinterpret_cast<const f32x4*>(wl + row * 128 + col8 + 4);
;       const bf16x8 zv = ld8(p.P + tt * LDP + C_ZM + d);
;       float f[8];
; #pragma unroll
;       for (int j = 0; j < 4; ++j) { f[j] = a0[j] * silu_f(bf2f((unsigned short)zv[j])); f[4 + j] = a1[j] * silu_f(bf2f((unsigned short)zv[4 + j])); }
;       u32x4 w = {cvtpk(f[0], f[1]), cvtpk(f[2], f[3]), cvtpk(f[4], f[5]), cvtpk(f[6], f[7])};
;       *reinterpret_cast<u32x4*>(p.y + tt * DM + 3072 + d) = w;
;     }
	v_pk_mul_f32 v[18:19], v[18:19], v[22:23]
	v_fma_f32 v12, -v26, v30, 1.0
	v_fmac_f32_e32 v30, v12, v30
	v_div_scale_f32 v12, vcc, v28, v11, v28
	v_mul_f32_e32 v22, v12, v30
	v_fma_f32 v23, -v26, v22, v12
	v_fmac_f32_e32 v22, v23, v30
	v_div_scale_f32 v23, s[0:1], v10, v10, v29
	v_rcp_f32_e32 v24, v23
	v_fma_f32 v12, -v26, v22, v12
	v_div_fmas_f32 v12, v12, v30, v22
	v_div_fixup_f32 v11, v12, v11, v28
	v_fma_f32 v12, -v23, v24, 1.0
	v_and_b32_e32 v26, 0xffff0000, v13
	v_lshlrev_b32_e32 v27, 16, v13
	v_fmac_f32_e32 v24, v12, v24
	v_mul_f32_e32 v12, 0xbfb8aa3b, v27
	v_mul_f32_e32 v13, 0xbfb8aa3b, v26
	v_exp_f32_e32 v12, v12
	v_exp_f32_e32 v13, v13
	v_div_scale_f32 v22, vcc, v29, v10, v29
	v_mul_f32_e32 v25, v22, v24
	v_fma_f32 v28, -v23, v25, v22
	v_fmac_f32_e32 v25, v28, v24
	v_pk_add_f32 v[12:13], v[12:13], 1.0 op_sel_hi:[1,0]
	v_fma_f32 v22, -v23, v25, v22
	v_div_scale_f32 v23, s[0:1], v13, v13, v26
	v_rcp_f32_e32 v28, v23
	v_div_fmas_f32 v22, v22, v24, v25
	v_div_fixup_f32 v10, v22, v10, v29
	v_pk_mul_f32 v[16:17], v[16:17], v[10:11]
	v_fma_f32 v10, -v23, v28, 1.0
	v_fmac_f32_e32 v28, v10, v28
	v_div_scale_f32 v10, vcc, v26, v13, v26
	v_mul_f32_e32 v11, v10, v28
	v_fma_f32 v22, -v23, v11, v10
	v_fmac_f32_e32 v11, v22, v28
	v_div_scale_f32 v22, s[0:1], v12, v12, v27
	v_fma_f32 v10, -v23, v11, v10
	v_rcp_f32_e32 v23, v22
	v_div_fmas_f32 v10, v10, v28, v11
	v_div_fixup_f32 v11, v10, v13, v26
	v_fma_f32 v10, -v22, v23, 1.0
	v_fmac_f32_e32 v23, v10, v23
	v_div_scale_f32 v10, vcc, v27, v12, v27
	v_mul_f32_e32 v13, v10, v23
	v_fma_f32 v24, -v22, v13, v10
	v_fmac_f32_e32 v13, v24, v23
	v_fma_f32 v10, -v22, v13, v10
	v_div_fmas_f32 v10, v10, v23, v13
	v_div_fixup_f32 v10, v10, v12, v27
	v_pk_mul_f32 v[20:21], v[20:21], v[10:11]
	v_cvt_pk_bf16_f32 v10, v14, v15
	v_lshlrev_b64 v[14:15], 13, v[2:3]
	v_lshl_add_u64 v[14:15], s[48:49], 0, v[14:15]
	v_lshl_add_u64 v[14:15], v[14:15], 0, v[4:5]
	v_cvt_pk_bf16_f32 v11, v16, v17
	v_add_co_u32_e32 v14, vcc, s2, v14
	v_or_b32_e32 v16, 24, v9
	v_cvt_pk_bf16_f32 v12, v18, v19
	v_cvt_pk_bf16_f32 v13, v20, v21
	v_addc_co_u32_e32 v15, vcc, 0, v15, vcc
	v_or_b32_e32 v2, v165, v16
	global_store_dwordx4 v[14:15], v[10:13], off offset:2048
	v_lshl_or_b32 v18, v16, 9, v8
	v_or_b32_e32 v9, 28, v9
	v_mad_u64_u32 v[10:11], s[0:1], v2, s33, v[6:7]
	v_lshl_add_u64 v[10:11], v[10:11], 0, v[4:5]
	v_add_co_u32_e32 v10, vcc, s4, v10
	s_nop 1
	v_addc_co_u32_e32 v11, vcc, 0, v11, vcc
	global_load_dwordx4 v[10:13], v[10:11], off offset:2048
	s_waitcnt vmcnt(0)
	v_and_b32_e32 v24, 0xffff0000, v10
	v_lshlrev_b32_e32 v10, 16, v10
	v_mul_f32_e32 v14, 0xbfb8aa3b, v10
	v_mul_f32_e32 v15, 0xbfb8aa3b, v24
	v_exp_f32_e32 v14, v14
	v_exp_f32_e32 v15, v15
	v_and_b32_e32 v30, 0xffff0000, v12
	v_lshlrev_b32_e32 v12, 16, v12
	v_pk_add_f32 v[22:23], v[14:15], 1.0 op_sel_hi:[1,0]
	s_nop 0
	v_div_scale_f32 v25, s[0:1], v23, v23, v24
	v_rcp_f32_e32 v26, v25
	ds_read_b128 v[14:17], v18
	ds_read_b128 v[18:21], v18 offset:16
	v_fma_f32 v27, -v25, v26, 1.0
	v_fmac_f32_e32 v26, v27, v26
	v_div_scale_f32 v27, vcc, v24, v23, v24
	v_mul_f32_e32 v28, v27, v26
	v_fma_f32 v29, -v25, v28, v27
	v_fmac_f32_e32 v28, v29, v26
	v_fma_f32 v25, -v25, v28, v27
	v_div_scale_f32 v27, s[0:1], v22, v22, v10
	v_rcp_f32_e32 v29, v27
	v_div_fmas_f32 v25, v25, v26, v28
	v_div_fixup_f32 v23, v25, v23, v24
	v_mul_f32_e32 v25, 0xbfb8aa3b, v30
	v_fma_f32 v24, -v27, v29, 1.0
	v_fmac_f32_e32 v29, v24, v29
	v_mul_f32_e32 v24, 0xbfb8aa3b, v12
	v_exp_f32_e32 v24, v24
	v_exp_f32_e32 v25, v25
	v_div_scale_f32 v26, vcc, v10, v22, v10
	v_mul_f32_e32 v28, v26, v29
	v_fma_f32 v31, -v27, v28, v26
	v_fmac_f32_e32 v28, v31, v29
	v_pk_add_f32 v[24:25], v[24:25], 1.0 op_sel_hi:[1,0]
	v_fma_f32 v26, -v27, v28, v26
	v_div_scale_f32 v27, s[0:1], v25, v25, v30
	v_rcp_f32_e32 v31, v27
	v_div_fmas_f32 v26, v26, v29, v28
	v_div_fixup_f32 v22, v26, v22, v10
	s_waitcnt lgkmcnt(1)
	v_pk_mul_f32 v[14:15], v[14:15], v[22:23]
	v_fma_f32 v10, -v27, v31, 1.0
	v_fmac_f32_e32 v31, v10, v31
	v_div_scale_f32 v10, vcc, v30, v25, v30
	v_mul_f32_e32 v22, v10, v31
	v_fma_f32 v23, -v27, v22, v10
	v_fmac_f32_e32 v22, v23, v31
	v_div_scale_f32 v26, s[0:1], v24, v24, v12
	v_fma_f32 v10, -v27, v22, v10
	v_rcp_f32_e32 v27, v26
	v_div_fmas_f32 v10, v10, v31, v22
	v_div_fixup_f32 v23, v10, v25, v30
	v_and_b32_e32 v28, 0xffff0000, v11
	v_fma_f32 v10, -v26, v27, 1.0
	v_lshlrev_b32_e32 v29, 16, v11
	v_fmac_f32_e32 v27, v10, v27
	v_mul_f32_e32 v10, 0xbfb8aa3b, v29
	v_mul_f32_e32 v11, 0xbfb8aa3b, v28
	v_exp_f32_e32 v10, v10
	v_exp_f32_e32 v11, v11
	v_div_scale_f32 v22, vcc, v12, v24, v12
	v_mul_f32_e32 v25, v22, v27
	v_fma_f32 v30, -v26, v25, v22
	v_fmac_f32_e32 v25, v30, v27
	v_pk_add_f32 v[10:11], v[10:11], 1.0 op_sel_hi:[1,0]
	v_fma_f32 v22, -v26, v25, v22
	v_div_scale_f32 v26, s[0:1], v11, v11, v28
	v_rcp_f32_e32 v30, v26
	v_div_fmas_f32 v22, v22, v27, v25
	v_div_fixup_f32 v22, v22, v24, v12
	s_waitcnt lgkmcnt(0)
; __device__ __forceinline__ float bf2f(unsigned short u) { return __uint_as_float(((unsigned)u) << 16); }
; __device__ __forceinline__ float silu_f(float z) { return z / (1.f + __expf(-z)); }
; __device__ void memx_item(const Params& p, int qblk, int hm, char* smem) {
;     ...
;     for (int i = 0; i < 8; ++i) {
;       const int c = i * 64 + lane, row = c >> 4, col8 = (c & 15) * 8;
;       const long tt = (long)qblk * 128 + 32 * rb + row; const int d = hm * 256 + dh * 128 + col8;
;       const f32x4 a0 = *reinterpret_cast<const f32x4*>(wl + row * 128 + col8), a1 = *reinterpret_cast<const f32x4*>(wl + row * 128 + col8 + 4);
;       const bf16x8 zv = ld8(p.P + tt * LDP + C_ZM + d);
;       float f[8];
; #pragma unroll
;       for (int j = 0; j < 4; ++j) { f[j] = a0[j] * silu_f(bf2f((unsigned short)zv[j])); f[4 + j] = a1[j] * silu_f(bf2f((unsigned short)zv[4 + j])); }
;       u32x4 w = {cvtpk(f[0], f[1]), cvtpk(f[2], f[3]), cvtpk(f[4], f[5]), cvtpk(f[6], f[7])};
;       *reinterpret_cast<u32x4*>(p.y + tt * DM + 3072 + d) = w;
;     }
	v_pk_mul_f32 v[18:19], v[18:19], v[22:23]
	v_fma_f32 v12, -v26, v30, 1.0
	v_fmac_f32_e32 v30, v12, v30
	v_div_scale_f32 v12, vcc, v28, v11, v28
	v_mul_f32_e32 v22, v12, v30
	v_fma_f32 v23, -v26, v22, v12
	v_fmac_f32_e32 v22, v23, v30
	v_div_scale_f32 v23, s[0:1], v10, v10, v29
	v_rcp_f32_e32 v24, v23
	v_fma_f32 v12, -v26, v22, v12
	v_div_fmas_f32 v12, v12, v30, v22
	v_div_fixup_f32 v11, v12, v11, v28
	v_fma_f32 v12, -v23, v24, 1.0
	v_and_b32_e32 v26, 0xffff0000, v13
	v_lshlrev_b32_e32 v27, 16, v13
	v_fmac_f32_e32 v24, v12, v24
	v_mul_f32_e32 v12, 0xbfb8aa3b, v27
	v_mul_f32_e32 v13, 0xbfb8aa3b, v26
	v_exp_f32_e32 v12, v12
	v_exp_f32_e32 v13, v13
	v_div_scale_f32 v22, vcc, v29, v10, v29
	v_mul_f32_e32 v25, v22, v24
	v_fma_f32 v28, -v23, v25, v22
	v_fmac_f32_e32 v25, v28, v24
	v_pk_add_f32 v[12:13], v[12:13], 1.0 op_sel_hi:[1,0]
	v_fma_f32 v22, -v23, v25, v22
	v_div_scale_f32 v23, s[0:1], v13, v13, v26
	v_rcp_f32_e32 v28, v23
	v_div_fmas_f32 v22, v22, v24, v25
	v_div_fixup_f32 v10, v22, v10, v29
	v_pk_mul_f32 v[16:17], v[16:17], v[10:11]
	v_fma_f32 v10, -v23, v28, 1.0
	v_fmac_f32_e32 v28, v10, v28
	v_div_scale_f32 v10, vcc, v26, v13, v26
	v_mul_f32_e32 v11, v10, v28
	v_fma_f32 v22, -v23, v11, v10
	v_fmac_f32_e32 v11, v22, v28
	v_div_scale_f32 v22, s[0:1], v12, v12, v27
	v_fma_f32 v10, -v23, v11, v10
	v_rcp_f32_e32 v23, v22
	v_div_fmas_f32 v10, v10, v28, v11
	v_div_fixup_f32 v11, v10, v13, v26
	v_fma_f32 v10, -v22, v23, 1.0
	v_fmac_f32_e32 v23, v10, v23
	v_div_scale_f32 v10, vcc, v27, v12, v27
	v_mul_f32_e32 v13, v10, v23
	v_fma_f32 v24, -v22, v13, v10
	v_fmac_f32_e32 v13, v24, v23
	v_fma_f32 v10, -v22, v13, v10
	v_div_fmas_f32 v10, v10, v23, v13
	v_div_fixup_f32 v10, v10, v12, v27
	v_pk_mul_f32 v[20:21], v[20:21], v[10:11]
	v_cvt_pk_bf16_f32 v10, v14, v15
	v_lshlrev_b64 v[14:15], 13, v[2:3]
	v_lshl_add_u64 v[14:15], s[48:49], 0, v[14:15]
	v_lshl_add_u64 v[14:15], v[14:15], 0, v[4:5]
	v_or_b32_e32 v2, v165, v9
	v_add_co_u32_e32 v14, vcc, s2, v14
	v_mad_u64_u32 v[6:7], s[0:1], v2, s33, v[6:7]
	s_nop 0
	v_addc_co_u32_e32 v15, vcc, 0, v15, vcc
	v_lshl_add_u64 v[6:7], v[6:7], 0, v[4:5]
	v_cvt_pk_bf16_f32 v11, v16, v17
	v_cvt_pk_bf16_f32 v12, v18, v19
	v_cvt_pk_bf16_f32 v13, v20, v21
	v_add_co_u32_e32 v6, vcc, s4, v6
	global_store_dwordx4 v[14:15], v[10:13], off offset:2048
	s_nop 0
	v_addc_co_u32_e32 v7, vcc, 0, v7, vcc
	global_load_dwordx4 v[10:13], v[6:7], off offset:2048
	v_lshl_or_b32 v14, v9, 9, v8
	s_mov_b64 s[2:3], 0
	s_waitcnt vmcnt(0)
	v_and_b32_e32 v20, 0xffff0000, v10
	v_lshlrev_b32_e32 v10, 16, v10
	v_mul_f32_e32 v6, 0xbfb8aa3b, v10
	v_mul_f32_e32 v7, 0xbfb8aa3b, v20
	v_exp_f32_e32 v6, v6
	v_exp_f32_e32 v7, v7
	v_and_b32_e32 v26, 0xffff0000, v12
	v_lshlrev_b32_e32 v12, 16, v12
	v_pk_add_f32 v[18:19], v[6:7], 1.0 op_sel_hi:[1,0]
	s_nop 0
	v_div_scale_f32 v21, s[0:1], v19, v19, v20
	v_rcp_f32_e32 v22, v21
	ds_read_b128 v[6:9], v14
	ds_read_b128 v[14:17], v14 offset:16
	v_fma_f32 v23, -v21, v22, 1.0
	v_fmac_f32_e32 v22, v23, v22
	v_div_scale_f32 v23, vcc, v20, v19, v20
	v_mul_f32_e32 v24, v23, v22
	v_fma_f32 v25, -v21, v24, v23
	v_fmac_f32_e32 v24, v25, v22
	v_fma_f32 v21, -v21, v24, v23
	v_div_scale_f32 v23, s[0:1], v18, v18, v10
	v_rcp_f32_e32 v25, v23
	v_div_fmas_f32 v21, v21, v22, v24
	v_div_fixup_f32 v19, v21, v19, v20
	v_mul_f32_e32 v21, 0xbfb8aa3b, v26
	v_fma_f32 v20, -v23, v25, 1.0
	v_fmac_f32_e32 v25, v20, v25
	v_mul_f32_e32 v20, 0xbfb8aa3b, v12
	v_exp_f32_e32 v20, v20
	v_exp_f32_e32 v21, v21
	v_div_scale_f32 v22, vcc, v10, v18, v10
	v_mul_f32_e32 v24, v22, v25
	v_fma_f32 v27, -v23, v24, v22
	v_fmac_f32_e32 v24, v27, v25
	v_pk_add_f32 v[20:21], v[20:21], 1.0 op_sel_hi:[1,0]
	v_fma_f32 v22, -v23, v24, v22
	v_div_scale_f32 v23, s[0:1], v21, v21, v26
	v_rcp_f32_e32 v27, v23
	v_div_fmas_f32 v22, v22, v25, v24
	v_div_fixup_f32 v18, v22, v18, v10
	s_waitcnt lgkmcnt(1)
	v_pk_mul_f32 v[6:7], v[6:7], v[18:19]
	v_fma_f32 v10, -v23, v27, 1.0
	v_fmac_f32_e32 v27, v10, v27
	v_div_scale_f32 v10, vcc, v26, v21, v26
	v_mul_f32_e32 v18, v10, v27
	v_fma_f32 v19, -v23, v18, v10
	v_fmac_f32_e32 v18, v19, v27
	v_div_scale_f32 v22, s[0:1], v20, v20, v12
	v_fma_f32 v10, -v23, v18, v10
	v_rcp_f32_e32 v23, v22
	v_div_fmas_f32 v10, v10, v27, v18
	v_div_fixup_f32 v19, v10, v21, v26
	v_and_b32_e32 v24, 0xffff0000, v11
	v_fma_f32 v10, -v22, v23, 1.0
	v_lshlrev_b32_e32 v25, 16, v11
	v_fmac_f32_e32 v23, v10, v23
	v_mul_f32_e32 v10, 0xbfb8aa3b, v25
	v_mul_f32_e32 v11, 0xbfb8aa3b, v24
	v_exp_f32_e32 v10, v10
	v_exp_f32_e32 v11, v11
	v_div_scale_f32 v18, vcc, v12, v20, v12
	v_mul_f32_e32 v21, v18, v23
	v_fma_f32 v26, -v22, v21, v18
	v_fmac_f32_e32 v21, v26, v23
	v_pk_add_f32 v[10:11], v[10:11], 1.0 op_sel_hi:[1,0]
	v_fma_f32 v18, -v22, v21, v18
	v_div_scale_f32 v22, s[0:1], v11, v11, v24
	v_rcp_f32_e32 v26, v22
	v_div_fmas_f32 v18, v18, v23, v21
	v_div_fixup_f32 v18, v18, v20, v12
	s_waitcnt lgkmcnt(0)
	v_pk_mul_f32 v[14:15], v[14:15], v[18:19]
	v_fma_f32 v12, -v22, v26, 1.0
	v_fmac_f32_e32 v26, v12, v26
	v_div_scale_f32 v12, vcc, v24, v11, v24
	v_mul_f32_e32 v18, v12, v26
	v_fma_f32 v19, -v22, v18, v12
	v_fmac_f32_e32 v18, v19, v26
	v_div_scale_f32 v19, s[0:1], v10, v10, v25
	v_rcp_f32_e32 v20, v19
	v_fma_f32 v12, -v22, v18, v12
	v_div_fmas_f32 v12, v12, v26, v18
	v_div_fixup_f32 v11, v12, v11, v24
	v_fma_f32 v12, -v19, v20, 1.0
	v_and_b32_e32 v22, 0xffff0000, v13
	v_lshlrev_b32_e32 v23, 16, v13
	v_fmac_f32_e32 v20, v12, v20
	v_mul_f32_e32 v12, 0xbfb8aa3b, v23
	v_mul_f32_e32 v13, 0xbfb8aa3b, v22
	v_exp_f32_e32 v12, v12
	v_exp_f32_e32 v13, v13
	v_div_scale_f32 v18, vcc, v25, v10, v25
	v_mul_f32_e32 v21, v18, v20
	v_fma_f32 v24, -v19, v21, v18
	v_fmac_f32_e32 v21, v24, v20
	v_pk_add_f32 v[12:13], v[12:13], 1.0 op_sel_hi:[1,0]
	v_fma_f32 v18, -v19, v21, v18
	v_div_scale_f32 v19, s[0:1], v13, v13, v22
	v_rcp_f32_e32 v24, v19
	v_div_fmas_f32 v18, v18, v20, v21
	v_div_fixup_f32 v10, v18, v10, v25
	v_pk_mul_f32 v[8:9], v[8:9], v[10:11]
	v_fma_f32 v10, -v19, v24, 1.0
	v_fmac_f32_e32 v24, v10, v24
	v_div_scale_f32 v10, vcc, v22, v13, v22
	v_mul_f32_e32 v11, v10, v24
	v_fma_f32 v18, -v19, v11, v10
	v_fmac_f32_e32 v11, v18, v24
	v_div_scale_f32 v18, s[0:1], v12, v12, v23
	v_fma_f32 v10, -v19, v11, v10
	v_rcp_f32_e32 v19, v18
	v_div_fmas_f32 v10, v10, v24, v11
	v_div_fixup_f32 v11, v10, v13, v22
	v_cvt_pk_bf16_f32 v6, v6, v7
	v_fma_f32 v10, -v18, v19, 1.0
	v_fmac_f32_e32 v19, v10, v19
	v_div_scale_f32 v10, vcc, v23, v12, v23
	v_mul_f32_e32 v13, v10, v19
	v_fma_f32 v20, -v18, v13, v10
	v_fmac_f32_e32 v13, v20, v19
	v_fma_f32 v10, -v18, v13, v10
	v_div_fmas_f32 v10, v10, v19, v13
	v_div_fixup_f32 v10, v10, v12, v23
	v_pk_mul_f32 v[10:11], v[16:17], v[10:11]
	v_cvt_pk_bf16_f32 v7, v8, v9
	v_cvt_pk_bf16_f32 v9, v10, v11
	v_lshlrev_b64 v[10:11], 13, v[2:3]
	v_lshl_add_u64 v[10:11], s[48:49], 0, v[10:11]
	v_lshl_add_u64 v[4:5], v[10:11], 0, v[4:5]
	v_add_co_u32_e32 v4, vcc, 0x1000, v4
	v_cvt_pk_bf16_f32 v8, v14, v15
	s_nop 0
	v_addc_co_u32_e32 v5, vcc, 0, v5, vcc
	global_store_dwordx4 v[4:5], v[6:9], off offset:2048

; template <int MODE, bool PB>
; __device__ __forceinline__ void nsa_pass(const Params& p, const LaneId& L, int q0, int g, int ntiles, int first, char* smem, const bf16x8* qr,
;                                          float& m, float& l, float off, float gate0, f32x16* o) {
;     ...
;       float* impq = imp + (L.wid * 8 + L.qi) * IMP_LD + (row >> 2) + L.hi;
.LBB0_282:
	v_add_f32_e32 v84, v68, v69
	v_add_f32_e32 v84, v70, v84
	v_add_f32_e32 v84, v71, v84
	v_add_f32_dpp v86, v71, v71 quad_perm:[1,0,3,2] row_mask:0xf bank_mask:0xf bound_ctrl:1
	v_add_u32_e32 v161, s52, v156
	v_add_f32_dpp v84, v84, v84 quad_perm:[1,0,3,2] row_mask:0xf bank_mask:0xf bound_ctrl:1
	v_mov_b32_dpp v87, v86 quad_perm:[2,3,0,1] row_mask:0xf bank_mask:0xf bound_ctrl:1
	s_nop 0
	v_mov_b32_dpp v85, v84 quad_perm:[2,3,0,1] row_mask:0xf bank_mask:0xf bound_ctrl:1
	s_and_saveexec_b64 s[2:3], s[8:9]
	s_cbranch_execz .LBB0_284
	v_add_u32_e32 v88, 0x10000, v161
	v_add_f32_e32 v84, v84, v85
	v_add_f32_e32 v85, v86, v87
	v_add_u32_e32 v86, 0x10004, v161
	ds_add_f32 v88, v84
	ds_add_f32 v86, v85
.LBB0_284:
	s_or_b64 exec, exec, s[2:3]
	v_add_f32_e32 v84, v72, v73
	v_add_f32_e32 v84, v74, v84
	v_add_f32_e32 v84, v75, v84
	v_add_f32_dpp v86, v75, v75 quad_perm:[1,0,3,2] row_mask:0xf bank_mask:0xf bound_ctrl:1
	s_nop 0
	v_add_f32_dpp v84, v84, v84 quad_perm:[1,0,3,2] row_mask:0xf bank_mask:0xf bound_ctrl:1
	v_mov_b32_dpp v87, v86 quad_perm:[2,3,0,1] row_mask:0xf bank_mask:0xf bound_ctrl:1
	s_nop 0
	v_mov_b32_dpp v85, v84 quad_perm:[2,3,0,1] row_mask:0xf bank_mask:0xf bound_ctrl:1
	s_and_saveexec_b64 s[2:3], s[8:9]
	s_cbranch_execz .LBB0_286
	v_add_f32_e32 v84, v84, v85
	v_add_f32_e32 v85, v86, v87
	v_add_u32_e32 v87, 0x10008, v161
	v_add_u32_e32 v86, 0x1000c, v161
	ds_add_f32 v87, v84
	ds_add_f32 v86, v85
.LBB0_286:
	s_or_b64 exec, exec, s[2:3]
	v_add_f32_e32 v84, v76, v77
	v_add_f32_e32 v84, v78, v84
	v_add_f32_e32 v84, v79, v84
	v_add_f32_dpp v86, v79, v79 quad_perm:[1,0,3,2] row_mask:0xf bank_mask:0xf bound_ctrl:1
	s_nop 0
	v_add_f32_dpp v84, v84, v84 quad_perm:[1,0,3,2] row_mask:0xf bank_mask:0xf bound_ctrl:1
	v_mov_b32_dpp v87, v86 quad_perm:[2,3,0,1] row_mask:0xf bank_mask:0xf bound_ctrl:1
	s_nop 0
	v_mov_b32_dpp v85, v84 quad_perm:[2,3,0,1] row_mask:0xf bank_mask:0xf bound_ctrl:1
	s_and_saveexec_b64 s[2:3], s[8:9]
	s_cbranch_execz .LBB0_288
	v_add_f32_e32 v84, v84, v85
	v_add_f32_e32 v85, v86, v87
	v_add_u32_e32 v87, 0x10010, v161
	v_add_u32_e32 v86, 0x10014, v161
	ds_add_f32 v87, v84
	ds_add_f32 v86, v85
.LBB0_288:
	s_or_b64 exec, exec, s[2:3]
	v_exp_f32_e32 v83, v83
	v_add_f32_e32 v84, v80, v81
	v_add_f32_e32 v84, v82, v84
	v_add_f32_e32 v85, v83, v84
	s_nop 0
	v_add_f32_dpp v84, v83, v83 quad_perm:[1,0,3,2] row_mask:0xf bank_mask:0xf bound_ctrl:1
	v_add_f32_dpp v85, v85, v85 quad_perm:[1,0,3,2] row_mask:0xf bank_mask:0xf bound_ctrl:1
	s_nop 0
	v_mov_b32_dpp v87, v84 quad_perm:[2,3,0,1] row_mask:0xf bank_mask:0xf bound_ctrl:1
	v_mov_b32_dpp v86, v85 quad_perm:[2,3,0,1] row_mask:0xf bank_mask:0xf bound_ctrl:1
	s_and_saveexec_b64 s[2:3], s[8:9]
	s_cbranch_execz .LBB0_290
	v_add_f32_e32 v85, v85, v86
	v_add_f32_e32 v84, v84, v87
	v_add_u32_e32 v87, 0x10018, v161
	v_add_u32_e32 v86, 0x1001c, v161
	ds_add_f32 v87, v85
	ds_add_f32 v86, v84

; template <int MODE, bool PB>
; __device__ __forceinline__ void nsa_pass(const Params& p, const LaneId& L, int q0, int g, int ntiles, int first, char* smem, const bf16x8* qr,
;                                          float& m, float& l, float off, float gate0, f32x16* o) {
;     ...
;       float* impq = imp + (L.wid * 8 + L.qi) * IMP_LD + (row >> 2) + L.hi;
.LBB0_294:
	v_add_f32_e32 v84, v68, v69
	v_add_f32_e32 v84, v70, v84
	v_add_f32_e32 v84, v71, v84
	v_add_f32_dpp v86, v71, v71 quad_perm:[1,0,3,2] row_mask:0xf bank_mask:0xf bound_ctrl:1
	s_nop 0
	v_add_f32_dpp v84, v84, v84 quad_perm:[1,0,3,2] row_mask:0xf bank_mask:0xf bound_ctrl:1
	v_mov_b32_dpp v87, v86 quad_perm:[2,3,0,1] row_mask:0xf bank_mask:0xf bound_ctrl:1
	s_nop 0
	v_mov_b32_dpp v85, v84 quad_perm:[2,3,0,1] row_mask:0xf bank_mask:0xf bound_ctrl:1
	s_and_saveexec_b64 s[2:3], s[8:9]
	s_cbranch_execz .LBB0_296
	v_add_f32_e32 v84, v84, v85
	v_add_f32_e32 v85, v86, v87
	v_add_u32_e32 v87, 0x10020, v161
	v_add_u32_e32 v86, 0x10024, v161
	ds_add_f32 v87, v84
	ds_add_f32 v86, v85
.LBB0_296:
	s_or_b64 exec, exec, s[2:3]
	v_add_f32_e32 v84, v72, v73
	v_add_f32_e32 v84, v74, v84
	v_add_f32_e32 v84, v75, v84
	v_add_f32_dpp v86, v75, v75 quad_perm:[1,0,3,2] row_mask:0xf bank_mask:0xf bound_ctrl:1
	s_nop 0
	v_add_f32_dpp v84, v84, v84 quad_perm:[1,0,3,2] row_mask:0xf bank_mask:0xf bound_ctrl:1
	v_mov_b32_dpp v87, v86 quad_perm:[2,3,0,1] row_mask:0xf bank_mask:0xf bound_ctrl:1
	s_nop 0
	v_mov_b32_dpp v85, v84 quad_perm:[2,3,0,1] row_mask:0xf bank_mask:0xf bound_ctrl:1
	s_and_saveexec_b64 s[2:3], s[8:9]
	s_cbranch_execz .LBB0_298
	v_add_f32_e32 v84, v84, v85
	v_add_f32_e32 v85, v86, v87
	v_add_u32_e32 v87, 0x10028, v161
	v_add_u32_e32 v86, 0x1002c, v161
	ds_add_f32 v87, v84
	ds_add_f32 v86, v85
.LBB0_298:
	s_or_b64 exec, exec, s[2:3]
	v_add_f32_e32 v84, v76, v77
	v_add_f32_e32 v84, v78, v84
	v_add_f32_e32 v84, v79, v84
	v_add_f32_dpp v86, v79, v79 quad_perm:[1,0,3,2] row_mask:0xf bank_mask:0xf bound_ctrl:1
	s_nop 0
	v_add_f32_dpp v84, v84, v84 quad_perm:[1,0,3,2] row_mask:0xf bank_mask:0xf bound_ctrl:1
	v_mov_b32_dpp v87, v86 quad_perm:[2,3,0,1] row_mask:0xf bank_mask:0xf bound_ctrl:1
	s_nop 0
	v_mov_b32_dpp v85, v84 quad_perm:[2,3,0,1] row_mask:0xf bank_mask:0xf bound_ctrl:1
	s_and_saveexec_b64 s[2:3], s[8:9]
	s_cbranch_execz .LBB0_300
	v_add_f32_e32 v84, v84, v85
	v_add_f32_e32 v85, v86, v87
	v_add_u32_e32 v87, 0x10030, v161
	v_add_u32_e32 v86, 0x10034, v161
	ds_add_f32 v87, v84
	ds_add_f32 v86, v85
.LBB0_300:
	s_or_b64 exec, exec, s[2:3]
	v_exp_f32_e32 v83, v83
	v_add_f32_e32 v84, v80, v81
	v_add_f32_e32 v84, v82, v84
	v_add_f32_e32 v85, v83, v84
	s_nop 0
	v_add_f32_dpp v84, v83, v83 quad_perm:[1,0,3,2] row_mask:0xf bank_mask:0xf bound_ctrl:1
	v_add_f32_dpp v85, v85, v85 quad_perm:[1,0,3,2] row_mask:0xf bank_mask:0xf bound_ctrl:1
	s_nop 0
	v_mov_b32_dpp v87, v84 quad_perm:[2,3,0,1] row_mask:0xf bank_mask:0xf bound_ctrl:1
	v_mov_b32_dpp v86, v85 quad_perm:[2,3,0,1] row_mask:0xf bank_mask:0xf bound_ctrl:1
	s_and_saveexec_b64 s[2:3], s[8:9]
	s_cbranch_execz .LBB0_275
	v_add_f32_e32 v85, v85, v86
	v_add_f32_e32 v84, v84, v87
	v_add_u32_e32 v87, 0x10038, v161
	v_add_u32_e32 v86, 0x1003c, v161
	ds_add_f32 v87, v85
	ds_add_f32 v86, v84
	s_branch .LBB0_275
